# v16 + GEMM K-loops: s_setprio 0 moved behind the post-MFMA barrier (one instruction less between the last MFMA and the barrier)
# baseline (speedup 1.0000x reference)
.LBB0_849:
	ds_read_b128 v[146:149], v155
	ds_read_b128 v[160:163], v155 offset:1024
	ds_read_b128 v[164:167], v155 offset:2048
	ds_read_b128 v[168:171], v155 offset:3072
	ds_read_b128 v[172:175], v156
	ds_read_b128 v[176:179], v156 offset:1024
	ds_read_b128 v[180:183], v156 offset:2048
	ds_read_b128 v[184:187], v156 offset:3072
	s_add_u32 s74, s72, 0xfff80080
	s_addc_u32 s75, s73, -1
	s_cmp_eq_u32 s85, 28
	s_cselect_b32 s77, s63, s75
	s_cselect_b32 s76, s69, s74
	s_cselect_b32 s75, s57, s84
	s_cselect_b32 s74, s71, s83
	v_lshl_add_u64 v[220:221], s[72:73], 0, v[138:139]
	s_add_i32 m0, s3, 0xc000
	ds_read_b128 v[188:191], v157
	ds_read_b128 v[192:195], v157 offset:1024
	ds_read_b128 v[196:199], v157 offset:2048
	ds_read_b128 v[200:203], v157 offset:3072
	ds_read_b128 v[204:207], v157 offset:4096
	ds_read_b128 v[208:211], v157 offset:5120
	ds_read_b128 v[212:215], v157 offset:6144
	ds_read_b128 v[216:219], v157 offset:7168
	global_load_lds_dwordx4 v[220:221], off
	v_lshl_add_u64 v[220:221], s[72:73], 0, v[140:141]
	s_add_i32 m0, s3, 0xe000
	s_nop 0
	global_load_lds_dwordx4 v[220:221], off
	s_waitcnt vmcnt(8)
	s_waitcnt lgkmcnt(0)
	s_barrier
	s_setprio 1
	s_waitcnt lgkmcnt(0)
	v_mfma_f32_16x16x32_bf16 v[124:127], v[146:149], v[188:191], v[124:127]
	v_mfma_f32_16x16x32_bf16 v[120:123], v[164:167], v[188:191], v[120:123]
	v_mfma_f32_16x16x32_bf16 v[108:111], v[146:149], v[196:199], v[108:111]
	v_mfma_f32_16x16x32_bf16 v[104:107], v[164:167], v[196:199], v[104:107]
	v_mfma_f32_16x16x32_bf16 v[92:95], v[146:149], v[204:207], v[92:95]
	v_mfma_f32_16x16x32_bf16 v[88:91], v[164:167], v[204:207], v[88:91]
	v_mfma_f32_16x16x32_bf16 v[76:79], v[146:149], v[212:215], v[76:79]
	v_mfma_f32_16x16x32_bf16 v[72:75], v[164:167], v[212:215], v[72:75]
	v_mfma_f32_16x16x32_bf16 v[124:127], v[160:163], v[192:195], v[124:127]
	v_mfma_f32_16x16x32_bf16 v[120:123], v[168:171], v[192:195], v[120:123]
	v_mfma_f32_16x16x32_bf16 v[108:111], v[160:163], v[200:203], v[108:111]
	v_mfma_f32_16x16x32_bf16 v[104:107], v[168:171], v[200:203], v[104:107]
	v_mfma_f32_16x16x32_bf16 v[92:95], v[160:163], v[208:211], v[92:95]
	v_mfma_f32_16x16x32_bf16 v[88:91], v[168:171], v[208:211], v[88:91]
	v_mfma_f32_16x16x32_bf16 v[76:79], v[160:163], v[216:219], v[76:79]
	v_mfma_f32_16x16x32_bf16 v[72:75], v[168:171], v[216:219], v[72:75]
	v_mfma_f32_16x16x32_bf16 v[116:119], v[172:175], v[188:191], v[116:119]
	v_mfma_f32_16x16x32_bf16 v[112:115], v[180:183], v[188:191], v[112:115]
	v_mfma_f32_16x16x32_bf16 v[100:103], v[172:175], v[196:199], v[100:103]
	v_mfma_f32_16x16x32_bf16 v[96:99], v[180:183], v[196:199], v[96:99]
	v_mfma_f32_16x16x32_bf16 v[84:87], v[172:175], v[204:207], v[84:87]
	v_mfma_f32_16x16x32_bf16 v[80:83], v[180:183], v[204:207], v[80:83]
	v_mfma_f32_16x16x32_bf16 v[68:71], v[172:175], v[212:215], v[68:71]
	v_mfma_f32_16x16x32_bf16 v[64:67], v[180:183], v[212:215], v[64:67]
	v_mfma_f32_16x16x32_bf16 v[116:119], v[176:179], v[192:195], v[116:119]
	v_mfma_f32_16x16x32_bf16 v[112:115], v[184:187], v[192:195], v[112:115]
	v_mfma_f32_16x16x32_bf16 v[100:103], v[176:179], v[200:203], v[100:103]
	v_mfma_f32_16x16x32_bf16 v[96:99], v[184:187], v[200:203], v[96:99]
	v_mfma_f32_16x16x32_bf16 v[84:87], v[176:179], v[208:211], v[84:87]
	v_mfma_f32_16x16x32_bf16 v[80:83], v[184:187], v[208:211], v[80:83]
	v_mfma_f32_16x16x32_bf16 v[68:71], v[176:179], v[216:219], v[68:71]
	v_mfma_f32_16x16x32_bf16 v[64:67], v[184:187], v[216:219], v[64:67]
	s_barrier
	s_setprio 0
	s_add_i32 s86, s79, s94
	v_lshl_add_u64 v[220:221], s[74:75], 0, v[130:131]
	s_mov_b32 m0, s86
	ds_read_b128 v[188:191], v157 offset:16384
	ds_read_b128 v[192:195], v157 offset:17408
	ds_read_b128 v[196:199], v157 offset:18432
	ds_read_b128 v[200:203], v157 offset:19456
	ds_read_b128 v[204:207], v157 offset:20480
	ds_read_b128 v[208:211], v157 offset:21504
	ds_read_b128 v[212:215], v157 offset:22528
	ds_read_b128 v[216:219], v157 offset:23552
	global_load_lds_dwordx4 v[220:221], off
	s_add_i32 m0, s86, 0x2000
	s_add_u32 s86, s74, 0x80000
	v_lshl_add_u64 v[222:223], s[74:75], 0, v[134:135]
	s_addc_u32 s87, s75, 0
	s_add_i32 s88, s81, s94
	global_load_lds_dwordx4 v[222:223], off
	v_lshl_add_u64 v[224:225], s[86:87], 0, v[130:131]
	s_mov_b32 m0, s88
	v_lshl_add_u64 v[226:227], s[76:77], 0, v[132:133]
	global_load_lds_dwordx4 v[224:225], off
	v_lshl_add_u64 v[224:225], s[86:87], 0, v[134:135]
	s_add_i32 m0, s88, 0x2000
	s_nop 0
	global_load_lds_dwordx4 v[224:225], off
	v_lshl_add_u64 v[224:225], s[76:77], 0, v[128:129]
	s_mov_b32 m0, s3
	s_nop 0
	global_load_lds_dwordx4 v[224:225], off
	s_mov_b32 m0, s6
	s_nop 0
	global_load_lds_dwordx4 v[226:227], off
	s_waitcnt vmcnt(8)
	s_waitcnt lgkmcnt(0)
	s_barrier
	s_setprio 1
	s_waitcnt lgkmcnt(0)
	v_mfma_f32_16x16x32_bf16 v[60:63], v[146:149], v[188:191], v[60:63]
	v_mfma_f32_16x16x32_bf16 v[56:59], v[164:167], v[188:191], v[56:59]
	v_mfma_f32_16x16x32_bf16 v[44:47], v[146:149], v[196:199], v[44:47]
	v_mfma_f32_16x16x32_bf16 v[40:43], v[164:167], v[196:199], v[40:43]
	v_mfma_f32_16x16x32_bf16 v[28:31], v[146:149], v[204:207], v[28:31]
	v_mfma_f32_16x16x32_bf16 v[24:27], v[164:167], v[204:207], v[24:27]
	v_mfma_f32_16x16x32_bf16 v[12:15], v[146:149], v[212:215], v[12:15]
	v_mfma_f32_16x16x32_bf16 v[8:11], v[164:167], v[212:215], v[8:11]
	v_mfma_f32_16x16x32_bf16 v[60:63], v[160:163], v[192:195], v[60:63]
	v_mfma_f32_16x16x32_bf16 v[56:59], v[168:171], v[192:195], v[56:59]
	v_mfma_f32_16x16x32_bf16 v[44:47], v[160:163], v[200:203], v[44:47]
	v_mfma_f32_16x16x32_bf16 v[40:43], v[168:171], v[200:203], v[40:43]
	v_mfma_f32_16x16x32_bf16 v[28:31], v[160:163], v[208:211], v[28:31]
	v_mfma_f32_16x16x32_bf16 v[24:27], v[168:171], v[208:211], v[24:27]
	v_mfma_f32_16x16x32_bf16 v[12:15], v[160:163], v[216:219], v[12:15]
	v_mfma_f32_16x16x32_bf16 v[8:11], v[168:171], v[216:219], v[8:11]
	v_mfma_f32_16x16x32_bf16 v[52:55], v[172:175], v[188:191], v[52:55]
	v_mfma_f32_16x16x32_bf16 v[48:51], v[180:183], v[188:191], v[48:51]
	v_mfma_f32_16x16x32_bf16 v[36:39], v[172:175], v[196:199], v[36:39]
	v_mfma_f32_16x16x32_bf16 v[32:35], v[180:183], v[196:199], v[32:35]
	v_mfma_f32_16x16x32_bf16 v[20:23], v[172:175], v[204:207], v[20:23]
	v_mfma_f32_16x16x32_bf16 v[16:19], v[180:183], v[204:207], v[16:19]
	v_mfma_f32_16x16x32_bf16 v[4:7], v[172:175], v[212:215], v[4:7]
	v_mfma_f32_16x16x32_bf16 v[0:3], v[180:183], v[212:215], v[0:3]
	v_mfma_f32_16x16x32_bf16 v[52:55], v[176:179], v[192:195], v[52:55]
	v_mfma_f32_16x16x32_bf16 v[48:51], v[184:187], v[192:195], v[48:51]
	v_mfma_f32_16x16x32_bf16 v[36:39], v[176:179], v[200:203], v[36:39]
	v_mfma_f32_16x16x32_bf16 v[32:35], v[184:187], v[200:203], v[32:35]
	v_mfma_f32_16x16x32_bf16 v[20:23], v[176:179], v[208:211], v[20:23]
	v_mfma_f32_16x16x32_bf16 v[16:19], v[184:187], v[208:211], v[16:19]
	v_mfma_f32_16x16x32_bf16 v[4:7], v[176:179], v[216:219], v[4:7]
	v_mfma_f32_16x16x32_bf16 v[0:3], v[184:187], v[216:219], v[0:3]
	s_barrier
	s_setprio 0
	s_add_i32 s86, 0, 0x18000
	v_add_u32_e32 v159, s86, v151
	s_add_i32 s87, 0, 0x1c000
	ds_read_b128 v[146:149], v159
	ds_read_b128 v[160:163], v159 offset:1024
	ds_read_b128 v[164:167], v159 offset:2048
	ds_read_b128 v[168:171], v159 offset:3072
	v_add_u32_e32 v159, s87, v151
	ds_read_b128 v[172:175], v159
	ds_read_b128 v[176:179], v159 offset:1024
	ds_read_b128 v[180:183], v159 offset:2048
	ds_read_b128 v[184:187], v159 offset:3072
	s_add_u32 s76, s76, 0x80000
	s_addc_u32 s77, s77, 0
	s_mov_b32 m0, s7
	v_lshl_add_u64 v[228:229], s[76:77], 0, v[128:129]
	ds_read_b128 v[188:191], v157 offset:32768
	ds_read_b128 v[192:195], v157 offset:33792
	ds_read_b128 v[196:199], v157 offset:34816
	ds_read_b128 v[200:203], v157 offset:35840
	ds_read_b128 v[204:207], v157 offset:36864
	ds_read_b128 v[208:211], v157 offset:37888
	ds_read_b128 v[212:215], v157 offset:38912
	ds_read_b128 v[216:219], v157 offset:39936
	global_load_lds_dwordx4 v[228:229], off
	v_lshl_add_u64 v[228:229], s[76:77], 0, v[132:133]
	s_mov_b32 m0, s29
	s_nop 0
	global_load_lds_dwordx4 v[228:229], off
	s_waitcnt vmcnt(8)
	s_waitcnt lgkmcnt(0)
	s_barrier
	s_setprio 1
	s_waitcnt lgkmcnt(0)
	v_mfma_f32_16x16x32_bf16 v[124:127], v[146:149], v[188:191], v[124:127]
	v_mfma_f32_16x16x32_bf16 v[120:123], v[164:167], v[188:191], v[120:123]
	v_mfma_f32_16x16x32_bf16 v[108:111], v[146:149], v[196:199], v[108:111]
	v_mfma_f32_16x16x32_bf16 v[104:107], v[164:167], v[196:199], v[104:107]
	v_mfma_f32_16x16x32_bf16 v[92:95], v[146:149], v[204:207], v[92:95]
	v_mfma_f32_16x16x32_bf16 v[88:91], v[164:167], v[204:207], v[88:91]
	v_mfma_f32_16x16x32_bf16 v[76:79], v[146:149], v[212:215], v[76:79]
	v_mfma_f32_16x16x32_bf16 v[72:75], v[164:167], v[212:215], v[72:75]
	v_mfma_f32_16x16x32_bf16 v[124:127], v[160:163], v[192:195], v[124:127]
	v_mfma_f32_16x16x32_bf16 v[120:123], v[168:171], v[192:195], v[120:123]
	v_mfma_f32_16x16x32_bf16 v[108:111], v[160:163], v[200:203], v[108:111]
	v_mfma_f32_16x16x32_bf16 v[104:107], v[168:171], v[200:203], v[104:107]
	v_mfma_f32_16x16x32_bf16 v[92:95], v[160:163], v[208:211], v[92:95]
	v_mfma_f32_16x16x32_bf16 v[88:91], v[168:171], v[208:211], v[88:91]
	v_mfma_f32_16x16x32_bf16 v[76:79], v[160:163], v[216:219], v[76:79]
	v_mfma_f32_16x16x32_bf16 v[72:75], v[168:171], v[216:219], v[72:75]
	v_mfma_f32_16x16x32_bf16 v[116:119], v[172:175], v[188:191], v[116:119]
	v_mfma_f32_16x16x32_bf16 v[112:115], v[180:183], v[188:191], v[112:115]
	v_mfma_f32_16x16x32_bf16 v[100:103], v[172:175], v[196:199], v[100:103]
	v_mfma_f32_16x16x32_bf16 v[96:99], v[180:183], v[196:199], v[96:99]
	v_mfma_f32_16x16x32_bf16 v[84:87], v[172:175], v[204:207], v[84:87]
	v_mfma_f32_16x16x32_bf16 v[80:83], v[180:183], v[204:207], v[80:83]
	v_mfma_f32_16x16x32_bf16 v[68:71], v[172:175], v[212:215], v[68:71]
	v_mfma_f32_16x16x32_bf16 v[64:67], v[180:183], v[212:215], v[64:67]
	v_mfma_f32_16x16x32_bf16 v[116:119], v[176:179], v[192:195], v[116:119]
	v_mfma_f32_16x16x32_bf16 v[112:115], v[184:187], v[192:195], v[112:115]
	v_mfma_f32_16x16x32_bf16 v[100:103], v[176:179], v[200:203], v[100:103]
	v_mfma_f32_16x16x32_bf16 v[96:99], v[184:187], v[200:203], v[96:99]
	v_mfma_f32_16x16x32_bf16 v[84:87], v[176:179], v[208:211], v[84:87]
	v_mfma_f32_16x16x32_bf16 v[80:83], v[184:187], v[208:211], v[80:83]
	v_mfma_f32_16x16x32_bf16 v[68:71], v[176:179], v[216:219], v[68:71]
	v_mfma_f32_16x16x32_bf16 v[64:67], v[184:187], v[216:219], v[64:67]
	s_barrier
	s_setprio 0
	s_add_i32 s76, s86, s94
	v_lshl_add_u64 v[220:221], v[220:221], 0, s[18:19]
	s_mov_b32 m0, s76
	ds_read_b128 v[188:191], v157 offset:49152
	ds_read_b128 v[192:195], v157 offset:50176
	ds_read_b128 v[196:199], v157 offset:51200
	ds_read_b128 v[200:203], v157 offset:52224
	ds_read_b128 v[204:207], v157 offset:53248
	ds_read_b128 v[208:211], v157 offset:54272
	ds_read_b128 v[212:215], v157 offset:55296
	ds_read_b128 v[216:219], v157 offset:56320
	global_load_lds_dwordx4 v[220:221], off
	s_add_i32 m0, s76, 0x2000
	s_add_u32 s74, s74, 0x80080
	v_lshl_add_u64 v[220:221], v[222:223], 0, s[18:19]
	s_addc_u32 s75, s75, 0
	s_add_i32 s76, s87, s94
	global_load_lds_dwordx4 v[220:221], off
	v_lshl_add_u64 v[220:221], s[74:75], 0, v[130:131]
	s_mov_b32 m0, s76
	s_nop 0
	global_load_lds_dwordx4 v[220:221], off
	v_lshl_add_u64 v[220:221], s[74:75], 0, v[134:135]
	s_add_i32 m0, s76, 0x2000
	s_nop 0
	global_load_lds_dwordx4 v[220:221], off
	v_lshl_add_u64 v[220:221], v[224:225], 0, s[18:19]
	s_mov_b32 m0, s34
	s_nop 0
	global_load_lds_dwordx4 v[220:221], off
	v_lshl_add_u64 v[220:221], v[226:227], 0, s[18:19]
	s_mov_b32 m0, s35
	s_nop 0
	global_load_lds_dwordx4 v[220:221], off
	s_waitcnt vmcnt(8)
	s_waitcnt lgkmcnt(0)
	s_barrier
	s_setprio 1
	s_waitcnt lgkmcnt(0)
	v_mfma_f32_16x16x32_bf16 v[60:63], v[146:149], v[188:191], v[60:63]
	v_mfma_f32_16x16x32_bf16 v[56:59], v[164:167], v[188:191], v[56:59]
	v_mfma_f32_16x16x32_bf16 v[44:47], v[146:149], v[196:199], v[44:47]
	v_mfma_f32_16x16x32_bf16 v[40:43], v[164:167], v[196:199], v[40:43]
	v_mfma_f32_16x16x32_bf16 v[28:31], v[146:149], v[204:207], v[28:31]
	v_mfma_f32_16x16x32_bf16 v[24:27], v[164:167], v[204:207], v[24:27]
	v_mfma_f32_16x16x32_bf16 v[12:15], v[146:149], v[212:215], v[12:15]
	v_mfma_f32_16x16x32_bf16 v[8:11], v[164:167], v[212:215], v[8:11]
	v_mfma_f32_16x16x32_bf16 v[60:63], v[160:163], v[192:195], v[60:63]
	v_mfma_f32_16x16x32_bf16 v[56:59], v[168:171], v[192:195], v[56:59]
	v_mfma_f32_16x16x32_bf16 v[44:47], v[160:163], v[200:203], v[44:47]
	v_mfma_f32_16x16x32_bf16 v[40:43], v[168:171], v[200:203], v[40:43]
	v_mfma_f32_16x16x32_bf16 v[28:31], v[160:163], v[208:211], v[28:31]
	v_mfma_f32_16x16x32_bf16 v[24:27], v[168:171], v[208:211], v[24:27]
	v_mfma_f32_16x16x32_bf16 v[12:15], v[160:163], v[216:219], v[12:15]
	v_mfma_f32_16x16x32_bf16 v[8:11], v[168:171], v[216:219], v[8:11]
	v_mfma_f32_16x16x32_bf16 v[52:55], v[172:175], v[188:191], v[52:55]
	v_mfma_f32_16x16x32_bf16 v[48:51], v[180:183], v[188:191], v[48:51]
	v_mfma_f32_16x16x32_bf16 v[36:39], v[172:175], v[196:199], v[36:39]
	v_mfma_f32_16x16x32_bf16 v[32:35], v[180:183], v[196:199], v[32:35]
	v_mfma_f32_16x16x32_bf16 v[20:23], v[172:175], v[204:207], v[20:23]
	v_mfma_f32_16x16x32_bf16 v[16:19], v[180:183], v[204:207], v[16:19]
	v_mfma_f32_16x16x32_bf16 v[4:7], v[172:175], v[212:215], v[4:7]
	v_mfma_f32_16x16x32_bf16 v[0:3], v[180:183], v[212:215], v[0:3]
	v_mfma_f32_16x16x32_bf16 v[52:55], v[176:179], v[192:195], v[52:55]
	v_mfma_f32_16x16x32_bf16 v[48:51], v[184:187], v[192:195], v[48:51]
	v_mfma_f32_16x16x32_bf16 v[36:39], v[176:179], v[200:203], v[36:39]
	v_mfma_f32_16x16x32_bf16 v[32:35], v[184:187], v[200:203], v[32:35]
	v_mfma_f32_16x16x32_bf16 v[20:23], v[176:179], v[208:211], v[20:23]
	v_mfma_f32_16x16x32_bf16 v[16:19], v[184:187], v[208:211], v[16:19]
	v_mfma_f32_16x16x32_bf16 v[4:7], v[176:179], v[216:219], v[4:7]
	v_mfma_f32_16x16x32_bf16 v[0:3], v[184:187], v[216:219], v[0:3]
	s_barrier
	s_setprio 0
	s_add_i32 s85, s85, 2
	s_add_u32 s72, s72, 0x100
	s_addc_u32 s73, s73, 0
	s_add_u32 s83, s83, 0x100
	s_addc_u32 s84, s84, 0
	s_cmp_gt_u32 s85, 29
	s_cbranch_scc0 .LBB0_849
	s_and_b64 vcc, exec, s[20:21]
	s_cbranch_vccz .LBB0_852
	s_barrier

.LBB0_946:
	ds_read_b128 v[148:151], v143
	ds_read_b128 v[152:155], v143 offset:1024
	ds_read_b128 v[156:159], v143 offset:2048
	ds_read_b128 v[160:163], v143 offset:3072
	ds_read_b128 v[164:167], v144
	ds_read_b128 v[168:171], v144 offset:1024
	ds_read_b128 v[172:175], v144 offset:2048
	ds_read_b128 v[176:179], v144 offset:3072
	s_add_u32 s18, s14, s16
	s_addc_u32 s19, s15, s17
	s_add_u32 s18, s18, 0x7498100
	s_addc_u32 s19, s19, 0
	s_add_u32 s20, s24, s16
	s_addc_u32 s21, s25, s17
	s_add_u32 s69, s20, 0x1308100
	s_addc_u32 s70, s21, 0
	s_cmpk_eq_i32 s16, 0xf00
	s_cselect_b32 s21, s11, s19
	s_cselect_b32 s20, s10, s18
	s_cselect_b32 s19, s9, s70
	s_cselect_b32 s18, s8, s69
	s_mov_b32 m0, s46
	v_lshl_add_u64 v[212:213], v[136:137], 0, s[16:17]
	ds_read_b128 v[180:183], v145
	ds_read_b128 v[184:187], v145 offset:1024
	ds_read_b128 v[188:191], v145 offset:2048
	ds_read_b128 v[192:195], v145 offset:3072
	ds_read_b128 v[196:199], v145 offset:4096
	ds_read_b128 v[200:203], v145 offset:5120
	ds_read_b128 v[204:207], v145 offset:6144
	ds_read_b128 v[208:211], v145 offset:7168
	global_load_lds_dwordx4 v[212:213], off
	v_lshl_add_u64 v[212:213], v[138:139], 0, s[16:17]
	s_mov_b32 m0, s56
	s_nop 0
	global_load_lds_dwordx4 v[212:213], off
	s_waitcnt vmcnt(8)
	s_waitcnt lgkmcnt(0)
	s_barrier
	s_setprio 1
	s_waitcnt lgkmcnt(0)
	v_mfma_f32_16x16x32_bf16 v[124:127], v[148:151], v[180:183], v[124:127]
	v_mfma_f32_16x16x32_bf16 v[120:123], v[156:159], v[180:183], v[120:123]
	v_mfma_f32_16x16x32_bf16 v[108:111], v[148:151], v[188:191], v[108:111]
	v_mfma_f32_16x16x32_bf16 v[104:107], v[156:159], v[188:191], v[104:107]
	v_mfma_f32_16x16x32_bf16 v[92:95], v[148:151], v[196:199], v[92:95]
	v_mfma_f32_16x16x32_bf16 v[88:91], v[156:159], v[196:199], v[88:91]
	v_mfma_f32_16x16x32_bf16 v[76:79], v[148:151], v[204:207], v[76:79]
	v_mfma_f32_16x16x32_bf16 v[72:75], v[156:159], v[204:207], v[72:75]
	v_mfma_f32_16x16x32_bf16 v[124:127], v[152:155], v[184:187], v[124:127]
	v_mfma_f32_16x16x32_bf16 v[120:123], v[160:163], v[184:187], v[120:123]
	v_mfma_f32_16x16x32_bf16 v[108:111], v[152:155], v[192:195], v[108:111]
	v_mfma_f32_16x16x32_bf16 v[104:107], v[160:163], v[192:195], v[104:107]
	v_mfma_f32_16x16x32_bf16 v[92:95], v[152:155], v[200:203], v[92:95]
	v_mfma_f32_16x16x32_bf16 v[88:91], v[160:163], v[200:203], v[88:91]
	v_mfma_f32_16x16x32_bf16 v[76:79], v[152:155], v[208:211], v[76:79]
	v_mfma_f32_16x16x32_bf16 v[72:75], v[160:163], v[208:211], v[72:75]
	v_mfma_f32_16x16x32_bf16 v[116:119], v[164:167], v[180:183], v[116:119]
	v_mfma_f32_16x16x32_bf16 v[112:115], v[172:175], v[180:183], v[112:115]
	v_mfma_f32_16x16x32_bf16 v[100:103], v[164:167], v[188:191], v[100:103]
	v_mfma_f32_16x16x32_bf16 v[96:99], v[172:175], v[188:191], v[96:99]
	v_mfma_f32_16x16x32_bf16 v[84:87], v[164:167], v[196:199], v[84:87]
	v_mfma_f32_16x16x32_bf16 v[80:83], v[172:175], v[196:199], v[80:83]
	v_mfma_f32_16x16x32_bf16 v[68:71], v[164:167], v[204:207], v[68:71]
	v_mfma_f32_16x16x32_bf16 v[64:67], v[172:175], v[204:207], v[64:67]
	v_mfma_f32_16x16x32_bf16 v[116:119], v[168:171], v[184:187], v[116:119]
	v_mfma_f32_16x16x32_bf16 v[112:115], v[176:179], v[184:187], v[112:115]
	v_mfma_f32_16x16x32_bf16 v[100:103], v[168:171], v[192:195], v[100:103]
	v_mfma_f32_16x16x32_bf16 v[96:99], v[176:179], v[192:195], v[96:99]
	v_mfma_f32_16x16x32_bf16 v[84:87], v[168:171], v[200:203], v[84:87]
	v_mfma_f32_16x16x32_bf16 v[80:83], v[176:179], v[200:203], v[80:83]
	v_mfma_f32_16x16x32_bf16 v[68:71], v[168:171], v[208:211], v[68:71]
	v_mfma_f32_16x16x32_bf16 v[64:67], v[176:179], v[208:211], v[64:67]
	s_barrier
	s_setprio 0
	s_mov_b32 m0, s57
	v_lshl_add_u64 v[212:213], s[18:19], 0, v[132:133]
	s_add_u32 s70, s18, 0x80000
	ds_read_b128 v[180:183], v145 offset:16384
	ds_read_b128 v[184:187], v145 offset:17408
	ds_read_b128 v[188:191], v145 offset:18432
	ds_read_b128 v[192:195], v145 offset:19456
	ds_read_b128 v[196:199], v145 offset:20480
	ds_read_b128 v[200:203], v145 offset:21504
	ds_read_b128 v[204:207], v145 offset:22528
	ds_read_b128 v[208:211], v145 offset:23552
	global_load_lds_dwordx4 v[212:213], off
	v_lshl_add_u64 v[214:215], s[18:19], 0, v[128:129]
	s_mov_b32 m0, s62
	s_addc_u32 s71, s19, 0
	global_load_lds_dwordx4 v[214:215], off
	v_lshl_add_u64 v[216:217], s[70:71], 0, v[132:133]
	s_mov_b32 m0, s63
	v_lshl_add_u64 v[218:219], s[20:21], 0, v[130:131]
	global_load_lds_dwordx4 v[216:217], off
	v_lshl_add_u64 v[216:217], s[70:71], 0, v[128:129]
	s_mov_b32 m0, s64
	s_nop 0
	global_load_lds_dwordx4 v[216:217], off
	v_lshl_add_u64 v[216:217], s[20:21], 0, v[134:135]
	s_mov_b32 m0, s3
	s_nop 0
	global_load_lds_dwordx4 v[216:217], off
	s_mov_b32 m0, s6
	s_nop 0
	global_load_lds_dwordx4 v[218:219], off
	s_waitcnt vmcnt(8)
	s_waitcnt lgkmcnt(0)
	s_barrier
	s_setprio 1
	s_waitcnt lgkmcnt(0)
	v_mfma_f32_16x16x32_bf16 v[60:63], v[148:151], v[180:183], v[60:63]
	v_mfma_f32_16x16x32_bf16 v[56:59], v[156:159], v[180:183], v[56:59]
	v_mfma_f32_16x16x32_bf16 v[44:47], v[148:151], v[188:191], v[44:47]
	v_mfma_f32_16x16x32_bf16 v[40:43], v[156:159], v[188:191], v[40:43]
	v_mfma_f32_16x16x32_bf16 v[28:31], v[148:151], v[196:199], v[28:31]
	v_mfma_f32_16x16x32_bf16 v[24:27], v[156:159], v[196:199], v[24:27]
	v_mfma_f32_16x16x32_bf16 v[12:15], v[148:151], v[204:207], v[12:15]
	v_mfma_f32_16x16x32_bf16 v[8:11], v[156:159], v[204:207], v[8:11]
	v_mfma_f32_16x16x32_bf16 v[60:63], v[152:155], v[184:187], v[60:63]
	v_mfma_f32_16x16x32_bf16 v[56:59], v[160:163], v[184:187], v[56:59]
	v_mfma_f32_16x16x32_bf16 v[44:47], v[152:155], v[192:195], v[44:47]
	v_mfma_f32_16x16x32_bf16 v[40:43], v[160:163], v[192:195], v[40:43]
	v_mfma_f32_16x16x32_bf16 v[28:31], v[152:155], v[200:203], v[28:31]
	v_mfma_f32_16x16x32_bf16 v[24:27], v[160:163], v[200:203], v[24:27]
	v_mfma_f32_16x16x32_bf16 v[12:15], v[152:155], v[208:211], v[12:15]
	v_mfma_f32_16x16x32_bf16 v[8:11], v[160:163], v[208:211], v[8:11]
	v_mfma_f32_16x16x32_bf16 v[52:55], v[164:167], v[180:183], v[52:55]
	v_mfma_f32_16x16x32_bf16 v[48:51], v[172:175], v[180:183], v[48:51]
	v_mfma_f32_16x16x32_bf16 v[36:39], v[164:167], v[188:191], v[36:39]
	v_mfma_f32_16x16x32_bf16 v[32:35], v[172:175], v[188:191], v[32:35]
	v_mfma_f32_16x16x32_bf16 v[20:23], v[164:167], v[196:199], v[20:23]
	v_mfma_f32_16x16x32_bf16 v[16:19], v[172:175], v[196:199], v[16:19]
	v_mfma_f32_16x16x32_bf16 v[4:7], v[164:167], v[204:207], v[4:7]
	v_mfma_f32_16x16x32_bf16 v[0:3], v[172:175], v[204:207], v[0:3]
	v_mfma_f32_16x16x32_bf16 v[52:55], v[168:171], v[184:187], v[52:55]
	v_mfma_f32_16x16x32_bf16 v[48:51], v[176:179], v[184:187], v[48:51]
	v_mfma_f32_16x16x32_bf16 v[36:39], v[168:171], v[192:195], v[36:39]
	v_mfma_f32_16x16x32_bf16 v[32:35], v[176:179], v[192:195], v[32:35]
	v_mfma_f32_16x16x32_bf16 v[20:23], v[168:171], v[200:203], v[20:23]
	v_mfma_f32_16x16x32_bf16 v[16:19], v[176:179], v[200:203], v[16:19]
	v_mfma_f32_16x16x32_bf16 v[4:7], v[168:171], v[208:211], v[4:7]
	v_mfma_f32_16x16x32_bf16 v[0:3], v[176:179], v[208:211], v[0:3]
	s_barrier
	s_setprio 0
	ds_read_b128 v[148:151], v146
	ds_read_b128 v[152:155], v146 offset:1024
	ds_read_b128 v[156:159], v146 offset:2048
	ds_read_b128 v[160:163], v146 offset:3072
	ds_read_b128 v[164:167], v147
	ds_read_b128 v[168:171], v147 offset:1024
	ds_read_b128 v[172:175], v147 offset:2048
	ds_read_b128 v[176:179], v147 offset:3072
	s_add_u32 s20, s20, 0x80000
	s_addc_u32 s21, s21, 0
	s_mov_b32 m0, s7
	v_lshl_add_u64 v[220:221], s[20:21], 0, v[134:135]
	ds_read_b128 v[180:183], v145 offset:32768
	ds_read_b128 v[184:187], v145 offset:33792
	ds_read_b128 v[188:191], v145 offset:34816
	ds_read_b128 v[192:195], v145 offset:35840
	ds_read_b128 v[196:199], v145 offset:36864
	ds_read_b128 v[200:203], v145 offset:37888
	ds_read_b128 v[204:207], v145 offset:38912
	ds_read_b128 v[208:211], v145 offset:39936
	global_load_lds_dwordx4 v[220:221], off
	v_lshl_add_u64 v[220:221], s[20:21], 0, v[130:131]
	s_mov_b32 m0, s29
	s_nop 0
	global_load_lds_dwordx4 v[220:221], off
	s_waitcnt vmcnt(8)
	s_waitcnt lgkmcnt(0)
	s_barrier
	s_setprio 1
	s_waitcnt lgkmcnt(0)
	v_mfma_f32_16x16x32_bf16 v[124:127], v[148:151], v[180:183], v[124:127]
	v_mfma_f32_16x16x32_bf16 v[120:123], v[156:159], v[180:183], v[120:123]
	v_mfma_f32_16x16x32_bf16 v[108:111], v[148:151], v[188:191], v[108:111]
	v_mfma_f32_16x16x32_bf16 v[104:107], v[156:159], v[188:191], v[104:107]
	v_mfma_f32_16x16x32_bf16 v[92:95], v[148:151], v[196:199], v[92:95]
	v_mfma_f32_16x16x32_bf16 v[88:91], v[156:159], v[196:199], v[88:91]
	v_mfma_f32_16x16x32_bf16 v[76:79], v[148:151], v[204:207], v[76:79]
	v_mfma_f32_16x16x32_bf16 v[72:75], v[156:159], v[204:207], v[72:75]
	v_mfma_f32_16x16x32_bf16 v[124:127], v[152:155], v[184:187], v[124:127]
	v_mfma_f32_16x16x32_bf16 v[120:123], v[160:163], v[184:187], v[120:123]
	v_mfma_f32_16x16x32_bf16 v[108:111], v[152:155], v[192:195], v[108:111]
	v_mfma_f32_16x16x32_bf16 v[104:107], v[160:163], v[192:195], v[104:107]
	v_mfma_f32_16x16x32_bf16 v[92:95], v[152:155], v[200:203], v[92:95]
	v_mfma_f32_16x16x32_bf16 v[88:91], v[160:163], v[200:203], v[88:91]
	v_mfma_f32_16x16x32_bf16 v[76:79], v[152:155], v[208:211], v[76:79]
	v_mfma_f32_16x16x32_bf16 v[72:75], v[160:163], v[208:211], v[72:75]
	v_mfma_f32_16x16x32_bf16 v[116:119], v[164:167], v[180:183], v[116:119]
	v_mfma_f32_16x16x32_bf16 v[112:115], v[172:175], v[180:183], v[112:115]
	v_mfma_f32_16x16x32_bf16 v[100:103], v[164:167], v[188:191], v[100:103]
	v_mfma_f32_16x16x32_bf16 v[96:99], v[172:175], v[188:191], v[96:99]
	v_mfma_f32_16x16x32_bf16 v[84:87], v[164:167], v[196:199], v[84:87]
	v_mfma_f32_16x16x32_bf16 v[80:83], v[172:175], v[196:199], v[80:83]
	v_mfma_f32_16x16x32_bf16 v[68:71], v[164:167], v[204:207], v[68:71]
	v_mfma_f32_16x16x32_bf16 v[64:67], v[172:175], v[204:207], v[64:67]
	v_mfma_f32_16x16x32_bf16 v[116:119], v[168:171], v[184:187], v[116:119]
	v_mfma_f32_16x16x32_bf16 v[112:115], v[176:179], v[184:187], v[112:115]
	v_mfma_f32_16x16x32_bf16 v[100:103], v[168:171], v[192:195], v[100:103]
	v_mfma_f32_16x16x32_bf16 v[96:99], v[176:179], v[192:195], v[96:99]
	v_mfma_f32_16x16x32_bf16 v[84:87], v[168:171], v[200:203], v[84:87]
	v_mfma_f32_16x16x32_bf16 v[80:83], v[176:179], v[200:203], v[80:83]
	v_mfma_f32_16x16x32_bf16 v[68:71], v[168:171], v[208:211], v[68:71]
	v_mfma_f32_16x16x32_bf16 v[64:67], v[176:179], v[208:211], v[64:67]
	s_barrier
	s_setprio 0
	s_mov_b32 m0, s65
	v_lshl_add_u64 v[212:213], v[212:213], 0, s[12:13]
	s_add_u32 s18, s18, 0x80080
	ds_read_b128 v[180:183], v145 offset:49152
	ds_read_b128 v[184:187], v145 offset:50176
	ds_read_b128 v[188:191], v145 offset:51200
	ds_read_b128 v[192:195], v145 offset:52224
	ds_read_b128 v[196:199], v145 offset:53248
	ds_read_b128 v[200:203], v145 offset:54272
	ds_read_b128 v[204:207], v145 offset:55296
	ds_read_b128 v[208:211], v145 offset:56320
	global_load_lds_dwordx4 v[212:213], off
	v_lshl_add_u64 v[212:213], v[214:215], 0, s[12:13]
	s_mov_b32 m0, s66
	s_addc_u32 s19, s19, 0
	global_load_lds_dwordx4 v[212:213], off
	v_lshl_add_u64 v[212:213], s[18:19], 0, v[132:133]
	s_mov_b32 m0, s67
	s_nop 0
	global_load_lds_dwordx4 v[212:213], off
	v_lshl_add_u64 v[212:213], s[18:19], 0, v[128:129]
	s_mov_b32 m0, s68
	s_nop 0
	global_load_lds_dwordx4 v[212:213], off
	v_lshl_add_u64 v[212:213], v[216:217], 0, s[12:13]
	s_mov_b32 m0, s30
	s_nop 0
	global_load_lds_dwordx4 v[212:213], off
	v_lshl_add_u64 v[212:213], v[218:219], 0, s[12:13]
	s_mov_b32 m0, s34
	s_nop 0
	global_load_lds_dwordx4 v[212:213], off
	s_waitcnt vmcnt(8)
	s_waitcnt lgkmcnt(0)
	s_barrier
	s_setprio 1
	s_waitcnt lgkmcnt(0)
	v_mfma_f32_16x16x32_bf16 v[60:63], v[148:151], v[180:183], v[60:63]
	v_mfma_f32_16x16x32_bf16 v[56:59], v[156:159], v[180:183], v[56:59]
	v_mfma_f32_16x16x32_bf16 v[44:47], v[148:151], v[188:191], v[44:47]
	v_mfma_f32_16x16x32_bf16 v[40:43], v[156:159], v[188:191], v[40:43]
	v_mfma_f32_16x16x32_bf16 v[28:31], v[148:151], v[196:199], v[28:31]
	v_mfma_f32_16x16x32_bf16 v[24:27], v[156:159], v[196:199], v[24:27]
	v_mfma_f32_16x16x32_bf16 v[12:15], v[148:151], v[204:207], v[12:15]
	v_mfma_f32_16x16x32_bf16 v[8:11], v[156:159], v[204:207], v[8:11]
	v_mfma_f32_16x16x32_bf16 v[60:63], v[152:155], v[184:187], v[60:63]
	v_mfma_f32_16x16x32_bf16 v[56:59], v[160:163], v[184:187], v[56:59]
	v_mfma_f32_16x16x32_bf16 v[44:47], v[152:155], v[192:195], v[44:47]
	v_mfma_f32_16x16x32_bf16 v[40:43], v[160:163], v[192:195], v[40:43]
	v_mfma_f32_16x16x32_bf16 v[28:31], v[152:155], v[200:203], v[28:31]
	v_mfma_f32_16x16x32_bf16 v[24:27], v[160:163], v[200:203], v[24:27]
	v_mfma_f32_16x16x32_bf16 v[12:15], v[152:155], v[208:211], v[12:15]
	v_mfma_f32_16x16x32_bf16 v[8:11], v[160:163], v[208:211], v[8:11]
	v_mfma_f32_16x16x32_bf16 v[52:55], v[164:167], v[180:183], v[52:55]
	v_mfma_f32_16x16x32_bf16 v[48:51], v[172:175], v[180:183], v[48:51]
	v_mfma_f32_16x16x32_bf16 v[36:39], v[164:167], v[188:191], v[36:39]
	v_mfma_f32_16x16x32_bf16 v[32:35], v[172:175], v[188:191], v[32:35]
	v_mfma_f32_16x16x32_bf16 v[20:23], v[164:167], v[196:199], v[20:23]
	v_mfma_f32_16x16x32_bf16 v[16:19], v[172:175], v[196:199], v[16:19]
	v_mfma_f32_16x16x32_bf16 v[4:7], v[164:167], v[204:207], v[4:7]
	v_mfma_f32_16x16x32_bf16 v[0:3], v[172:175], v[204:207], v[0:3]
	v_mfma_f32_16x16x32_bf16 v[52:55], v[168:171], v[184:187], v[52:55]
	v_mfma_f32_16x16x32_bf16 v[48:51], v[176:179], v[184:187], v[48:51]
	v_mfma_f32_16x16x32_bf16 v[36:39], v[168:171], v[192:195], v[36:39]
	v_mfma_f32_16x16x32_bf16 v[32:35], v[176:179], v[192:195], v[32:35]
	v_mfma_f32_16x16x32_bf16 v[20:23], v[168:171], v[200:203], v[20:23]
	v_mfma_f32_16x16x32_bf16 v[16:19], v[176:179], v[200:203], v[16:19]
	v_mfma_f32_16x16x32_bf16 v[4:7], v[168:171], v[208:211], v[4:7]
	v_mfma_f32_16x16x32_bf16 v[0:3], v[176:179], v[208:211], v[0:3]
	s_barrier
	s_setprio 0
	s_add_i32 s35, s35, 2
	s_add_u32 s16, s16, 0x100
	s_addc_u32 s17, s17, 0
	s_cmp_gt_u32 s35, 29
	s_cbranch_scc0 .LBB0_946
	s_cmpk_lt_u32 s80, 0x100
	s_cbranch_scc0 .LBB0_949
	s_barrier

.LBB0_1693:
	ds_read_b128 v[140:143], v149
	ds_read_b128 v[152:155], v149 offset:1024
	ds_read_b128 v[156:159], v149 offset:2048
	ds_read_b128 v[160:163], v149 offset:3072
	ds_read_b128 v[164:167], v150
	ds_read_b128 v[168:171], v150 offset:1024
	ds_read_b128 v[172:175], v150 offset:2048
	ds_read_b128 v[176:179], v150 offset:3072
	s_add_u32 s76, s74, 0xfff80080
	s_addc_u32 s77, s75, -1
	s_cmp_eq_u32 s86, 28
	s_cselect_b32 s79, s67, s77
	s_cselect_b32 s78, s73, s76
	s_cselect_b32 s77, s65, s85
	s_cselect_b32 s76, s83, s84
	v_lshl_add_u64 v[212:213], s[74:75], 0, v[132:133]
	s_add_i32 m0, s6, 0xc000
	ds_read_b128 v[180:183], v151
	ds_read_b128 v[184:187], v151 offset:1024
	ds_read_b128 v[188:191], v151 offset:2048
	ds_read_b128 v[192:195], v151 offset:3072
	ds_read_b128 v[196:199], v151 offset:4096
	ds_read_b128 v[200:203], v151 offset:5120
	ds_read_b128 v[204:207], v151 offset:6144
	ds_read_b128 v[208:211], v151 offset:7168
	global_load_lds_dwordx4 v[212:213], off
	v_lshl_add_u64 v[212:213], s[74:75], 0, v[134:135]
	s_add_i32 m0, s6, 0xe000
	s_nop 0
	global_load_lds_dwordx4 v[212:213], off
	s_waitcnt vmcnt(8)
	s_waitcnt lgkmcnt(0)
	s_barrier
	s_setprio 1
	s_waitcnt lgkmcnt(0)
	v_mfma_f32_16x16x32_bf16 v[124:127], v[140:143], v[180:183], v[124:127]
	v_mfma_f32_16x16x32_bf16 v[120:123], v[156:159], v[180:183], v[120:123]
	v_mfma_f32_16x16x32_bf16 v[108:111], v[140:143], v[188:191], v[108:111]
	v_mfma_f32_16x16x32_bf16 v[104:107], v[156:159], v[188:191], v[104:107]
	v_mfma_f32_16x16x32_bf16 v[92:95], v[140:143], v[196:199], v[92:95]
	v_mfma_f32_16x16x32_bf16 v[88:91], v[156:159], v[196:199], v[88:91]
	v_mfma_f32_16x16x32_bf16 v[76:79], v[140:143], v[204:207], v[76:79]
	v_mfma_f32_16x16x32_bf16 v[72:75], v[156:159], v[204:207], v[72:75]
	v_mfma_f32_16x16x32_bf16 v[124:127], v[152:155], v[184:187], v[124:127]
	v_mfma_f32_16x16x32_bf16 v[120:123], v[160:163], v[184:187], v[120:123]
	v_mfma_f32_16x16x32_bf16 v[108:111], v[152:155], v[192:195], v[108:111]
	v_mfma_f32_16x16x32_bf16 v[104:107], v[160:163], v[192:195], v[104:107]
	v_mfma_f32_16x16x32_bf16 v[92:95], v[152:155], v[200:203], v[92:95]
	v_mfma_f32_16x16x32_bf16 v[88:91], v[160:163], v[200:203], v[88:91]
	v_mfma_f32_16x16x32_bf16 v[76:79], v[152:155], v[208:211], v[76:79]
	v_mfma_f32_16x16x32_bf16 v[72:75], v[160:163], v[208:211], v[72:75]
	v_mfma_f32_16x16x32_bf16 v[116:119], v[164:167], v[180:183], v[116:119]
	v_mfma_f32_16x16x32_bf16 v[112:115], v[172:175], v[180:183], v[112:115]
	v_mfma_f32_16x16x32_bf16 v[100:103], v[164:167], v[188:191], v[100:103]
	v_mfma_f32_16x16x32_bf16 v[96:99], v[172:175], v[188:191], v[96:99]
	v_mfma_f32_16x16x32_bf16 v[84:87], v[164:167], v[196:199], v[84:87]
	v_mfma_f32_16x16x32_bf16 v[80:83], v[172:175], v[196:199], v[80:83]
	v_mfma_f32_16x16x32_bf16 v[68:71], v[164:167], v[204:207], v[68:71]
	v_mfma_f32_16x16x32_bf16 v[64:67], v[172:175], v[204:207], v[64:67]
	v_mfma_f32_16x16x32_bf16 v[116:119], v[168:171], v[184:187], v[116:119]
	v_mfma_f32_16x16x32_bf16 v[112:115], v[176:179], v[184:187], v[112:115]
	v_mfma_f32_16x16x32_bf16 v[100:103], v[168:171], v[192:195], v[100:103]
	v_mfma_f32_16x16x32_bf16 v[96:99], v[176:179], v[192:195], v[96:99]
	v_mfma_f32_16x16x32_bf16 v[84:87], v[168:171], v[200:203], v[84:87]
	v_mfma_f32_16x16x32_bf16 v[80:83], v[176:179], v[200:203], v[80:83]
	v_mfma_f32_16x16x32_bf16 v[68:71], v[168:171], v[208:211], v[68:71]
	v_mfma_f32_16x16x32_bf16 v[64:67], v[176:179], v[208:211], v[64:67]
	s_barrier
	s_setprio 0
	s_add_i32 s87, s57, s94
	v_lshl_add_u64 v[212:213], s[76:77], 0, v[128:129]
	s_mov_b32 m0, s87
	ds_read_b128 v[180:183], v151 offset:16384
	ds_read_b128 v[184:187], v151 offset:17408
	ds_read_b128 v[188:191], v151 offset:18432
	ds_read_b128 v[192:195], v151 offset:19456
	ds_read_b128 v[196:199], v151 offset:20480
	ds_read_b128 v[200:203], v151 offset:21504
	ds_read_b128 v[204:207], v151 offset:22528
	ds_read_b128 v[208:211], v151 offset:23552
	global_load_lds_dwordx4 v[212:213], off
	s_add_i32 m0, s87, 0x2000
	s_add_u32 s88, s76, 0x80000
	v_lshl_add_u64 v[214:215], s[76:77], 0, v[130:131]
	s_addc_u32 s89, s77, 0
	s_add_i32 s87, s81, s94
	global_load_lds_dwordx4 v[214:215], off
	v_lshl_add_u64 v[216:217], s[88:89], 0, v[128:129]
	s_mov_b32 m0, s87
	v_lshl_add_u64 v[218:219], s[78:79], 0, v[130:131]
	global_load_lds_dwordx4 v[216:217], off
	v_lshl_add_u64 v[216:217], s[88:89], 0, v[130:131]
	s_add_i32 m0, s87, 0x2000
	s_nop 0
	global_load_lds_dwordx4 v[216:217], off
	v_lshl_add_u64 v[216:217], s[78:79], 0, v[128:129]
	s_mov_b32 m0, s6
	s_nop 0
	global_load_lds_dwordx4 v[216:217], off
	s_mov_b32 m0, s7
	s_nop 0
	global_load_lds_dwordx4 v[218:219], off
	s_waitcnt vmcnt(8)
	s_waitcnt lgkmcnt(0)
	s_barrier
	s_setprio 1
	s_waitcnt lgkmcnt(0)
	v_mfma_f32_16x16x32_bf16 v[60:63], v[140:143], v[180:183], v[60:63]
	v_mfma_f32_16x16x32_bf16 v[56:59], v[156:159], v[180:183], v[56:59]
	v_mfma_f32_16x16x32_bf16 v[44:47], v[140:143], v[188:191], v[44:47]
	v_mfma_f32_16x16x32_bf16 v[40:43], v[156:159], v[188:191], v[40:43]
	v_mfma_f32_16x16x32_bf16 v[28:31], v[140:143], v[196:199], v[28:31]
	v_mfma_f32_16x16x32_bf16 v[24:27], v[156:159], v[196:199], v[24:27]
	v_mfma_f32_16x16x32_bf16 v[12:15], v[140:143], v[204:207], v[12:15]
	v_mfma_f32_16x16x32_bf16 v[8:11], v[156:159], v[204:207], v[8:11]
	v_mfma_f32_16x16x32_bf16 v[60:63], v[152:155], v[184:187], v[60:63]
	v_mfma_f32_16x16x32_bf16 v[56:59], v[160:163], v[184:187], v[56:59]
	v_mfma_f32_16x16x32_bf16 v[44:47], v[152:155], v[192:195], v[44:47]
	v_mfma_f32_16x16x32_bf16 v[40:43], v[160:163], v[192:195], v[40:43]
	v_mfma_f32_16x16x32_bf16 v[28:31], v[152:155], v[200:203], v[28:31]
	v_mfma_f32_16x16x32_bf16 v[24:27], v[160:163], v[200:203], v[24:27]
	v_mfma_f32_16x16x32_bf16 v[12:15], v[152:155], v[208:211], v[12:15]
	v_mfma_f32_16x16x32_bf16 v[8:11], v[160:163], v[208:211], v[8:11]
	v_mfma_f32_16x16x32_bf16 v[52:55], v[164:167], v[180:183], v[52:55]
	v_mfma_f32_16x16x32_bf16 v[48:51], v[172:175], v[180:183], v[48:51]
	v_mfma_f32_16x16x32_bf16 v[36:39], v[164:167], v[188:191], v[36:39]
	v_mfma_f32_16x16x32_bf16 v[32:35], v[172:175], v[188:191], v[32:35]
	v_mfma_f32_16x16x32_bf16 v[20:23], v[164:167], v[196:199], v[20:23]
	v_mfma_f32_16x16x32_bf16 v[16:19], v[172:175], v[196:199], v[16:19]
	v_mfma_f32_16x16x32_bf16 v[4:7], v[164:167], v[204:207], v[4:7]
	v_mfma_f32_16x16x32_bf16 v[0:3], v[172:175], v[204:207], v[0:3]
	v_mfma_f32_16x16x32_bf16 v[52:55], v[168:171], v[184:187], v[52:55]
	v_mfma_f32_16x16x32_bf16 v[48:51], v[176:179], v[184:187], v[48:51]
	v_mfma_f32_16x16x32_bf16 v[36:39], v[168:171], v[192:195], v[36:39]
	v_mfma_f32_16x16x32_bf16 v[32:35], v[176:179], v[192:195], v[32:35]
	v_mfma_f32_16x16x32_bf16 v[20:23], v[168:171], v[200:203], v[20:23]
	v_mfma_f32_16x16x32_bf16 v[16:19], v[176:179], v[200:203], v[16:19]
	v_mfma_f32_16x16x32_bf16 v[4:7], v[168:171], v[208:211], v[4:7]
	v_mfma_f32_16x16x32_bf16 v[0:3], v[176:179], v[208:211], v[0:3]
	s_barrier
	s_setprio 0
	s_add_i32 s87, 0, 0x18000
	s_add_i32 s88, 0, 0x1c000
	v_add_u32_e32 v160, s87, v145
	v_add_u32_e32 v176, s88, v145
	ds_read_b128 v[140:143], v160
	ds_read_b128 v[152:155], v160 offset:1024
	ds_read_b128 v[156:159], v160 offset:2048
	ds_read_b128 v[160:163], v160 offset:3072
	ds_read_b128 v[164:167], v176
	ds_read_b128 v[168:171], v176 offset:1024
	ds_read_b128 v[172:175], v176 offset:2048
	ds_read_b128 v[176:179], v176 offset:3072
	s_add_u32 s78, s78, 0x80000
	s_addc_u32 s79, s79, 0
	s_mov_b32 m0, s29
	v_lshl_add_u64 v[220:221], s[78:79], 0, v[128:129]
	ds_read_b128 v[180:183], v151 offset:32768
	ds_read_b128 v[184:187], v151 offset:33792
	ds_read_b128 v[188:191], v151 offset:34816
	ds_read_b128 v[192:195], v151 offset:35840
	ds_read_b128 v[196:199], v151 offset:36864
	ds_read_b128 v[200:203], v151 offset:37888
	ds_read_b128 v[204:207], v151 offset:38912
	ds_read_b128 v[208:211], v151 offset:39936
	global_load_lds_dwordx4 v[220:221], off
	v_lshl_add_u64 v[220:221], s[78:79], 0, v[130:131]
	s_mov_b32 m0, s30
	s_nop 0
	global_load_lds_dwordx4 v[220:221], off
	s_waitcnt vmcnt(8)
	s_waitcnt lgkmcnt(0)
	s_barrier
	s_setprio 1
	s_waitcnt lgkmcnt(0)
	v_mfma_f32_16x16x32_bf16 v[124:127], v[140:143], v[180:183], v[124:127]
	v_mfma_f32_16x16x32_bf16 v[120:123], v[156:159], v[180:183], v[120:123]
	v_mfma_f32_16x16x32_bf16 v[108:111], v[140:143], v[188:191], v[108:111]
	v_mfma_f32_16x16x32_bf16 v[104:107], v[156:159], v[188:191], v[104:107]
	v_mfma_f32_16x16x32_bf16 v[92:95], v[140:143], v[196:199], v[92:95]
	v_mfma_f32_16x16x32_bf16 v[88:91], v[156:159], v[196:199], v[88:91]
	v_mfma_f32_16x16x32_bf16 v[76:79], v[140:143], v[204:207], v[76:79]
	v_mfma_f32_16x16x32_bf16 v[72:75], v[156:159], v[204:207], v[72:75]
	v_mfma_f32_16x16x32_bf16 v[124:127], v[152:155], v[184:187], v[124:127]
	v_mfma_f32_16x16x32_bf16 v[120:123], v[160:163], v[184:187], v[120:123]
	v_mfma_f32_16x16x32_bf16 v[108:111], v[152:155], v[192:195], v[108:111]
	v_mfma_f32_16x16x32_bf16 v[104:107], v[160:163], v[192:195], v[104:107]
	v_mfma_f32_16x16x32_bf16 v[92:95], v[152:155], v[200:203], v[92:95]
	v_mfma_f32_16x16x32_bf16 v[88:91], v[160:163], v[200:203], v[88:91]
	v_mfma_f32_16x16x32_bf16 v[76:79], v[152:155], v[208:211], v[76:79]
	v_mfma_f32_16x16x32_bf16 v[72:75], v[160:163], v[208:211], v[72:75]
	v_mfma_f32_16x16x32_bf16 v[116:119], v[164:167], v[180:183], v[116:119]
	v_mfma_f32_16x16x32_bf16 v[112:115], v[172:175], v[180:183], v[112:115]
	v_mfma_f32_16x16x32_bf16 v[100:103], v[164:167], v[188:191], v[100:103]
	v_mfma_f32_16x16x32_bf16 v[96:99], v[172:175], v[188:191], v[96:99]
	v_mfma_f32_16x16x32_bf16 v[84:87], v[164:167], v[196:199], v[84:87]
	v_mfma_f32_16x16x32_bf16 v[80:83], v[172:175], v[196:199], v[80:83]
	v_mfma_f32_16x16x32_bf16 v[68:71], v[164:167], v[204:207], v[68:71]
	v_mfma_f32_16x16x32_bf16 v[64:67], v[172:175], v[204:207], v[64:67]
	v_mfma_f32_16x16x32_bf16 v[116:119], v[168:171], v[184:187], v[116:119]
	v_mfma_f32_16x16x32_bf16 v[112:115], v[176:179], v[184:187], v[112:115]
	v_mfma_f32_16x16x32_bf16 v[100:103], v[168:171], v[192:195], v[100:103]
	v_mfma_f32_16x16x32_bf16 v[96:99], v[176:179], v[192:195], v[96:99]
	v_mfma_f32_16x16x32_bf16 v[84:87], v[168:171], v[200:203], v[84:87]
	v_mfma_f32_16x16x32_bf16 v[80:83], v[176:179], v[200:203], v[80:83]
	v_mfma_f32_16x16x32_bf16 v[68:71], v[168:171], v[208:211], v[68:71]
	v_mfma_f32_16x16x32_bf16 v[64:67], v[176:179], v[208:211], v[64:67]
	s_barrier
	s_setprio 0
	s_add_i32 s78, s87, s94
	v_lshl_add_u64 v[212:213], v[212:213], 0, s[58:59]
	s_mov_b32 m0, s78
	ds_read_b128 v[180:183], v151 offset:49152
	ds_read_b128 v[184:187], v151 offset:50176
	ds_read_b128 v[188:191], v151 offset:51200
	ds_read_b128 v[192:195], v151 offset:52224
	ds_read_b128 v[196:199], v151 offset:53248
	ds_read_b128 v[200:203], v151 offset:54272
	ds_read_b128 v[204:207], v151 offset:55296
	ds_read_b128 v[208:211], v151 offset:56320
	global_load_lds_dwordx4 v[212:213], off
	s_add_i32 m0, s78, 0x2000
	s_add_u32 s76, s76, 0x80080
	v_lshl_add_u64 v[212:213], v[214:215], 0, s[58:59]
	s_addc_u32 s77, s77, 0
	s_add_i32 s78, s88, s94
	global_load_lds_dwordx4 v[212:213], off
	v_lshl_add_u64 v[212:213], s[76:77], 0, v[128:129]
	s_mov_b32 m0, s78
	s_nop 0
	global_load_lds_dwordx4 v[212:213], off
	v_lshl_add_u64 v[212:213], s[76:77], 0, v[130:131]
	s_add_i32 m0, s78, 0x2000
	s_nop 0
	global_load_lds_dwordx4 v[212:213], off
	v_lshl_add_u64 v[212:213], v[216:217], 0, s[58:59]
	s_mov_b32 m0, s34
	s_nop 0
	global_load_lds_dwordx4 v[212:213], off
	v_lshl_add_u64 v[212:213], v[218:219], 0, s[58:59]
	s_mov_b32 m0, s35
	s_nop 0
	global_load_lds_dwordx4 v[212:213], off
	s_waitcnt vmcnt(8)
	s_waitcnt lgkmcnt(0)
	s_barrier
	s_setprio 1
	s_waitcnt lgkmcnt(0)
	v_mfma_f32_16x16x32_bf16 v[60:63], v[140:143], v[180:183], v[60:63]
	v_mfma_f32_16x16x32_bf16 v[56:59], v[156:159], v[180:183], v[56:59]
	v_mfma_f32_16x16x32_bf16 v[44:47], v[140:143], v[188:191], v[44:47]
	v_mfma_f32_16x16x32_bf16 v[40:43], v[156:159], v[188:191], v[40:43]
	v_mfma_f32_16x16x32_bf16 v[28:31], v[140:143], v[196:199], v[28:31]
	v_mfma_f32_16x16x32_bf16 v[24:27], v[156:159], v[196:199], v[24:27]
	v_mfma_f32_16x16x32_bf16 v[12:15], v[140:143], v[204:207], v[12:15]
	v_mfma_f32_16x16x32_bf16 v[8:11], v[156:159], v[204:207], v[8:11]
	v_mfma_f32_16x16x32_bf16 v[60:63], v[152:155], v[184:187], v[60:63]
	v_mfma_f32_16x16x32_bf16 v[56:59], v[160:163], v[184:187], v[56:59]
	v_mfma_f32_16x16x32_bf16 v[44:47], v[152:155], v[192:195], v[44:47]
	v_mfma_f32_16x16x32_bf16 v[40:43], v[160:163], v[192:195], v[40:43]
	v_mfma_f32_16x16x32_bf16 v[28:31], v[152:155], v[200:203], v[28:31]
	v_mfma_f32_16x16x32_bf16 v[24:27], v[160:163], v[200:203], v[24:27]
	v_mfma_f32_16x16x32_bf16 v[12:15], v[152:155], v[208:211], v[12:15]
	v_mfma_f32_16x16x32_bf16 v[8:11], v[160:163], v[208:211], v[8:11]
	v_mfma_f32_16x16x32_bf16 v[52:55], v[164:167], v[180:183], v[52:55]
	v_mfma_f32_16x16x32_bf16 v[48:51], v[172:175], v[180:183], v[48:51]
	v_mfma_f32_16x16x32_bf16 v[36:39], v[164:167], v[188:191], v[36:39]
	v_mfma_f32_16x16x32_bf16 v[32:35], v[172:175], v[188:191], v[32:35]
	v_mfma_f32_16x16x32_bf16 v[20:23], v[164:167], v[196:199], v[20:23]
	v_mfma_f32_16x16x32_bf16 v[16:19], v[172:175], v[196:199], v[16:19]
	v_mfma_f32_16x16x32_bf16 v[4:7], v[164:167], v[204:207], v[4:7]
	v_mfma_f32_16x16x32_bf16 v[0:3], v[172:175], v[204:207], v[0:3]
	v_mfma_f32_16x16x32_bf16 v[52:55], v[168:171], v[184:187], v[52:55]
	v_mfma_f32_16x16x32_bf16 v[48:51], v[176:179], v[184:187], v[48:51]
	v_mfma_f32_16x16x32_bf16 v[36:39], v[168:171], v[192:195], v[36:39]
	v_mfma_f32_16x16x32_bf16 v[32:35], v[176:179], v[192:195], v[32:35]
	v_mfma_f32_16x16x32_bf16 v[20:23], v[168:171], v[200:203], v[20:23]
	v_mfma_f32_16x16x32_bf16 v[16:19], v[176:179], v[200:203], v[16:19]
	v_mfma_f32_16x16x32_bf16 v[4:7], v[168:171], v[208:211], v[4:7]
	v_mfma_f32_16x16x32_bf16 v[0:3], v[176:179], v[208:211], v[0:3]
	s_barrier
	s_setprio 0
	s_add_i32 s86, s86, 2
	s_add_u32 s74, s74, 0x100
	s_addc_u32 s75, s75, 0
	s_add_u32 s84, s84, 0x100
	s_addc_u32 s85, s85, 0
	s_cmp_gt_u32 s86, 29
	s_cbranch_scc0 .LBB0_1693
	s_and_b64 vcc, exec, s[60:61]
	s_cbranch_vccz .LBB0_1696
	s_barrier

.LBB0_1785:
	ds_read_b128 v[146:149], v155
	ds_read_b128 v[160:163], v155 offset:1024
	ds_read_b128 v[164:167], v155 offset:2048
	ds_read_b128 v[168:171], v155 offset:3072
	ds_read_b128 v[172:175], v156
	ds_read_b128 v[176:179], v156 offset:1024
	ds_read_b128 v[180:183], v156 offset:2048
	ds_read_b128 v[184:187], v156 offset:3072
	s_add_u32 s60, s72, 0xfff80080
	s_addc_u32 s61, s73, -1
	s_cmp_eq_u32 s78, 28
	s_cselect_b32 s77, s56, s61
	s_cselect_b32 s76, s57, s60
	s_cselect_b32 s75, s23, s71
	s_cselect_b32 s74, s63, s69
	v_lshl_add_u64 v[220:221], s[72:73], 0, v[138:139]
	s_add_i32 m0, s6, 0xc000
	ds_read_b128 v[188:191], v157
	ds_read_b128 v[192:195], v157 offset:1024
	ds_read_b128 v[196:199], v157 offset:2048
	ds_read_b128 v[200:203], v157 offset:3072
	ds_read_b128 v[204:207], v157 offset:4096
	ds_read_b128 v[208:211], v157 offset:5120
	ds_read_b128 v[212:215], v157 offset:6144
	ds_read_b128 v[216:219], v157 offset:7168
	global_load_lds_dwordx4 v[220:221], off
	v_lshl_add_u64 v[220:221], s[72:73], 0, v[140:141]
	s_add_i32 m0, s6, 0xe000
	s_nop 0
	global_load_lds_dwordx4 v[220:221], off
	s_waitcnt vmcnt(8)
	s_waitcnt lgkmcnt(0)
	s_barrier
	s_setprio 1
	s_waitcnt lgkmcnt(0)
	v_mfma_f32_16x16x32_bf16 v[124:127], v[146:149], v[188:191], v[124:127]
	v_mfma_f32_16x16x32_bf16 v[120:123], v[164:167], v[188:191], v[120:123]
	v_mfma_f32_16x16x32_bf16 v[108:111], v[146:149], v[196:199], v[108:111]
	v_mfma_f32_16x16x32_bf16 v[104:107], v[164:167], v[196:199], v[104:107]
	v_mfma_f32_16x16x32_bf16 v[92:95], v[146:149], v[204:207], v[92:95]
	v_mfma_f32_16x16x32_bf16 v[88:91], v[164:167], v[204:207], v[88:91]
	v_mfma_f32_16x16x32_bf16 v[76:79], v[146:149], v[212:215], v[76:79]
	v_mfma_f32_16x16x32_bf16 v[72:75], v[164:167], v[212:215], v[72:75]
	v_mfma_f32_16x16x32_bf16 v[124:127], v[160:163], v[192:195], v[124:127]
	v_mfma_f32_16x16x32_bf16 v[120:123], v[168:171], v[192:195], v[120:123]
	v_mfma_f32_16x16x32_bf16 v[108:111], v[160:163], v[200:203], v[108:111]
	v_mfma_f32_16x16x32_bf16 v[104:107], v[168:171], v[200:203], v[104:107]
	v_mfma_f32_16x16x32_bf16 v[92:95], v[160:163], v[208:211], v[92:95]
	v_mfma_f32_16x16x32_bf16 v[88:91], v[168:171], v[208:211], v[88:91]
	v_mfma_f32_16x16x32_bf16 v[76:79], v[160:163], v[216:219], v[76:79]
	v_mfma_f32_16x16x32_bf16 v[72:75], v[168:171], v[216:219], v[72:75]
	v_mfma_f32_16x16x32_bf16 v[116:119], v[172:175], v[188:191], v[116:119]
	v_mfma_f32_16x16x32_bf16 v[112:115], v[180:183], v[188:191], v[112:115]
	v_mfma_f32_16x16x32_bf16 v[100:103], v[172:175], v[196:199], v[100:103]
	v_mfma_f32_16x16x32_bf16 v[96:99], v[180:183], v[196:199], v[96:99]
	v_mfma_f32_16x16x32_bf16 v[84:87], v[172:175], v[204:207], v[84:87]
	v_mfma_f32_16x16x32_bf16 v[80:83], v[180:183], v[204:207], v[80:83]
	v_mfma_f32_16x16x32_bf16 v[68:71], v[172:175], v[212:215], v[68:71]
	v_mfma_f32_16x16x32_bf16 v[64:67], v[180:183], v[212:215], v[64:67]
	v_mfma_f32_16x16x32_bf16 v[116:119], v[176:179], v[192:195], v[116:119]
	v_mfma_f32_16x16x32_bf16 v[112:115], v[184:187], v[192:195], v[112:115]
	v_mfma_f32_16x16x32_bf16 v[100:103], v[176:179], v[200:203], v[100:103]
	v_mfma_f32_16x16x32_bf16 v[96:99], v[184:187], v[200:203], v[96:99]
	v_mfma_f32_16x16x32_bf16 v[84:87], v[176:179], v[208:211], v[84:87]
	v_mfma_f32_16x16x32_bf16 v[80:83], v[184:187], v[208:211], v[80:83]
	v_mfma_f32_16x16x32_bf16 v[68:71], v[176:179], v[216:219], v[68:71]
	v_mfma_f32_16x16x32_bf16 v[64:67], v[184:187], v[216:219], v[64:67]
	s_barrier
	s_setprio 0
	s_add_i32 s60, s35, s94
	v_lshl_add_u64 v[220:221], s[74:75], 0, v[130:131]
	s_mov_b32 m0, s60
	ds_read_b128 v[188:191], v157 offset:16384
	ds_read_b128 v[192:195], v157 offset:17408
	ds_read_b128 v[196:199], v157 offset:18432
	ds_read_b128 v[200:203], v157 offset:19456
	ds_read_b128 v[204:207], v157 offset:20480
	ds_read_b128 v[208:211], v157 offset:21504
	ds_read_b128 v[212:215], v157 offset:22528
	ds_read_b128 v[216:219], v157 offset:23552
	global_load_lds_dwordx4 v[220:221], off
	s_add_i32 m0, s60, 0x2000
	s_add_u32 s80, s74, 0x80000
	v_lshl_add_u64 v[222:223], s[74:75], 0, v[134:135]
	s_addc_u32 s81, s75, 0
	s_add_i32 s60, s46, s94
	global_load_lds_dwordx4 v[222:223], off
	v_lshl_add_u64 v[224:225], s[80:81], 0, v[130:131]
	s_mov_b32 m0, s60
	v_lshl_add_u64 v[226:227], s[76:77], 0, v[132:133]
	global_load_lds_dwordx4 v[224:225], off
	v_lshl_add_u64 v[224:225], s[80:81], 0, v[134:135]
	s_add_i32 m0, s60, 0x2000
	s_nop 0
	global_load_lds_dwordx4 v[224:225], off
	v_lshl_add_u64 v[224:225], s[76:77], 0, v[128:129]
	s_mov_b32 m0, s6
	s_nop 0
	global_load_lds_dwordx4 v[224:225], off
	s_mov_b32 m0, s7
	s_nop 0
	global_load_lds_dwordx4 v[226:227], off
	s_waitcnt vmcnt(8)
	s_waitcnt lgkmcnt(0)
	s_barrier
	s_setprio 1
	s_waitcnt lgkmcnt(0)
	v_mfma_f32_16x16x32_bf16 v[60:63], v[146:149], v[188:191], v[60:63]
	v_mfma_f32_16x16x32_bf16 v[56:59], v[164:167], v[188:191], v[56:59]
	v_mfma_f32_16x16x32_bf16 v[44:47], v[146:149], v[196:199], v[44:47]
	v_mfma_f32_16x16x32_bf16 v[40:43], v[164:167], v[196:199], v[40:43]
	v_mfma_f32_16x16x32_bf16 v[28:31], v[146:149], v[204:207], v[28:31]
	v_mfma_f32_16x16x32_bf16 v[24:27], v[164:167], v[204:207], v[24:27]
	v_mfma_f32_16x16x32_bf16 v[12:15], v[146:149], v[212:215], v[12:15]
	v_mfma_f32_16x16x32_bf16 v[8:11], v[164:167], v[212:215], v[8:11]
	v_mfma_f32_16x16x32_bf16 v[60:63], v[160:163], v[192:195], v[60:63]
	v_mfma_f32_16x16x32_bf16 v[56:59], v[168:171], v[192:195], v[56:59]
	v_mfma_f32_16x16x32_bf16 v[44:47], v[160:163], v[200:203], v[44:47]
	v_mfma_f32_16x16x32_bf16 v[40:43], v[168:171], v[200:203], v[40:43]
	v_mfma_f32_16x16x32_bf16 v[28:31], v[160:163], v[208:211], v[28:31]
	v_mfma_f32_16x16x32_bf16 v[24:27], v[168:171], v[208:211], v[24:27]
	v_mfma_f32_16x16x32_bf16 v[12:15], v[160:163], v[216:219], v[12:15]
	v_mfma_f32_16x16x32_bf16 v[8:11], v[168:171], v[216:219], v[8:11]
	v_mfma_f32_16x16x32_bf16 v[52:55], v[172:175], v[188:191], v[52:55]
	v_mfma_f32_16x16x32_bf16 v[48:51], v[180:183], v[188:191], v[48:51]
	v_mfma_f32_16x16x32_bf16 v[36:39], v[172:175], v[196:199], v[36:39]
	v_mfma_f32_16x16x32_bf16 v[32:35], v[180:183], v[196:199], v[32:35]
	v_mfma_f32_16x16x32_bf16 v[20:23], v[172:175], v[204:207], v[20:23]
	v_mfma_f32_16x16x32_bf16 v[16:19], v[180:183], v[204:207], v[16:19]
	v_mfma_f32_16x16x32_bf16 v[4:7], v[172:175], v[212:215], v[4:7]
	v_mfma_f32_16x16x32_bf16 v[0:3], v[180:183], v[212:215], v[0:3]
	v_mfma_f32_16x16x32_bf16 v[52:55], v[176:179], v[192:195], v[52:55]
	v_mfma_f32_16x16x32_bf16 v[48:51], v[184:187], v[192:195], v[48:51]
	v_mfma_f32_16x16x32_bf16 v[36:39], v[176:179], v[200:203], v[36:39]
	v_mfma_f32_16x16x32_bf16 v[32:35], v[184:187], v[200:203], v[32:35]
	v_mfma_f32_16x16x32_bf16 v[20:23], v[176:179], v[208:211], v[20:23]
	v_mfma_f32_16x16x32_bf16 v[16:19], v[184:187], v[208:211], v[16:19]
	v_mfma_f32_16x16x32_bf16 v[4:7], v[176:179], v[216:219], v[4:7]
	v_mfma_f32_16x16x32_bf16 v[0:3], v[184:187], v[216:219], v[0:3]
	s_barrier
	s_setprio 0
	s_add_i32 s60, 0, 0x18000
	v_add_u32_e32 v159, s60, v151
	s_add_i32 s61, 0, 0x1c000
	ds_read_b128 v[146:149], v159
	ds_read_b128 v[160:163], v159 offset:1024
	ds_read_b128 v[164:167], v159 offset:2048
	ds_read_b128 v[168:171], v159 offset:3072
	v_add_u32_e32 v159, s61, v151
	ds_read_b128 v[172:175], v159
	ds_read_b128 v[176:179], v159 offset:1024
	ds_read_b128 v[180:183], v159 offset:2048
	ds_read_b128 v[184:187], v159 offset:3072
	s_add_u32 s76, s76, 0x80000
	s_addc_u32 s77, s77, 0
	s_mov_b32 m0, s12
	v_lshl_add_u64 v[228:229], s[76:77], 0, v[128:129]
	ds_read_b128 v[188:191], v157 offset:32768
	ds_read_b128 v[192:195], v157 offset:33792
	ds_read_b128 v[196:199], v157 offset:34816
	ds_read_b128 v[200:203], v157 offset:35840
	ds_read_b128 v[204:207], v157 offset:36864
	ds_read_b128 v[208:211], v157 offset:37888
	ds_read_b128 v[212:215], v157 offset:38912
	ds_read_b128 v[216:219], v157 offset:39936
	global_load_lds_dwordx4 v[228:229], off
	v_lshl_add_u64 v[228:229], s[76:77], 0, v[132:133]
	s_mov_b32 m0, s13
	s_nop 0
	global_load_lds_dwordx4 v[228:229], off
	s_waitcnt vmcnt(8)
	s_waitcnt lgkmcnt(0)
	s_barrier
	s_setprio 1
	s_waitcnt lgkmcnt(0)
	v_mfma_f32_16x16x32_bf16 v[124:127], v[146:149], v[188:191], v[124:127]
	v_mfma_f32_16x16x32_bf16 v[120:123], v[164:167], v[188:191], v[120:123]
	v_mfma_f32_16x16x32_bf16 v[108:111], v[146:149], v[196:199], v[108:111]
	v_mfma_f32_16x16x32_bf16 v[104:107], v[164:167], v[196:199], v[104:107]
	v_mfma_f32_16x16x32_bf16 v[92:95], v[146:149], v[204:207], v[92:95]
	v_mfma_f32_16x16x32_bf16 v[88:91], v[164:167], v[204:207], v[88:91]
	v_mfma_f32_16x16x32_bf16 v[76:79], v[146:149], v[212:215], v[76:79]
	v_mfma_f32_16x16x32_bf16 v[72:75], v[164:167], v[212:215], v[72:75]
	v_mfma_f32_16x16x32_bf16 v[124:127], v[160:163], v[192:195], v[124:127]
	v_mfma_f32_16x16x32_bf16 v[120:123], v[168:171], v[192:195], v[120:123]
	v_mfma_f32_16x16x32_bf16 v[108:111], v[160:163], v[200:203], v[108:111]
	v_mfma_f32_16x16x32_bf16 v[104:107], v[168:171], v[200:203], v[104:107]
	v_mfma_f32_16x16x32_bf16 v[92:95], v[160:163], v[208:211], v[92:95]
	v_mfma_f32_16x16x32_bf16 v[88:91], v[168:171], v[208:211], v[88:91]
	v_mfma_f32_16x16x32_bf16 v[76:79], v[160:163], v[216:219], v[76:79]
	v_mfma_f32_16x16x32_bf16 v[72:75], v[168:171], v[216:219], v[72:75]
	v_mfma_f32_16x16x32_bf16 v[116:119], v[172:175], v[188:191], v[116:119]
	v_mfma_f32_16x16x32_bf16 v[112:115], v[180:183], v[188:191], v[112:115]
	v_mfma_f32_16x16x32_bf16 v[100:103], v[172:175], v[196:199], v[100:103]
	v_mfma_f32_16x16x32_bf16 v[96:99], v[180:183], v[196:199], v[96:99]
	v_mfma_f32_16x16x32_bf16 v[84:87], v[172:175], v[204:207], v[84:87]
	v_mfma_f32_16x16x32_bf16 v[80:83], v[180:183], v[204:207], v[80:83]
	v_mfma_f32_16x16x32_bf16 v[68:71], v[172:175], v[212:215], v[68:71]
	v_mfma_f32_16x16x32_bf16 v[64:67], v[180:183], v[212:215], v[64:67]
	v_mfma_f32_16x16x32_bf16 v[116:119], v[176:179], v[192:195], v[116:119]
	v_mfma_f32_16x16x32_bf16 v[112:115], v[184:187], v[192:195], v[112:115]
	v_mfma_f32_16x16x32_bf16 v[100:103], v[176:179], v[200:203], v[100:103]
	v_mfma_f32_16x16x32_bf16 v[96:99], v[184:187], v[200:203], v[96:99]
	v_mfma_f32_16x16x32_bf16 v[84:87], v[176:179], v[208:211], v[84:87]
	v_mfma_f32_16x16x32_bf16 v[80:83], v[184:187], v[208:211], v[80:83]
	v_mfma_f32_16x16x32_bf16 v[68:71], v[176:179], v[216:219], v[68:71]
	v_mfma_f32_16x16x32_bf16 v[64:67], v[184:187], v[216:219], v[64:67]
	s_barrier
	s_setprio 0
	s_add_i32 s60, s60, s94
	v_lshl_add_u64 v[220:221], v[220:221], 0, s[20:21]
	s_mov_b32 m0, s60
	ds_read_b128 v[188:191], v157 offset:49152
	ds_read_b128 v[192:195], v157 offset:50176
	ds_read_b128 v[196:199], v157 offset:51200
	ds_read_b128 v[200:203], v157 offset:52224
	ds_read_b128 v[204:207], v157 offset:53248
	ds_read_b128 v[208:211], v157 offset:54272
	ds_read_b128 v[212:215], v157 offset:55296
	ds_read_b128 v[216:219], v157 offset:56320
	global_load_lds_dwordx4 v[220:221], off
	s_add_i32 m0, s60, 0x2000
	s_add_u32 s74, s74, 0x80080
	v_lshl_add_u64 v[220:221], v[222:223], 0, s[20:21]
	s_addc_u32 s75, s75, 0
	s_add_i32 s60, s61, s94
	global_load_lds_dwordx4 v[220:221], off
	v_lshl_add_u64 v[220:221], s[74:75], 0, v[130:131]
	s_mov_b32 m0, s60
	s_nop 0
	global_load_lds_dwordx4 v[220:221], off
	v_lshl_add_u64 v[220:221], s[74:75], 0, v[134:135]
	s_add_i32 m0, s60, 0x2000
	s_nop 0
	global_load_lds_dwordx4 v[220:221], off
	v_lshl_add_u64 v[220:221], v[224:225], 0, s[20:21]
	s_mov_b32 m0, s30
	s_nop 0
	global_load_lds_dwordx4 v[220:221], off
	v_lshl_add_u64 v[220:221], v[226:227], 0, s[20:21]
	s_mov_b32 m0, s34
	s_nop 0
	global_load_lds_dwordx4 v[220:221], off
	s_waitcnt vmcnt(8)
	s_waitcnt lgkmcnt(0)
	s_barrier
	s_setprio 1
	s_waitcnt lgkmcnt(0)
	v_mfma_f32_16x16x32_bf16 v[60:63], v[146:149], v[188:191], v[60:63]
	v_mfma_f32_16x16x32_bf16 v[56:59], v[164:167], v[188:191], v[56:59]
	v_mfma_f32_16x16x32_bf16 v[44:47], v[146:149], v[196:199], v[44:47]
	v_mfma_f32_16x16x32_bf16 v[40:43], v[164:167], v[196:199], v[40:43]
	v_mfma_f32_16x16x32_bf16 v[28:31], v[146:149], v[204:207], v[28:31]
	v_mfma_f32_16x16x32_bf16 v[24:27], v[164:167], v[204:207], v[24:27]
	v_mfma_f32_16x16x32_bf16 v[12:15], v[146:149], v[212:215], v[12:15]
	v_mfma_f32_16x16x32_bf16 v[8:11], v[164:167], v[212:215], v[8:11]
	v_mfma_f32_16x16x32_bf16 v[60:63], v[160:163], v[192:195], v[60:63]
	v_mfma_f32_16x16x32_bf16 v[56:59], v[168:171], v[192:195], v[56:59]
	v_mfma_f32_16x16x32_bf16 v[44:47], v[160:163], v[200:203], v[44:47]
	v_mfma_f32_16x16x32_bf16 v[40:43], v[168:171], v[200:203], v[40:43]
	v_mfma_f32_16x16x32_bf16 v[28:31], v[160:163], v[208:211], v[28:31]
	v_mfma_f32_16x16x32_bf16 v[24:27], v[168:171], v[208:211], v[24:27]
	v_mfma_f32_16x16x32_bf16 v[12:15], v[160:163], v[216:219], v[12:15]
	v_mfma_f32_16x16x32_bf16 v[8:11], v[168:171], v[216:219], v[8:11]
	v_mfma_f32_16x16x32_bf16 v[52:55], v[172:175], v[188:191], v[52:55]
	v_mfma_f32_16x16x32_bf16 v[48:51], v[180:183], v[188:191], v[48:51]
	v_mfma_f32_16x16x32_bf16 v[36:39], v[172:175], v[196:199], v[36:39]
	v_mfma_f32_16x16x32_bf16 v[32:35], v[180:183], v[196:199], v[32:35]
	v_mfma_f32_16x16x32_bf16 v[20:23], v[172:175], v[204:207], v[20:23]
	v_mfma_f32_16x16x32_bf16 v[16:19], v[180:183], v[204:207], v[16:19]
	v_mfma_f32_16x16x32_bf16 v[4:7], v[172:175], v[212:215], v[4:7]
	v_mfma_f32_16x16x32_bf16 v[0:3], v[180:183], v[212:215], v[0:3]
	v_mfma_f32_16x16x32_bf16 v[52:55], v[176:179], v[192:195], v[52:55]
	v_mfma_f32_16x16x32_bf16 v[48:51], v[184:187], v[192:195], v[48:51]
	v_mfma_f32_16x16x32_bf16 v[36:39], v[176:179], v[200:203], v[36:39]
	v_mfma_f32_16x16x32_bf16 v[32:35], v[184:187], v[200:203], v[32:35]
	v_mfma_f32_16x16x32_bf16 v[20:23], v[176:179], v[208:211], v[20:23]
	v_mfma_f32_16x16x32_bf16 v[16:19], v[184:187], v[208:211], v[16:19]
	v_mfma_f32_16x16x32_bf16 v[4:7], v[176:179], v[216:219], v[4:7]
	v_mfma_f32_16x16x32_bf16 v[0:3], v[184:187], v[216:219], v[0:3]
	s_barrier
	s_setprio 0
	s_add_i32 s78, s78, 2
	s_add_u32 s72, s72, 0x100
	s_addc_u32 s73, s73, 0
	s_add_u32 s69, s69, 0x100
	s_addc_u32 s71, s71, 0
	s_cmp_gt_u32 s78, 29
	s_cbranch_scc0 .LBB0_1785
	s_and_b64 vcc, exec, s[58:59]
	s_cbranch_vccz .LBB0_1788
	s_barrier

.LBB0_1897:
	ds_read_b128 v[140:143], v149
	ds_read_b128 v[152:155], v149 offset:1024
	ds_read_b128 v[156:159], v149 offset:2048
	ds_read_b128 v[160:163], v149 offset:3072
	ds_read_b128 v[164:167], v150
	ds_read_b128 v[168:171], v150 offset:1024
	ds_read_b128 v[172:175], v150 offset:2048
	ds_read_b128 v[176:179], v150 offset:3072
	s_add_u32 s60, s72, 0xffe00080
	s_addc_u32 s61, s73, -1
	s_cmpk_eq_i32 s79, 0x7c
	s_cselect_b32 s77, s56, s61
	s_cselect_b32 s76, s57, s60
	s_cselect_b32 s75, s63, s78
	s_cselect_b32 s74, s65, s71
	v_lshl_add_u64 v[212:213], s[72:73], 0, v[132:133]
	s_add_i32 m0, s6, 0xc000
	ds_read_b128 v[180:183], v151
	ds_read_b128 v[184:187], v151 offset:1024
	ds_read_b128 v[188:191], v151 offset:2048
	ds_read_b128 v[192:195], v151 offset:3072
	ds_read_b128 v[196:199], v151 offset:4096
	ds_read_b128 v[200:203], v151 offset:5120
	ds_read_b128 v[204:207], v151 offset:6144
	ds_read_b128 v[208:211], v151 offset:7168
	global_load_lds_dwordx4 v[212:213], off
	v_lshl_add_u64 v[212:213], s[72:73], 0, v[134:135]
	s_add_i32 m0, s6, 0xe000
	s_nop 0
	global_load_lds_dwordx4 v[212:213], off
	s_waitcnt vmcnt(8)
	s_waitcnt lgkmcnt(0)
	s_barrier
	s_setprio 1
	s_waitcnt lgkmcnt(0)
	v_mfma_f32_16x16x32_bf16 v[124:127], v[140:143], v[180:183], v[124:127]
	v_mfma_f32_16x16x32_bf16 v[120:123], v[156:159], v[180:183], v[120:123]
	v_mfma_f32_16x16x32_bf16 v[108:111], v[140:143], v[188:191], v[108:111]
	v_mfma_f32_16x16x32_bf16 v[104:107], v[156:159], v[188:191], v[104:107]
	v_mfma_f32_16x16x32_bf16 v[92:95], v[140:143], v[196:199], v[92:95]
	v_mfma_f32_16x16x32_bf16 v[88:91], v[156:159], v[196:199], v[88:91]
	v_mfma_f32_16x16x32_bf16 v[76:79], v[140:143], v[204:207], v[76:79]
	v_mfma_f32_16x16x32_bf16 v[72:75], v[156:159], v[204:207], v[72:75]
	v_mfma_f32_16x16x32_bf16 v[124:127], v[152:155], v[184:187], v[124:127]
	v_mfma_f32_16x16x32_bf16 v[120:123], v[160:163], v[184:187], v[120:123]
	v_mfma_f32_16x16x32_bf16 v[108:111], v[152:155], v[192:195], v[108:111]
	v_mfma_f32_16x16x32_bf16 v[104:107], v[160:163], v[192:195], v[104:107]
	v_mfma_f32_16x16x32_bf16 v[92:95], v[152:155], v[200:203], v[92:95]
	v_mfma_f32_16x16x32_bf16 v[88:91], v[160:163], v[200:203], v[88:91]
	v_mfma_f32_16x16x32_bf16 v[76:79], v[152:155], v[208:211], v[76:79]
	v_mfma_f32_16x16x32_bf16 v[72:75], v[160:163], v[208:211], v[72:75]
	v_mfma_f32_16x16x32_bf16 v[116:119], v[164:167], v[180:183], v[116:119]
	v_mfma_f32_16x16x32_bf16 v[112:115], v[172:175], v[180:183], v[112:115]
	v_mfma_f32_16x16x32_bf16 v[100:103], v[164:167], v[188:191], v[100:103]
	v_mfma_f32_16x16x32_bf16 v[96:99], v[172:175], v[188:191], v[96:99]
	v_mfma_f32_16x16x32_bf16 v[84:87], v[164:167], v[196:199], v[84:87]
	v_mfma_f32_16x16x32_bf16 v[80:83], v[172:175], v[196:199], v[80:83]
	v_mfma_f32_16x16x32_bf16 v[68:71], v[164:167], v[204:207], v[68:71]
	v_mfma_f32_16x16x32_bf16 v[64:67], v[172:175], v[204:207], v[64:67]
	v_mfma_f32_16x16x32_bf16 v[116:119], v[168:171], v[184:187], v[116:119]
	v_mfma_f32_16x16x32_bf16 v[112:115], v[176:179], v[184:187], v[112:115]
	v_mfma_f32_16x16x32_bf16 v[100:103], v[168:171], v[192:195], v[100:103]
	v_mfma_f32_16x16x32_bf16 v[96:99], v[176:179], v[192:195], v[96:99]
	v_mfma_f32_16x16x32_bf16 v[84:87], v[168:171], v[200:203], v[84:87]
	v_mfma_f32_16x16x32_bf16 v[80:83], v[176:179], v[200:203], v[80:83]
	v_mfma_f32_16x16x32_bf16 v[68:71], v[168:171], v[208:211], v[68:71]
	v_mfma_f32_16x16x32_bf16 v[64:67], v[176:179], v[208:211], v[64:67]
	s_barrier
	s_setprio 0
	s_add_i32 s60, s34, s94
	v_lshl_add_u64 v[212:213], s[74:75], 0, v[128:129]
	s_mov_b32 m0, s60
	ds_read_b128 v[180:183], v151 offset:16384
	ds_read_b128 v[184:187], v151 offset:17408
	ds_read_b128 v[188:191], v151 offset:18432
	ds_read_b128 v[192:195], v151 offset:19456
	ds_read_b128 v[196:199], v151 offset:20480
	ds_read_b128 v[200:203], v151 offset:21504
	ds_read_b128 v[204:207], v151 offset:22528
	ds_read_b128 v[208:211], v151 offset:23552
	global_load_lds_dwordx4 v[212:213], off
	s_add_i32 m0, s60, 0x2000
	s_add_u32 s80, s74, 0x200000
	v_lshl_add_u64 v[214:215], s[74:75], 0, v[130:131]
	s_addc_u32 s81, s75, 0
	s_add_i32 s60, s35, s94
	global_load_lds_dwordx4 v[214:215], off
	v_lshl_add_u64 v[216:217], s[80:81], 0, v[128:129]
	s_mov_b32 m0, s60
	v_lshl_add_u64 v[218:219], s[76:77], 0, v[130:131]
	global_load_lds_dwordx4 v[216:217], off
	v_lshl_add_u64 v[216:217], s[80:81], 0, v[130:131]
	s_add_i32 m0, s60, 0x2000
	s_nop 0
	global_load_lds_dwordx4 v[216:217], off
	v_lshl_add_u64 v[216:217], s[76:77], 0, v[128:129]
	s_mov_b32 m0, s6
	s_nop 0
	global_load_lds_dwordx4 v[216:217], off
	s_mov_b32 m0, s7
	s_nop 0
	global_load_lds_dwordx4 v[218:219], off
	s_waitcnt vmcnt(8)
	s_waitcnt lgkmcnt(0)
	s_barrier
	s_setprio 1
	s_waitcnt lgkmcnt(0)
	v_mfma_f32_16x16x32_bf16 v[60:63], v[140:143], v[180:183], v[60:63]
	v_mfma_f32_16x16x32_bf16 v[56:59], v[156:159], v[180:183], v[56:59]
	v_mfma_f32_16x16x32_bf16 v[44:47], v[140:143], v[188:191], v[44:47]
	v_mfma_f32_16x16x32_bf16 v[40:43], v[156:159], v[188:191], v[40:43]
	v_mfma_f32_16x16x32_bf16 v[28:31], v[140:143], v[196:199], v[28:31]
	v_mfma_f32_16x16x32_bf16 v[24:27], v[156:159], v[196:199], v[24:27]
	v_mfma_f32_16x16x32_bf16 v[12:15], v[140:143], v[204:207], v[12:15]
	v_mfma_f32_16x16x32_bf16 v[8:11], v[156:159], v[204:207], v[8:11]
	v_mfma_f32_16x16x32_bf16 v[60:63], v[152:155], v[184:187], v[60:63]
	v_mfma_f32_16x16x32_bf16 v[56:59], v[160:163], v[184:187], v[56:59]
	v_mfma_f32_16x16x32_bf16 v[44:47], v[152:155], v[192:195], v[44:47]
	v_mfma_f32_16x16x32_bf16 v[40:43], v[160:163], v[192:195], v[40:43]
	v_mfma_f32_16x16x32_bf16 v[28:31], v[152:155], v[200:203], v[28:31]
	v_mfma_f32_16x16x32_bf16 v[24:27], v[160:163], v[200:203], v[24:27]
	v_mfma_f32_16x16x32_bf16 v[12:15], v[152:155], v[208:211], v[12:15]
	v_mfma_f32_16x16x32_bf16 v[8:11], v[160:163], v[208:211], v[8:11]
	v_mfma_f32_16x16x32_bf16 v[52:55], v[164:167], v[180:183], v[52:55]
	v_mfma_f32_16x16x32_bf16 v[48:51], v[172:175], v[180:183], v[48:51]
	v_mfma_f32_16x16x32_bf16 v[36:39], v[164:167], v[188:191], v[36:39]
	v_mfma_f32_16x16x32_bf16 v[32:35], v[172:175], v[188:191], v[32:35]
	v_mfma_f32_16x16x32_bf16 v[20:23], v[164:167], v[196:199], v[20:23]
	v_mfma_f32_16x16x32_bf16 v[16:19], v[172:175], v[196:199], v[16:19]
	v_mfma_f32_16x16x32_bf16 v[4:7], v[164:167], v[204:207], v[4:7]
	v_mfma_f32_16x16x32_bf16 v[0:3], v[172:175], v[204:207], v[0:3]
	v_mfma_f32_16x16x32_bf16 v[52:55], v[168:171], v[184:187], v[52:55]
	v_mfma_f32_16x16x32_bf16 v[48:51], v[176:179], v[184:187], v[48:51]
	v_mfma_f32_16x16x32_bf16 v[36:39], v[168:171], v[192:195], v[36:39]
	v_mfma_f32_16x16x32_bf16 v[32:35], v[176:179], v[192:195], v[32:35]
	v_mfma_f32_16x16x32_bf16 v[20:23], v[168:171], v[200:203], v[20:23]
	v_mfma_f32_16x16x32_bf16 v[16:19], v[176:179], v[200:203], v[16:19]
	v_mfma_f32_16x16x32_bf16 v[4:7], v[168:171], v[208:211], v[4:7]
	v_mfma_f32_16x16x32_bf16 v[0:3], v[176:179], v[208:211], v[0:3]
	s_barrier
	s_setprio 0
	s_add_i32 s60, 0, 0x18000
	s_add_i32 s61, 0, 0x1c000
	v_add_u32_e32 v160, s60, v145
	v_add_u32_e32 v176, s61, v145
	ds_read_b128 v[140:143], v160
	ds_read_b128 v[152:155], v160 offset:1024
	ds_read_b128 v[156:159], v160 offset:2048
	ds_read_b128 v[160:163], v160 offset:3072
	ds_read_b128 v[164:167], v176
	ds_read_b128 v[168:171], v176 offset:1024
	ds_read_b128 v[172:175], v176 offset:2048
	ds_read_b128 v[176:179], v176 offset:3072
	s_add_u32 s76, s76, 0x200000
	s_addc_u32 s77, s77, 0
	s_mov_b32 m0, s12
	v_lshl_add_u64 v[220:221], s[76:77], 0, v[128:129]
	ds_read_b128 v[180:183], v151 offset:32768
	ds_read_b128 v[184:187], v151 offset:33792
	ds_read_b128 v[188:191], v151 offset:34816
	ds_read_b128 v[192:195], v151 offset:35840
	ds_read_b128 v[196:199], v151 offset:36864
	ds_read_b128 v[200:203], v151 offset:37888
	ds_read_b128 v[204:207], v151 offset:38912
	ds_read_b128 v[208:211], v151 offset:39936
	global_load_lds_dwordx4 v[220:221], off
	v_lshl_add_u64 v[220:221], s[76:77], 0, v[130:131]
	s_mov_b32 m0, s13
	s_nop 0
	global_load_lds_dwordx4 v[220:221], off
	s_waitcnt vmcnt(8)
	s_waitcnt lgkmcnt(0)
	s_barrier
	s_setprio 1
	s_waitcnt lgkmcnt(0)
	v_mfma_f32_16x16x32_bf16 v[124:127], v[140:143], v[180:183], v[124:127]
	v_mfma_f32_16x16x32_bf16 v[120:123], v[156:159], v[180:183], v[120:123]
	v_mfma_f32_16x16x32_bf16 v[108:111], v[140:143], v[188:191], v[108:111]
	v_mfma_f32_16x16x32_bf16 v[104:107], v[156:159], v[188:191], v[104:107]
	v_mfma_f32_16x16x32_bf16 v[92:95], v[140:143], v[196:199], v[92:95]
	v_mfma_f32_16x16x32_bf16 v[88:91], v[156:159], v[196:199], v[88:91]
	v_mfma_f32_16x16x32_bf16 v[76:79], v[140:143], v[204:207], v[76:79]
	v_mfma_f32_16x16x32_bf16 v[72:75], v[156:159], v[204:207], v[72:75]
	v_mfma_f32_16x16x32_bf16 v[124:127], v[152:155], v[184:187], v[124:127]
	v_mfma_f32_16x16x32_bf16 v[120:123], v[160:163], v[184:187], v[120:123]
	v_mfma_f32_16x16x32_bf16 v[108:111], v[152:155], v[192:195], v[108:111]
	v_mfma_f32_16x16x32_bf16 v[104:107], v[160:163], v[192:195], v[104:107]
	v_mfma_f32_16x16x32_bf16 v[92:95], v[152:155], v[200:203], v[92:95]
	v_mfma_f32_16x16x32_bf16 v[88:91], v[160:163], v[200:203], v[88:91]
	v_mfma_f32_16x16x32_bf16 v[76:79], v[152:155], v[208:211], v[76:79]
	v_mfma_f32_16x16x32_bf16 v[72:75], v[160:163], v[208:211], v[72:75]
	v_mfma_f32_16x16x32_bf16 v[116:119], v[164:167], v[180:183], v[116:119]
	v_mfma_f32_16x16x32_bf16 v[112:115], v[172:175], v[180:183], v[112:115]
	v_mfma_f32_16x16x32_bf16 v[100:103], v[164:167], v[188:191], v[100:103]
	v_mfma_f32_16x16x32_bf16 v[96:99], v[172:175], v[188:191], v[96:99]
	v_mfma_f32_16x16x32_bf16 v[84:87], v[164:167], v[196:199], v[84:87]
	v_mfma_f32_16x16x32_bf16 v[80:83], v[172:175], v[196:199], v[80:83]
	v_mfma_f32_16x16x32_bf16 v[68:71], v[164:167], v[204:207], v[68:71]
	v_mfma_f32_16x16x32_bf16 v[64:67], v[172:175], v[204:207], v[64:67]
	v_mfma_f32_16x16x32_bf16 v[116:119], v[168:171], v[184:187], v[116:119]
	v_mfma_f32_16x16x32_bf16 v[112:115], v[176:179], v[184:187], v[112:115]
	v_mfma_f32_16x16x32_bf16 v[100:103], v[168:171], v[192:195], v[100:103]
	v_mfma_f32_16x16x32_bf16 v[96:99], v[176:179], v[192:195], v[96:99]
	v_mfma_f32_16x16x32_bf16 v[84:87], v[168:171], v[200:203], v[84:87]
	v_mfma_f32_16x16x32_bf16 v[80:83], v[176:179], v[200:203], v[80:83]
	v_mfma_f32_16x16x32_bf16 v[68:71], v[168:171], v[208:211], v[68:71]
	v_mfma_f32_16x16x32_bf16 v[64:67], v[176:179], v[208:211], v[64:67]
	s_barrier
	s_setprio 0
	s_add_i32 s60, s60, s94
	v_lshl_add_u64 v[212:213], v[212:213], 0, s[22:23]
	s_mov_b32 m0, s60
	ds_read_b128 v[180:183], v151 offset:49152
	ds_read_b128 v[184:187], v151 offset:50176
	ds_read_b128 v[188:191], v151 offset:51200
	ds_read_b128 v[192:195], v151 offset:52224
	ds_read_b128 v[196:199], v151 offset:53248
	ds_read_b128 v[200:203], v151 offset:54272
	ds_read_b128 v[204:207], v151 offset:55296
	ds_read_b128 v[208:211], v151 offset:56320
	global_load_lds_dwordx4 v[212:213], off
	s_add_i32 m0, s60, 0x2000
	s_add_u32 s74, s74, 0x200080
	v_lshl_add_u64 v[212:213], v[214:215], 0, s[22:23]
	s_addc_u32 s75, s75, 0
	s_add_i32 s60, s61, s94
	global_load_lds_dwordx4 v[212:213], off
	v_lshl_add_u64 v[212:213], s[74:75], 0, v[128:129]
	s_mov_b32 m0, s60
	s_nop 0
	global_load_lds_dwordx4 v[212:213], off
	v_lshl_add_u64 v[212:213], s[74:75], 0, v[130:131]
	s_add_i32 m0, s60, 0x2000
	s_nop 0
	global_load_lds_dwordx4 v[212:213], off
	v_lshl_add_u64 v[212:213], v[216:217], 0, s[22:23]
	s_mov_b32 m0, s29
	s_nop 0
	global_load_lds_dwordx4 v[212:213], off
	v_lshl_add_u64 v[212:213], v[218:219], 0, s[22:23]
	s_mov_b32 m0, s30
	s_nop 0
	global_load_lds_dwordx4 v[212:213], off
	s_waitcnt vmcnt(8)
	s_waitcnt lgkmcnt(0)
	s_barrier
	s_setprio 1
	s_waitcnt lgkmcnt(0)
	v_mfma_f32_16x16x32_bf16 v[60:63], v[140:143], v[180:183], v[60:63]
	v_mfma_f32_16x16x32_bf16 v[56:59], v[156:159], v[180:183], v[56:59]
	v_mfma_f32_16x16x32_bf16 v[44:47], v[140:143], v[188:191], v[44:47]
	v_mfma_f32_16x16x32_bf16 v[40:43], v[156:159], v[188:191], v[40:43]
	v_mfma_f32_16x16x32_bf16 v[28:31], v[140:143], v[196:199], v[28:31]
	v_mfma_f32_16x16x32_bf16 v[24:27], v[156:159], v[196:199], v[24:27]
	v_mfma_f32_16x16x32_bf16 v[12:15], v[140:143], v[204:207], v[12:15]
	v_mfma_f32_16x16x32_bf16 v[8:11], v[156:159], v[204:207], v[8:11]
	v_mfma_f32_16x16x32_bf16 v[60:63], v[152:155], v[184:187], v[60:63]
	v_mfma_f32_16x16x32_bf16 v[56:59], v[160:163], v[184:187], v[56:59]
	v_mfma_f32_16x16x32_bf16 v[44:47], v[152:155], v[192:195], v[44:47]
	v_mfma_f32_16x16x32_bf16 v[40:43], v[160:163], v[192:195], v[40:43]
	v_mfma_f32_16x16x32_bf16 v[28:31], v[152:155], v[200:203], v[28:31]
	v_mfma_f32_16x16x32_bf16 v[24:27], v[160:163], v[200:203], v[24:27]
	v_mfma_f32_16x16x32_bf16 v[12:15], v[152:155], v[208:211], v[12:15]
	v_mfma_f32_16x16x32_bf16 v[8:11], v[160:163], v[208:211], v[8:11]
	v_mfma_f32_16x16x32_bf16 v[52:55], v[164:167], v[180:183], v[52:55]
	v_mfma_f32_16x16x32_bf16 v[48:51], v[172:175], v[180:183], v[48:51]
	v_mfma_f32_16x16x32_bf16 v[36:39], v[164:167], v[188:191], v[36:39]
	v_mfma_f32_16x16x32_bf16 v[32:35], v[172:175], v[188:191], v[32:35]
	v_mfma_f32_16x16x32_bf16 v[20:23], v[164:167], v[196:199], v[20:23]
	v_mfma_f32_16x16x32_bf16 v[16:19], v[172:175], v[196:199], v[16:19]
	v_mfma_f32_16x16x32_bf16 v[4:7], v[164:167], v[204:207], v[4:7]
	v_mfma_f32_16x16x32_bf16 v[0:3], v[172:175], v[204:207], v[0:3]
	v_mfma_f32_16x16x32_bf16 v[52:55], v[168:171], v[184:187], v[52:55]
	v_mfma_f32_16x16x32_bf16 v[48:51], v[176:179], v[184:187], v[48:51]
	v_mfma_f32_16x16x32_bf16 v[36:39], v[168:171], v[192:195], v[36:39]
	v_mfma_f32_16x16x32_bf16 v[32:35], v[176:179], v[192:195], v[32:35]
	v_mfma_f32_16x16x32_bf16 v[20:23], v[168:171], v[200:203], v[20:23]
	v_mfma_f32_16x16x32_bf16 v[16:19], v[176:179], v[200:203], v[16:19]
	v_mfma_f32_16x16x32_bf16 v[4:7], v[168:171], v[208:211], v[4:7]
	v_mfma_f32_16x16x32_bf16 v[0:3], v[176:179], v[208:211], v[0:3]
	s_barrier
	s_setprio 0
	s_add_i32 s79, s79, 2
	s_add_u32 s72, s72, 0x100
	s_addc_u32 s73, s73, 0
	s_add_u32 s71, s71, 0x100
	s_addc_u32 s78, s78, 0
	s_cmpk_gt_u32 s79, 0x7d
	s_cbranch_scc0 .LBB0_1897
	s_and_b64 vcc, exec, s[58:59]
	s_cbranch_vccz .LBB0_1900
	s_barrier

.LBB0_2128:
	ds_read_b128 v[148:151], v179
	ds_read_b128 v[152:155], v179 offset:1024
	ds_read_b128 v[156:159], v179 offset:2048
	ds_read_b128 v[160:163], v179 offset:3072
	ds_read_b128 v[164:167], v180
	ds_read_b128 v[168:171], v180 offset:1024
	ds_read_b128 v[184:187], v180 offset:2048
	ds_read_b128 v[188:191], v180 offset:3072
	s_add_u32 s60, s84, 0xfff80080
	s_addc_u32 s61, s85, -1
	s_cmp_eq_u32 s95, 28
	s_cselect_b32 s89, s23, s61
	s_cselect_b32 s88, s79, s60
	s_cselect_b32 s87, s77, s97
	s_cselect_b32 s86, vcc_lo, vcc_hi
	v_lshl_add_u64 v[172:173], s[84:85], 0, v[140:141]
	s_add_i32 m0, s6, 0xc000
	ds_read_b128 v[192:195], v181
	ds_read_b128 v[196:199], v181 offset:1024
	ds_read_b128 v[200:203], v181 offset:2048
	ds_read_b128 v[204:207], v181 offset:3072
	ds_read_b128 v[208:211], v181 offset:4096
	ds_read_b128 v[212:215], v181 offset:5120
	ds_read_b128 v[216:219], v181 offset:6144
	ds_read_b128 v[220:223], v181 offset:7168
	global_load_lds_dwordx4 v[172:173], off
	v_lshl_add_u64 v[172:173], s[84:85], 0, v[142:143]
	s_add_i32 m0, s6, 0xe000
	s_nop 0
	global_load_lds_dwordx4 v[172:173], off
	s_waitcnt vmcnt(8)
	s_waitcnt lgkmcnt(0)
	s_barrier
	s_setprio 1
	s_waitcnt lgkmcnt(0)
	v_mfma_f32_16x16x32_bf16 v[124:127], v[148:151], v[192:195], v[124:127]
	v_mfma_f32_16x16x32_bf16 v[120:123], v[156:159], v[192:195], v[120:123]
	v_mfma_f32_16x16x32_bf16 v[108:111], v[148:151], v[200:203], v[108:111]
	v_mfma_f32_16x16x32_bf16 v[104:107], v[156:159], v[200:203], v[104:107]
	v_mfma_f32_16x16x32_bf16 v[92:95], v[148:151], v[208:211], v[92:95]
	v_mfma_f32_16x16x32_bf16 v[88:91], v[156:159], v[208:211], v[88:91]
	v_mfma_f32_16x16x32_bf16 v[76:79], v[148:151], v[216:219], v[76:79]
	v_mfma_f32_16x16x32_bf16 v[72:75], v[156:159], v[216:219], v[72:75]
	v_mfma_f32_16x16x32_bf16 v[124:127], v[152:155], v[196:199], v[124:127]
	v_mfma_f32_16x16x32_bf16 v[120:123], v[160:163], v[196:199], v[120:123]
	v_mfma_f32_16x16x32_bf16 v[108:111], v[152:155], v[204:207], v[108:111]
	v_mfma_f32_16x16x32_bf16 v[104:107], v[160:163], v[204:207], v[104:107]
	v_mfma_f32_16x16x32_bf16 v[92:95], v[152:155], v[212:215], v[92:95]
	v_mfma_f32_16x16x32_bf16 v[88:91], v[160:163], v[212:215], v[88:91]
	v_mfma_f32_16x16x32_bf16 v[76:79], v[152:155], v[220:223], v[76:79]
	v_mfma_f32_16x16x32_bf16 v[72:75], v[160:163], v[220:223], v[72:75]
	v_mfma_f32_16x16x32_bf16 v[116:119], v[164:167], v[192:195], v[116:119]
	v_mfma_f32_16x16x32_bf16 v[112:115], v[184:187], v[192:195], v[112:115]
	v_mfma_f32_16x16x32_bf16 v[100:103], v[164:167], v[200:203], v[100:103]
	v_mfma_f32_16x16x32_bf16 v[96:99], v[184:187], v[200:203], v[96:99]
	v_mfma_f32_16x16x32_bf16 v[84:87], v[164:167], v[208:211], v[84:87]
	v_mfma_f32_16x16x32_bf16 v[80:83], v[184:187], v[208:211], v[80:83]
	v_mfma_f32_16x16x32_bf16 v[68:71], v[164:167], v[216:219], v[68:71]
	v_mfma_f32_16x16x32_bf16 v[64:67], v[184:187], v[216:219], v[64:67]
	v_mfma_f32_16x16x32_bf16 v[116:119], v[168:171], v[196:199], v[116:119]
	v_mfma_f32_16x16x32_bf16 v[112:115], v[188:191], v[196:199], v[112:115]
	v_mfma_f32_16x16x32_bf16 v[100:103], v[168:171], v[204:207], v[100:103]
	v_mfma_f32_16x16x32_bf16 v[96:99], v[188:191], v[204:207], v[96:99]
	v_mfma_f32_16x16x32_bf16 v[84:87], v[168:171], v[212:215], v[84:87]
	v_mfma_f32_16x16x32_bf16 v[80:83], v[188:191], v[212:215], v[80:83]
	v_mfma_f32_16x16x32_bf16 v[68:71], v[168:171], v[220:223], v[68:71]
	v_mfma_f32_16x16x32_bf16 v[64:67], v[188:191], v[220:223], v[64:67]
	s_barrier
	s_setprio 0
	s_add_i32 s60, s12, s94
	v_lshl_add_u64 v[172:173], s[86:87], 0, v[130:131]
	s_mov_b32 m0, s60
	ds_read_b128 v[192:195], v181 offset:16384
	ds_read_b128 v[196:199], v181 offset:17408
	ds_read_b128 v[200:203], v181 offset:18432
	ds_read_b128 v[204:207], v181 offset:19456
	ds_read_b128 v[208:211], v181 offset:20480
	ds_read_b128 v[212:215], v181 offset:21504
	ds_read_b128 v[216:219], v181 offset:22528
	ds_read_b128 v[220:223], v181 offset:23552
	global_load_lds_dwordx4 v[172:173], off
	s_add_i32 m0, s60, 0x2000
	s_add_u32 s60, s86, 0x80000
	v_lshl_add_u64 v[224:225], s[86:87], 0, v[134:135]
	s_addc_u32 s61, s87, 0
	s_add_i32 s96, s13, s94
	global_load_lds_dwordx4 v[224:225], off
	v_lshl_add_u64 v[226:227], s[60:61], 0, v[130:131]
	s_mov_b32 m0, s96
	v_lshl_add_u64 v[228:229], s[88:89], 0, v[132:133]
	global_load_lds_dwordx4 v[226:227], off
	v_lshl_add_u64 v[226:227], s[60:61], 0, v[134:135]
	s_add_i32 m0, s96, 0x2000
	s_nop 0
	global_load_lds_dwordx4 v[226:227], off
	v_lshl_add_u64 v[226:227], s[88:89], 0, v[128:129]
	s_mov_b32 m0, s6
	s_nop 0
	global_load_lds_dwordx4 v[226:227], off
	s_mov_b32 m0, s7
	s_nop 0
	global_load_lds_dwordx4 v[228:229], off
	s_waitcnt vmcnt(8)
	s_waitcnt lgkmcnt(0)
	s_barrier
	s_setprio 1
	s_waitcnt lgkmcnt(0)
	v_mfma_f32_16x16x32_bf16 v[60:63], v[148:151], v[192:195], v[60:63]
	v_mfma_f32_16x16x32_bf16 v[56:59], v[156:159], v[192:195], v[56:59]
	v_mfma_f32_16x16x32_bf16 v[44:47], v[148:151], v[200:203], v[44:47]
	v_mfma_f32_16x16x32_bf16 v[40:43], v[156:159], v[200:203], v[40:43]
	v_mfma_f32_16x16x32_bf16 v[28:31], v[148:151], v[208:211], v[28:31]
	v_mfma_f32_16x16x32_bf16 v[24:27], v[156:159], v[208:211], v[24:27]
	v_mfma_f32_16x16x32_bf16 v[12:15], v[148:151], v[216:219], v[12:15]
	v_mfma_f32_16x16x32_bf16 v[8:11], v[156:159], v[216:219], v[8:11]
	v_mfma_f32_16x16x32_bf16 v[60:63], v[152:155], v[196:199], v[60:63]
	v_mfma_f32_16x16x32_bf16 v[56:59], v[160:163], v[196:199], v[56:59]
	v_mfma_f32_16x16x32_bf16 v[44:47], v[152:155], v[204:207], v[44:47]
	v_mfma_f32_16x16x32_bf16 v[40:43], v[160:163], v[204:207], v[40:43]
	v_mfma_f32_16x16x32_bf16 v[28:31], v[152:155], v[212:215], v[28:31]
	v_mfma_f32_16x16x32_bf16 v[24:27], v[160:163], v[212:215], v[24:27]
	v_mfma_f32_16x16x32_bf16 v[12:15], v[152:155], v[220:223], v[12:15]
	v_mfma_f32_16x16x32_bf16 v[8:11], v[160:163], v[220:223], v[8:11]
	v_mfma_f32_16x16x32_bf16 v[52:55], v[164:167], v[192:195], v[52:55]
	v_mfma_f32_16x16x32_bf16 v[48:51], v[184:187], v[192:195], v[48:51]
	v_mfma_f32_16x16x32_bf16 v[36:39], v[164:167], v[200:203], v[36:39]
	v_mfma_f32_16x16x32_bf16 v[32:35], v[184:187], v[200:203], v[32:35]
	v_mfma_f32_16x16x32_bf16 v[20:23], v[164:167], v[208:211], v[20:23]
	v_mfma_f32_16x16x32_bf16 v[16:19], v[184:187], v[208:211], v[16:19]
	v_mfma_f32_16x16x32_bf16 v[4:7], v[164:167], v[216:219], v[4:7]
	v_mfma_f32_16x16x32_bf16 v[0:3], v[184:187], v[216:219], v[0:3]
	v_mfma_f32_16x16x32_bf16 v[52:55], v[168:171], v[196:199], v[52:55]
	v_mfma_f32_16x16x32_bf16 v[48:51], v[188:191], v[196:199], v[48:51]
	v_mfma_f32_16x16x32_bf16 v[36:39], v[168:171], v[204:207], v[36:39]
	v_mfma_f32_16x16x32_bf16 v[32:35], v[188:191], v[204:207], v[32:35]
	v_mfma_f32_16x16x32_bf16 v[20:23], v[168:171], v[212:215], v[20:23]
	v_mfma_f32_16x16x32_bf16 v[16:19], v[188:191], v[212:215], v[16:19]
	v_mfma_f32_16x16x32_bf16 v[4:7], v[168:171], v[220:223], v[4:7]
	v_mfma_f32_16x16x32_bf16 v[0:3], v[188:191], v[220:223], v[0:3]
	s_barrier
	s_setprio 0
	s_add_i32 s96, 0, 0x18000
	v_add_u32_e32 v136, s96, v175
	s_add_i32 s8, 0, 0x1c000
	ds_read_b128 v[148:151], v136
	ds_read_b128 v[152:155], v136 offset:1024
	ds_read_b128 v[156:159], v136 offset:2048
	ds_read_b128 v[160:163], v136 offset:3072
	v_add_u32_e32 v136, s8, v175
	ds_read_b128 v[164:167], v136
	ds_read_b128 v[168:171], v136 offset:1024
	ds_read_b128 v[184:187], v136 offset:2048
	ds_read_b128 v[188:191], v136 offset:3072
	s_add_u32 s60, s88, 0x80000
	s_addc_u32 s61, s89, 0
	s_mov_b32 m0, s34
	v_lshl_add_u64 v[230:231], s[60:61], 0, v[128:129]
	ds_read_b128 v[192:195], v181 offset:32768
	ds_read_b128 v[196:199], v181 offset:33792
	ds_read_b128 v[200:203], v181 offset:34816
	ds_read_b128 v[204:207], v181 offset:35840
	ds_read_b128 v[208:211], v181 offset:36864
	ds_read_b128 v[212:215], v181 offset:37888
	ds_read_b128 v[216:219], v181 offset:38912
	ds_read_b128 v[220:223], v181 offset:39936
	global_load_lds_dwordx4 v[230:231], off
	v_lshl_add_u64 v[230:231], s[60:61], 0, v[132:133]
	s_mov_b32 m0, s46
	s_nop 0
	global_load_lds_dwordx4 v[230:231], off
	s_waitcnt vmcnt(8)
	s_waitcnt lgkmcnt(0)
	s_barrier
	s_setprio 1
	s_waitcnt lgkmcnt(0)
	v_mfma_f32_16x16x32_bf16 v[124:127], v[148:151], v[192:195], v[124:127]
	v_mfma_f32_16x16x32_bf16 v[120:123], v[156:159], v[192:195], v[120:123]
	v_mfma_f32_16x16x32_bf16 v[108:111], v[148:151], v[200:203], v[108:111]
	v_mfma_f32_16x16x32_bf16 v[104:107], v[156:159], v[200:203], v[104:107]
	v_mfma_f32_16x16x32_bf16 v[92:95], v[148:151], v[208:211], v[92:95]
	v_mfma_f32_16x16x32_bf16 v[88:91], v[156:159], v[208:211], v[88:91]
	v_mfma_f32_16x16x32_bf16 v[76:79], v[148:151], v[216:219], v[76:79]
	v_mfma_f32_16x16x32_bf16 v[72:75], v[156:159], v[216:219], v[72:75]
	v_mfma_f32_16x16x32_bf16 v[124:127], v[152:155], v[196:199], v[124:127]
	v_mfma_f32_16x16x32_bf16 v[120:123], v[160:163], v[196:199], v[120:123]
	v_mfma_f32_16x16x32_bf16 v[108:111], v[152:155], v[204:207], v[108:111]
	v_mfma_f32_16x16x32_bf16 v[104:107], v[160:163], v[204:207], v[104:107]
	v_mfma_f32_16x16x32_bf16 v[92:95], v[152:155], v[212:215], v[92:95]
	v_mfma_f32_16x16x32_bf16 v[88:91], v[160:163], v[212:215], v[88:91]
	v_mfma_f32_16x16x32_bf16 v[76:79], v[152:155], v[220:223], v[76:79]
	v_mfma_f32_16x16x32_bf16 v[72:75], v[160:163], v[220:223], v[72:75]
	v_mfma_f32_16x16x32_bf16 v[116:119], v[164:167], v[192:195], v[116:119]
	v_mfma_f32_16x16x32_bf16 v[112:115], v[184:187], v[192:195], v[112:115]
	v_mfma_f32_16x16x32_bf16 v[100:103], v[164:167], v[200:203], v[100:103]
	v_mfma_f32_16x16x32_bf16 v[96:99], v[184:187], v[200:203], v[96:99]
	v_mfma_f32_16x16x32_bf16 v[84:87], v[164:167], v[208:211], v[84:87]
	v_mfma_f32_16x16x32_bf16 v[80:83], v[184:187], v[208:211], v[80:83]
	v_mfma_f32_16x16x32_bf16 v[68:71], v[164:167], v[216:219], v[68:71]
	v_mfma_f32_16x16x32_bf16 v[64:67], v[184:187], v[216:219], v[64:67]
	v_mfma_f32_16x16x32_bf16 v[116:119], v[168:171], v[196:199], v[116:119]
	v_mfma_f32_16x16x32_bf16 v[112:115], v[188:191], v[196:199], v[112:115]
	v_mfma_f32_16x16x32_bf16 v[100:103], v[168:171], v[204:207], v[100:103]
	v_mfma_f32_16x16x32_bf16 v[96:99], v[188:191], v[204:207], v[96:99]
	v_mfma_f32_16x16x32_bf16 v[84:87], v[168:171], v[212:215], v[84:87]
	v_mfma_f32_16x16x32_bf16 v[80:83], v[188:191], v[212:215], v[80:83]
	v_mfma_f32_16x16x32_bf16 v[68:71], v[168:171], v[220:223], v[68:71]
	v_mfma_f32_16x16x32_bf16 v[64:67], v[188:191], v[220:223], v[64:67]
	s_barrier
	s_setprio 0
	s_add_i32 s9, s96, s94
	v_lshl_add_u64 v[172:173], v[172:173], 0, s[74:75]
	s_mov_b32 m0, s9
	ds_read_b128 v[192:195], v181 offset:49152
	ds_read_b128 v[196:199], v181 offset:50176
	ds_read_b128 v[200:203], v181 offset:51200
	ds_read_b128 v[204:207], v181 offset:52224
	ds_read_b128 v[208:211], v181 offset:53248
	ds_read_b128 v[212:215], v181 offset:54272
	ds_read_b128 v[216:219], v181 offset:55296
	ds_read_b128 v[220:223], v181 offset:56320
	global_load_lds_dwordx4 v[172:173], off
	s_add_i32 m0, s9, 0x2000
	s_add_u32 s60, s86, 0x80080
	v_lshl_add_u64 v[172:173], v[224:225], 0, s[74:75]
	s_addc_u32 s61, s87, 0
	s_add_i32 s8, s8, s94
	global_load_lds_dwordx4 v[172:173], off
	v_lshl_add_u64 v[172:173], s[60:61], 0, v[130:131]
	s_mov_b32 m0, s8
	s_nop 0
	global_load_lds_dwordx4 v[172:173], off
	v_lshl_add_u64 v[172:173], s[60:61], 0, v[134:135]
	s_add_i32 m0, s8, 0x2000
	s_nop 0
	global_load_lds_dwordx4 v[172:173], off
	v_lshl_add_u64 v[172:173], v[226:227], 0, s[74:75]
	s_mov_b32 m0, s56
	s_nop 0
	global_load_lds_dwordx4 v[172:173], off
	v_lshl_add_u64 v[172:173], v[228:229], 0, s[74:75]
	s_mov_b32 m0, s57
	s_nop 0
	global_load_lds_dwordx4 v[172:173], off
	s_waitcnt vmcnt(8)
	s_waitcnt lgkmcnt(0)
	s_barrier
	s_setprio 1
	s_waitcnt lgkmcnt(0)
	v_mfma_f32_16x16x32_bf16 v[60:63], v[148:151], v[192:195], v[60:63]
	v_mfma_f32_16x16x32_bf16 v[56:59], v[156:159], v[192:195], v[56:59]
	v_mfma_f32_16x16x32_bf16 v[44:47], v[148:151], v[200:203], v[44:47]
	v_mfma_f32_16x16x32_bf16 v[40:43], v[156:159], v[200:203], v[40:43]
	v_mfma_f32_16x16x32_bf16 v[28:31], v[148:151], v[208:211], v[28:31]
	v_mfma_f32_16x16x32_bf16 v[24:27], v[156:159], v[208:211], v[24:27]
	v_mfma_f32_16x16x32_bf16 v[12:15], v[148:151], v[216:219], v[12:15]
	v_mfma_f32_16x16x32_bf16 v[8:11], v[156:159], v[216:219], v[8:11]
	v_mfma_f32_16x16x32_bf16 v[60:63], v[152:155], v[196:199], v[60:63]
	v_mfma_f32_16x16x32_bf16 v[56:59], v[160:163], v[196:199], v[56:59]
	v_mfma_f32_16x16x32_bf16 v[44:47], v[152:155], v[204:207], v[44:47]
	v_mfma_f32_16x16x32_bf16 v[40:43], v[160:163], v[204:207], v[40:43]
	v_mfma_f32_16x16x32_bf16 v[28:31], v[152:155], v[212:215], v[28:31]
	v_mfma_f32_16x16x32_bf16 v[24:27], v[160:163], v[212:215], v[24:27]
	v_mfma_f32_16x16x32_bf16 v[12:15], v[152:155], v[220:223], v[12:15]
	v_mfma_f32_16x16x32_bf16 v[8:11], v[160:163], v[220:223], v[8:11]
	v_mfma_f32_16x16x32_bf16 v[52:55], v[164:167], v[192:195], v[52:55]
	v_mfma_f32_16x16x32_bf16 v[48:51], v[184:187], v[192:195], v[48:51]
	v_mfma_f32_16x16x32_bf16 v[36:39], v[164:167], v[200:203], v[36:39]
	v_mfma_f32_16x16x32_bf16 v[32:35], v[184:187], v[200:203], v[32:35]
	v_mfma_f32_16x16x32_bf16 v[20:23], v[164:167], v[208:211], v[20:23]
	v_mfma_f32_16x16x32_bf16 v[16:19], v[184:187], v[208:211], v[16:19]
	v_mfma_f32_16x16x32_bf16 v[4:7], v[164:167], v[216:219], v[4:7]
	v_mfma_f32_16x16x32_bf16 v[0:3], v[184:187], v[216:219], v[0:3]
	v_mfma_f32_16x16x32_bf16 v[52:55], v[168:171], v[196:199], v[52:55]
	v_mfma_f32_16x16x32_bf16 v[48:51], v[188:191], v[196:199], v[48:51]
	v_mfma_f32_16x16x32_bf16 v[36:39], v[168:171], v[204:207], v[36:39]
	v_mfma_f32_16x16x32_bf16 v[32:35], v[188:191], v[204:207], v[32:35]
	v_mfma_f32_16x16x32_bf16 v[20:23], v[168:171], v[212:215], v[20:23]
	v_mfma_f32_16x16x32_bf16 v[16:19], v[188:191], v[212:215], v[16:19]
	v_mfma_f32_16x16x32_bf16 v[4:7], v[168:171], v[220:223], v[4:7]
	v_mfma_f32_16x16x32_bf16 v[0:3], v[188:191], v[220:223], v[0:3]
	s_barrier
	s_setprio 0
	s_add_i32 s95, s95, 2
	s_add_u32 s84, s84, 0x100
	s_addc_u32 s85, s85, 0
	s_add_u32 vcc_hi, vcc_hi, 0x100
	s_addc_u32 s97, s97, 0
	s_cmp_gt_u32 s95, 29
	s_cbranch_scc0 .LBB0_2128
	s_and_b64 vcc, exec, s[58:59]
	s_cbranch_vccz .LBB0_2131
	s_barrier

.LBB0_2459:
	ds_read_b128 v[148:151], v163
	ds_read_b128 v[152:155], v163 offset:1024
	ds_read_b128 v[168:171], v163 offset:2048
	ds_read_b128 v[172:175], v163 offset:3072
	ds_read_b128 v[176:179], v164
	ds_read_b128 v[180:183], v164 offset:1024
	ds_read_b128 v[184:187], v164 offset:2048
	ds_read_b128 v[188:191], v164 offset:3072
	s_add_u32 s16, s70, 0x100
	s_addc_u32 s17, s71, 0
	s_cmp_eq_u32 s86, 8
	s_cselect_b32 s75, s23, s17
	s_cselect_b32 s74, s22, s16
	s_cselect_b32 s73, s49, s85
	s_cselect_b32 s72, s48, s84
	v_lshl_add_u64 v[156:157], s[70:71], 0, v[140:141]
	s_add_i32 m0, s12, 0xc000
	ds_read_b128 v[192:195], v165
	ds_read_b128 v[196:199], v165 offset:1024
	ds_read_b128 v[200:203], v165 offset:2048
	ds_read_b128 v[204:207], v165 offset:3072
	ds_read_b128 v[208:211], v165 offset:4096
	ds_read_b128 v[212:215], v165 offset:5120
	ds_read_b128 v[216:219], v165 offset:6144
	ds_read_b128 v[220:223], v165 offset:7168
	global_load_lds_dwordx4 v[156:157], off
	v_lshl_add_u64 v[156:157], s[70:71], 0, v[142:143]
	s_add_i32 m0, s12, 0xe000
	s_nop 0
	global_load_lds_dwordx4 v[156:157], off
	s_waitcnt vmcnt(8)
	s_waitcnt lgkmcnt(0)
	s_barrier
	s_setprio 1
	s_waitcnt lgkmcnt(0)
	v_mfma_f32_16x16x32_bf16 v[124:127], v[148:151], v[192:195], v[124:127]
	v_mfma_f32_16x16x32_bf16 v[120:123], v[168:171], v[192:195], v[120:123]
	v_mfma_f32_16x16x32_bf16 v[108:111], v[148:151], v[200:203], v[108:111]
	v_mfma_f32_16x16x32_bf16 v[104:107], v[168:171], v[200:203], v[104:107]
	v_mfma_f32_16x16x32_bf16 v[92:95], v[148:151], v[208:211], v[92:95]
	v_mfma_f32_16x16x32_bf16 v[88:91], v[168:171], v[208:211], v[88:91]
	v_mfma_f32_16x16x32_bf16 v[76:79], v[148:151], v[216:219], v[76:79]
	v_mfma_f32_16x16x32_bf16 v[72:75], v[168:171], v[216:219], v[72:75]
	v_mfma_f32_16x16x32_bf16 v[124:127], v[152:155], v[196:199], v[124:127]
	v_mfma_f32_16x16x32_bf16 v[120:123], v[172:175], v[196:199], v[120:123]
	v_mfma_f32_16x16x32_bf16 v[108:111], v[152:155], v[204:207], v[108:111]
	v_mfma_f32_16x16x32_bf16 v[104:107], v[172:175], v[204:207], v[104:107]
	v_mfma_f32_16x16x32_bf16 v[92:95], v[152:155], v[212:215], v[92:95]
	v_mfma_f32_16x16x32_bf16 v[88:91], v[172:175], v[212:215], v[88:91]
	v_mfma_f32_16x16x32_bf16 v[76:79], v[152:155], v[220:223], v[76:79]
	v_mfma_f32_16x16x32_bf16 v[72:75], v[172:175], v[220:223], v[72:75]
	v_mfma_f32_16x16x32_bf16 v[116:119], v[176:179], v[192:195], v[116:119]
	v_mfma_f32_16x16x32_bf16 v[112:115], v[184:187], v[192:195], v[112:115]
	v_mfma_f32_16x16x32_bf16 v[100:103], v[176:179], v[200:203], v[100:103]
	v_mfma_f32_16x16x32_bf16 v[96:99], v[184:187], v[200:203], v[96:99]
	v_mfma_f32_16x16x32_bf16 v[84:87], v[176:179], v[208:211], v[84:87]
	v_mfma_f32_16x16x32_bf16 v[80:83], v[184:187], v[208:211], v[80:83]
	v_mfma_f32_16x16x32_bf16 v[68:71], v[176:179], v[216:219], v[68:71]
	v_mfma_f32_16x16x32_bf16 v[64:67], v[184:187], v[216:219], v[64:67]
	v_mfma_f32_16x16x32_bf16 v[116:119], v[180:183], v[196:199], v[116:119]
	v_mfma_f32_16x16x32_bf16 v[112:115], v[188:191], v[196:199], v[112:115]
	v_mfma_f32_16x16x32_bf16 v[100:103], v[180:183], v[204:207], v[100:103]
	v_mfma_f32_16x16x32_bf16 v[96:99], v[188:191], v[204:207], v[96:99]
	v_mfma_f32_16x16x32_bf16 v[84:87], v[180:183], v[212:215], v[84:87]
	v_mfma_f32_16x16x32_bf16 v[80:83], v[188:191], v[212:215], v[80:83]
	v_mfma_f32_16x16x32_bf16 v[68:71], v[180:183], v[220:223], v[68:71]
	v_mfma_f32_16x16x32_bf16 v[64:67], v[188:191], v[220:223], v[64:67]
	s_barrier
	s_setprio 0
	s_add_i32 s8, s76, s94
	v_lshl_add_u64 v[156:157], s[72:73], 0, v[130:131]
	s_mov_b32 m0, s8
	ds_read_b128 v[192:195], v165 offset:16384
	ds_read_b128 v[196:199], v165 offset:17408
	ds_read_b128 v[200:203], v165 offset:18432
	ds_read_b128 v[204:207], v165 offset:19456
	ds_read_b128 v[208:211], v165 offset:20480
	ds_read_b128 v[212:215], v165 offset:21504
	ds_read_b128 v[216:219], v165 offset:22528
	ds_read_b128 v[220:223], v165 offset:23552
	global_load_lds_dwordx4 v[156:157], off
	s_add_i32 m0, s8, 0x2000
	s_add_u32 s60, s72, 0x30000
	v_lshl_add_u64 v[224:225], s[72:73], 0, v[134:135]
	s_addc_u32 s61, s73, 0
	s_add_i32 s8, s77, s94
	global_load_lds_dwordx4 v[224:225], off
	v_lshl_add_u64 v[226:227], s[60:61], 0, v[130:131]
	s_mov_b32 m0, s8
	v_lshl_add_u64 v[228:229], s[74:75], 0, v[132:133]
	global_load_lds_dwordx4 v[226:227], off
	v_lshl_add_u64 v[226:227], s[60:61], 0, v[134:135]
	s_add_i32 m0, s8, 0x2000
	s_nop 0
	global_load_lds_dwordx4 v[226:227], off
	v_lshl_add_u64 v[226:227], s[74:75], 0, v[128:129]
	s_mov_b32 m0, s12
	s_nop 0
	global_load_lds_dwordx4 v[226:227], off
	s_mov_b32 m0, s13
	s_nop 0
	global_load_lds_dwordx4 v[228:229], off
	s_waitcnt vmcnt(8)
	s_waitcnt lgkmcnt(0)
	s_barrier
	s_setprio 1
	s_waitcnt lgkmcnt(0)
	v_mfma_f32_16x16x32_bf16 v[60:63], v[148:151], v[192:195], v[60:63]
	v_mfma_f32_16x16x32_bf16 v[56:59], v[168:171], v[192:195], v[56:59]
	v_mfma_f32_16x16x32_bf16 v[44:47], v[148:151], v[200:203], v[44:47]
	v_mfma_f32_16x16x32_bf16 v[40:43], v[168:171], v[200:203], v[40:43]
	v_mfma_f32_16x16x32_bf16 v[28:31], v[148:151], v[208:211], v[28:31]
	v_mfma_f32_16x16x32_bf16 v[24:27], v[168:171], v[208:211], v[24:27]
	v_mfma_f32_16x16x32_bf16 v[12:15], v[148:151], v[216:219], v[12:15]
	v_mfma_f32_16x16x32_bf16 v[8:11], v[168:171], v[216:219], v[8:11]
	v_mfma_f32_16x16x32_bf16 v[60:63], v[152:155], v[196:199], v[60:63]
	v_mfma_f32_16x16x32_bf16 v[56:59], v[172:175], v[196:199], v[56:59]
	v_mfma_f32_16x16x32_bf16 v[44:47], v[152:155], v[204:207], v[44:47]
	v_mfma_f32_16x16x32_bf16 v[40:43], v[172:175], v[204:207], v[40:43]
	v_mfma_f32_16x16x32_bf16 v[28:31], v[152:155], v[212:215], v[28:31]
	v_mfma_f32_16x16x32_bf16 v[24:27], v[172:175], v[212:215], v[24:27]
	v_mfma_f32_16x16x32_bf16 v[12:15], v[152:155], v[220:223], v[12:15]
	v_mfma_f32_16x16x32_bf16 v[8:11], v[172:175], v[220:223], v[8:11]
	v_mfma_f32_16x16x32_bf16 v[52:55], v[176:179], v[192:195], v[52:55]
	v_mfma_f32_16x16x32_bf16 v[48:51], v[184:187], v[192:195], v[48:51]
	v_mfma_f32_16x16x32_bf16 v[36:39], v[176:179], v[200:203], v[36:39]
	v_mfma_f32_16x16x32_bf16 v[32:35], v[184:187], v[200:203], v[32:35]
	v_mfma_f32_16x16x32_bf16 v[20:23], v[176:179], v[208:211], v[20:23]
	v_mfma_f32_16x16x32_bf16 v[16:19], v[184:187], v[208:211], v[16:19]
	v_mfma_f32_16x16x32_bf16 v[4:7], v[176:179], v[216:219], v[4:7]
	v_mfma_f32_16x16x32_bf16 v[0:3], v[184:187], v[216:219], v[0:3]
	v_mfma_f32_16x16x32_bf16 v[52:55], v[180:183], v[196:199], v[52:55]
	v_mfma_f32_16x16x32_bf16 v[48:51], v[188:191], v[196:199], v[48:51]
	v_mfma_f32_16x16x32_bf16 v[36:39], v[180:183], v[204:207], v[36:39]
	v_mfma_f32_16x16x32_bf16 v[32:35], v[188:191], v[204:207], v[32:35]
	v_mfma_f32_16x16x32_bf16 v[20:23], v[180:183], v[212:215], v[20:23]
	v_mfma_f32_16x16x32_bf16 v[16:19], v[188:191], v[212:215], v[16:19]
	v_mfma_f32_16x16x32_bf16 v[4:7], v[180:183], v[220:223], v[4:7]
	v_mfma_f32_16x16x32_bf16 v[0:3], v[188:191], v[220:223], v[0:3]
	s_barrier
	s_setprio 0
	s_add_i32 s8, 0, 0x18000
	v_add_u32_e32 v136, s8, v159
	s_add_i32 s9, 0, 0x1c000
	ds_read_b128 v[148:151], v136
	ds_read_b128 v[152:155], v136 offset:1024
	ds_read_b128 v[168:171], v136 offset:2048
	ds_read_b128 v[172:175], v136 offset:3072
	v_add_u32_e32 v136, s9, v159
	ds_read_b128 v[176:179], v136
	ds_read_b128 v[180:183], v136 offset:1024
	ds_read_b128 v[184:187], v136 offset:2048
	ds_read_b128 v[188:191], v136 offset:3072
	s_add_u32 s60, s74, 0x60000
	s_addc_u32 s61, s75, 0
	s_mov_b32 m0, s29
	v_lshl_add_u64 v[230:231], s[60:61], 0, v[128:129]
	ds_read_b128 v[192:195], v165 offset:32768
	ds_read_b128 v[196:199], v165 offset:33792
	ds_read_b128 v[200:203], v165 offset:34816
	ds_read_b128 v[204:207], v165 offset:35840
	ds_read_b128 v[208:211], v165 offset:36864
	ds_read_b128 v[212:215], v165 offset:37888
	ds_read_b128 v[216:219], v165 offset:38912
	ds_read_b128 v[220:223], v165 offset:39936
	global_load_lds_dwordx4 v[230:231], off
	v_lshl_add_u64 v[230:231], s[60:61], 0, v[132:133]
	s_mov_b32 m0, s30
	s_nop 0
	global_load_lds_dwordx4 v[230:231], off
	s_waitcnt vmcnt(8)
	s_waitcnt lgkmcnt(0)
	s_barrier
	s_setprio 1
	s_waitcnt lgkmcnt(0)
	v_mfma_f32_16x16x32_bf16 v[124:127], v[148:151], v[192:195], v[124:127]
	v_mfma_f32_16x16x32_bf16 v[120:123], v[168:171], v[192:195], v[120:123]
	v_mfma_f32_16x16x32_bf16 v[108:111], v[148:151], v[200:203], v[108:111]
	v_mfma_f32_16x16x32_bf16 v[104:107], v[168:171], v[200:203], v[104:107]
	v_mfma_f32_16x16x32_bf16 v[92:95], v[148:151], v[208:211], v[92:95]
	v_mfma_f32_16x16x32_bf16 v[88:91], v[168:171], v[208:211], v[88:91]
	v_mfma_f32_16x16x32_bf16 v[76:79], v[148:151], v[216:219], v[76:79]
	v_mfma_f32_16x16x32_bf16 v[72:75], v[168:171], v[216:219], v[72:75]
	v_mfma_f32_16x16x32_bf16 v[124:127], v[152:155], v[196:199], v[124:127]
	v_mfma_f32_16x16x32_bf16 v[120:123], v[172:175], v[196:199], v[120:123]
	v_mfma_f32_16x16x32_bf16 v[108:111], v[152:155], v[204:207], v[108:111]
	v_mfma_f32_16x16x32_bf16 v[104:107], v[172:175], v[204:207], v[104:107]
	v_mfma_f32_16x16x32_bf16 v[92:95], v[152:155], v[212:215], v[92:95]
	v_mfma_f32_16x16x32_bf16 v[88:91], v[172:175], v[212:215], v[88:91]
	v_mfma_f32_16x16x32_bf16 v[76:79], v[152:155], v[220:223], v[76:79]
	v_mfma_f32_16x16x32_bf16 v[72:75], v[172:175], v[220:223], v[72:75]
	v_mfma_f32_16x16x32_bf16 v[116:119], v[176:179], v[192:195], v[116:119]
	v_mfma_f32_16x16x32_bf16 v[112:115], v[184:187], v[192:195], v[112:115]
	v_mfma_f32_16x16x32_bf16 v[100:103], v[176:179], v[200:203], v[100:103]
	v_mfma_f32_16x16x32_bf16 v[96:99], v[184:187], v[200:203], v[96:99]
	v_mfma_f32_16x16x32_bf16 v[84:87], v[176:179], v[208:211], v[84:87]
	v_mfma_f32_16x16x32_bf16 v[80:83], v[184:187], v[208:211], v[80:83]
	v_mfma_f32_16x16x32_bf16 v[68:71], v[176:179], v[216:219], v[68:71]
	v_mfma_f32_16x16x32_bf16 v[64:67], v[184:187], v[216:219], v[64:67]
	v_mfma_f32_16x16x32_bf16 v[116:119], v[180:183], v[196:199], v[116:119]
	v_mfma_f32_16x16x32_bf16 v[112:115], v[188:191], v[196:199], v[112:115]
	v_mfma_f32_16x16x32_bf16 v[100:103], v[180:183], v[204:207], v[100:103]
	v_mfma_f32_16x16x32_bf16 v[96:99], v[188:191], v[204:207], v[96:99]
	v_mfma_f32_16x16x32_bf16 v[84:87], v[180:183], v[212:215], v[84:87]
	v_mfma_f32_16x16x32_bf16 v[80:83], v[188:191], v[212:215], v[80:83]
	v_mfma_f32_16x16x32_bf16 v[68:71], v[180:183], v[220:223], v[68:71]
	v_mfma_f32_16x16x32_bf16 v[64:67], v[188:191], v[220:223], v[64:67]
	s_barrier
	s_setprio 0
	s_add_i32 s8, s8, s94
	v_lshl_add_u64 v[156:157], v[156:157], 0, s[20:21]
	s_mov_b32 m0, s8
	ds_read_b128 v[192:195], v165 offset:49152
	ds_read_b128 v[196:199], v165 offset:50176
	ds_read_b128 v[200:203], v165 offset:51200
	ds_read_b128 v[204:207], v165 offset:52224
	ds_read_b128 v[208:211], v165 offset:53248
	ds_read_b128 v[212:215], v165 offset:54272
	ds_read_b128 v[216:219], v165 offset:55296
	ds_read_b128 v[220:223], v165 offset:56320
	global_load_lds_dwordx4 v[156:157], off
	s_add_i32 m0, s8, 0x2000
	s_add_u32 s60, s72, 0x30080
	v_lshl_add_u64 v[156:157], v[224:225], 0, s[20:21]
	s_addc_u32 s61, s73, 0
	s_add_i32 s8, s9, s94
	global_load_lds_dwordx4 v[156:157], off
	v_lshl_add_u64 v[156:157], s[60:61], 0, v[130:131]
	s_mov_b32 m0, s8
	s_nop 0
	global_load_lds_dwordx4 v[156:157], off
	v_lshl_add_u64 v[156:157], s[60:61], 0, v[134:135]
	s_add_i32 m0, s8, 0x2000
	s_nop 0
	global_load_lds_dwordx4 v[156:157], off
	v_lshl_add_u64 v[156:157], v[226:227], 0, s[20:21]
	s_mov_b32 m0, s46
	s_nop 0
	global_load_lds_dwordx4 v[156:157], off
	v_lshl_add_u64 v[156:157], v[228:229], 0, s[20:21]
	s_mov_b32 m0, s56
	s_nop 0
	global_load_lds_dwordx4 v[156:157], off
	s_waitcnt vmcnt(8)
	s_waitcnt lgkmcnt(0)
	s_barrier
	s_setprio 1
	s_waitcnt lgkmcnt(0)
	v_mfma_f32_16x16x32_bf16 v[60:63], v[148:151], v[192:195], v[60:63]
	v_mfma_f32_16x16x32_bf16 v[56:59], v[168:171], v[192:195], v[56:59]
	v_mfma_f32_16x16x32_bf16 v[44:47], v[148:151], v[200:203], v[44:47]
	v_mfma_f32_16x16x32_bf16 v[40:43], v[168:171], v[200:203], v[40:43]
	v_mfma_f32_16x16x32_bf16 v[28:31], v[148:151], v[208:211], v[28:31]
	v_mfma_f32_16x16x32_bf16 v[24:27], v[168:171], v[208:211], v[24:27]
	v_mfma_f32_16x16x32_bf16 v[12:15], v[148:151], v[216:219], v[12:15]
	v_mfma_f32_16x16x32_bf16 v[8:11], v[168:171], v[216:219], v[8:11]
	v_mfma_f32_16x16x32_bf16 v[60:63], v[152:155], v[196:199], v[60:63]
	v_mfma_f32_16x16x32_bf16 v[56:59], v[172:175], v[196:199], v[56:59]
	v_mfma_f32_16x16x32_bf16 v[44:47], v[152:155], v[204:207], v[44:47]
	v_mfma_f32_16x16x32_bf16 v[40:43], v[172:175], v[204:207], v[40:43]
	v_mfma_f32_16x16x32_bf16 v[28:31], v[152:155], v[212:215], v[28:31]
	v_mfma_f32_16x16x32_bf16 v[24:27], v[172:175], v[212:215], v[24:27]
	v_mfma_f32_16x16x32_bf16 v[12:15], v[152:155], v[220:223], v[12:15]
	v_mfma_f32_16x16x32_bf16 v[8:11], v[172:175], v[220:223], v[8:11]
	v_mfma_f32_16x16x32_bf16 v[52:55], v[176:179], v[192:195], v[52:55]
	v_mfma_f32_16x16x32_bf16 v[48:51], v[184:187], v[192:195], v[48:51]
	v_mfma_f32_16x16x32_bf16 v[36:39], v[176:179], v[200:203], v[36:39]
	v_mfma_f32_16x16x32_bf16 v[32:35], v[184:187], v[200:203], v[32:35]
	v_mfma_f32_16x16x32_bf16 v[20:23], v[176:179], v[208:211], v[20:23]
	v_mfma_f32_16x16x32_bf16 v[16:19], v[184:187], v[208:211], v[16:19]
	v_mfma_f32_16x16x32_bf16 v[4:7], v[176:179], v[216:219], v[4:7]
	v_mfma_f32_16x16x32_bf16 v[0:3], v[184:187], v[216:219], v[0:3]
	v_mfma_f32_16x16x32_bf16 v[52:55], v[180:183], v[196:199], v[52:55]
	v_mfma_f32_16x16x32_bf16 v[48:51], v[188:191], v[196:199], v[48:51]
	v_mfma_f32_16x16x32_bf16 v[36:39], v[180:183], v[204:207], v[36:39]
	v_mfma_f32_16x16x32_bf16 v[32:35], v[188:191], v[204:207], v[32:35]
	v_mfma_f32_16x16x32_bf16 v[20:23], v[180:183], v[212:215], v[20:23]
	v_mfma_f32_16x16x32_bf16 v[16:19], v[188:191], v[212:215], v[16:19]
	v_mfma_f32_16x16x32_bf16 v[4:7], v[180:183], v[220:223], v[4:7]
	v_mfma_f32_16x16x32_bf16 v[0:3], v[188:191], v[220:223], v[0:3]
	s_barrier
	s_setprio 0
	s_add_i32 s86, s86, 2
	s_add_u32 s84, s84, 0x100
	s_addc_u32 s85, s85, 0
	s_cmp_gt_u32 s86, 9
	s_mov_b64 s[70:71], s[16:17]
	s_cbranch_scc0 .LBB0_2459
	s_and_b64 vcc, exec, s[58:59]
	s_cbranch_vccz .LBB0_2462
	s_barrier

.LBB0_2535:
	ds_read_b128 v[146:149], v155
	ds_read_b128 v[160:163], v155 offset:1024
	ds_read_b128 v[164:167], v155 offset:2048
	ds_read_b128 v[168:171], v155 offset:3072
	ds_read_b128 v[172:175], v156
	ds_read_b128 v[176:179], v156 offset:1024
	ds_read_b128 v[180:183], v156 offset:2048
	ds_read_b128 v[184:187], v156 offset:3072
	s_add_u32 s16, s68, 0x100
	s_addc_u32 s17, s69, 0
	s_cmp_eq_u32 s80, 4
	s_cselect_b32 s73, s49, s17
	s_cselect_b32 s72, s48, s16
	s_cselect_b32 s71, s43, s79
	s_cselect_b32 s70, s77, s78
	v_lshl_add_u64 v[220:221], s[68:69], 0, v[138:139]
	s_add_i32 m0, s29, 0xc000
	ds_read_b128 v[188:191], v157
	ds_read_b128 v[192:195], v157 offset:1024
	ds_read_b128 v[196:199], v157 offset:2048
	ds_read_b128 v[200:203], v157 offset:3072
	ds_read_b128 v[204:207], v157 offset:4096
	ds_read_b128 v[208:211], v157 offset:5120
	ds_read_b128 v[212:215], v157 offset:6144
	ds_read_b128 v[216:219], v157 offset:7168
	global_load_lds_dwordx4 v[220:221], off
	v_lshl_add_u64 v[220:221], s[68:69], 0, v[140:141]
	s_add_i32 m0, s29, 0xe000
	s_nop 0
	global_load_lds_dwordx4 v[220:221], off
	s_waitcnt vmcnt(8)
	s_waitcnt lgkmcnt(0)
	s_barrier
	s_setprio 1
	s_waitcnt lgkmcnt(0)
	v_mfma_f32_16x16x32_bf16 v[124:127], v[146:149], v[188:191], v[124:127]
	v_mfma_f32_16x16x32_bf16 v[120:123], v[164:167], v[188:191], v[120:123]
	v_mfma_f32_16x16x32_bf16 v[108:111], v[146:149], v[196:199], v[108:111]
	v_mfma_f32_16x16x32_bf16 v[104:107], v[164:167], v[196:199], v[104:107]
	v_mfma_f32_16x16x32_bf16 v[92:95], v[146:149], v[204:207], v[92:95]
	v_mfma_f32_16x16x32_bf16 v[88:91], v[164:167], v[204:207], v[88:91]
	v_mfma_f32_16x16x32_bf16 v[76:79], v[146:149], v[212:215], v[76:79]
	v_mfma_f32_16x16x32_bf16 v[72:75], v[164:167], v[212:215], v[72:75]
	v_mfma_f32_16x16x32_bf16 v[124:127], v[160:163], v[192:195], v[124:127]
	v_mfma_f32_16x16x32_bf16 v[120:123], v[168:171], v[192:195], v[120:123]
	v_mfma_f32_16x16x32_bf16 v[108:111], v[160:163], v[200:203], v[108:111]
	v_mfma_f32_16x16x32_bf16 v[104:107], v[168:171], v[200:203], v[104:107]
	v_mfma_f32_16x16x32_bf16 v[92:95], v[160:163], v[208:211], v[92:95]
	v_mfma_f32_16x16x32_bf16 v[88:91], v[168:171], v[208:211], v[88:91]
	v_mfma_f32_16x16x32_bf16 v[76:79], v[160:163], v[216:219], v[76:79]
	v_mfma_f32_16x16x32_bf16 v[72:75], v[168:171], v[216:219], v[72:75]
	v_mfma_f32_16x16x32_bf16 v[116:119], v[172:175], v[188:191], v[116:119]
	v_mfma_f32_16x16x32_bf16 v[112:115], v[180:183], v[188:191], v[112:115]
	v_mfma_f32_16x16x32_bf16 v[100:103], v[172:175], v[196:199], v[100:103]
	v_mfma_f32_16x16x32_bf16 v[96:99], v[180:183], v[196:199], v[96:99]
	v_mfma_f32_16x16x32_bf16 v[84:87], v[172:175], v[204:207], v[84:87]
	v_mfma_f32_16x16x32_bf16 v[80:83], v[180:183], v[204:207], v[80:83]
	v_mfma_f32_16x16x32_bf16 v[68:71], v[172:175], v[212:215], v[68:71]
	v_mfma_f32_16x16x32_bf16 v[64:67], v[180:183], v[212:215], v[64:67]
	v_mfma_f32_16x16x32_bf16 v[116:119], v[176:179], v[192:195], v[116:119]
	v_mfma_f32_16x16x32_bf16 v[112:115], v[184:187], v[192:195], v[112:115]
	v_mfma_f32_16x16x32_bf16 v[100:103], v[176:179], v[200:203], v[100:103]
	v_mfma_f32_16x16x32_bf16 v[96:99], v[184:187], v[200:203], v[96:99]
	v_mfma_f32_16x16x32_bf16 v[84:87], v[176:179], v[208:211], v[84:87]
	v_mfma_f32_16x16x32_bf16 v[80:83], v[184:187], v[208:211], v[80:83]
	v_mfma_f32_16x16x32_bf16 v[68:71], v[176:179], v[216:219], v[68:71]
	v_mfma_f32_16x16x32_bf16 v[64:67], v[184:187], v[216:219], v[64:67]
	s_barrier
	s_setprio 0
	s_add_i32 s8, s67, s94
	v_lshl_add_u64 v[220:221], s[70:71], 0, v[130:131]
	s_mov_b32 m0, s8
	ds_read_b128 v[188:191], v157 offset:16384
	ds_read_b128 v[192:195], v157 offset:17408
	ds_read_b128 v[196:199], v157 offset:18432
	ds_read_b128 v[200:203], v157 offset:19456
	ds_read_b128 v[204:207], v157 offset:20480
	ds_read_b128 v[208:211], v157 offset:21504
	ds_read_b128 v[212:215], v157 offset:22528
	ds_read_b128 v[216:219], v157 offset:23552
	global_load_lds_dwordx4 v[220:221], off
	s_add_i32 m0, s8, 0x2000
	s_add_u32 s60, s70, 0x20000
	v_lshl_add_u64 v[222:223], s[70:71], 0, v[134:135]
	s_addc_u32 s61, s71, 0
	s_add_i32 s8, s74, s94
	global_load_lds_dwordx4 v[222:223], off
	v_lshl_add_u64 v[224:225], s[60:61], 0, v[130:131]
	s_mov_b32 m0, s8
	v_lshl_add_u64 v[226:227], s[72:73], 0, v[132:133]
	global_load_lds_dwordx4 v[224:225], off
	v_lshl_add_u64 v[224:225], s[60:61], 0, v[134:135]
	s_add_i32 m0, s8, 0x2000
	s_nop 0
	global_load_lds_dwordx4 v[224:225], off
	v_lshl_add_u64 v[224:225], s[72:73], 0, v[128:129]
	s_mov_b32 m0, s29
	s_nop 0
	global_load_lds_dwordx4 v[224:225], off
	s_mov_b32 m0, s30
	s_nop 0
	global_load_lds_dwordx4 v[226:227], off
	s_waitcnt vmcnt(8)
	s_waitcnt lgkmcnt(0)
	s_barrier
	s_setprio 1
	s_waitcnt lgkmcnt(0)
	v_mfma_f32_16x16x32_bf16 v[60:63], v[146:149], v[188:191], v[60:63]
	v_mfma_f32_16x16x32_bf16 v[56:59], v[164:167], v[188:191], v[56:59]
	v_mfma_f32_16x16x32_bf16 v[44:47], v[146:149], v[196:199], v[44:47]
	v_mfma_f32_16x16x32_bf16 v[40:43], v[164:167], v[196:199], v[40:43]
	v_mfma_f32_16x16x32_bf16 v[28:31], v[146:149], v[204:207], v[28:31]
	v_mfma_f32_16x16x32_bf16 v[24:27], v[164:167], v[204:207], v[24:27]
	v_mfma_f32_16x16x32_bf16 v[12:15], v[146:149], v[212:215], v[12:15]
	v_mfma_f32_16x16x32_bf16 v[8:11], v[164:167], v[212:215], v[8:11]
	v_mfma_f32_16x16x32_bf16 v[60:63], v[160:163], v[192:195], v[60:63]
	v_mfma_f32_16x16x32_bf16 v[56:59], v[168:171], v[192:195], v[56:59]
	v_mfma_f32_16x16x32_bf16 v[44:47], v[160:163], v[200:203], v[44:47]
	v_mfma_f32_16x16x32_bf16 v[40:43], v[168:171], v[200:203], v[40:43]
	v_mfma_f32_16x16x32_bf16 v[28:31], v[160:163], v[208:211], v[28:31]
	v_mfma_f32_16x16x32_bf16 v[24:27], v[168:171], v[208:211], v[24:27]
	v_mfma_f32_16x16x32_bf16 v[12:15], v[160:163], v[216:219], v[12:15]
	v_mfma_f32_16x16x32_bf16 v[8:11], v[168:171], v[216:219], v[8:11]
	v_mfma_f32_16x16x32_bf16 v[52:55], v[172:175], v[188:191], v[52:55]
	v_mfma_f32_16x16x32_bf16 v[48:51], v[180:183], v[188:191], v[48:51]
	v_mfma_f32_16x16x32_bf16 v[36:39], v[172:175], v[196:199], v[36:39]
	v_mfma_f32_16x16x32_bf16 v[32:35], v[180:183], v[196:199], v[32:35]
	v_mfma_f32_16x16x32_bf16 v[20:23], v[172:175], v[204:207], v[20:23]
	v_mfma_f32_16x16x32_bf16 v[16:19], v[180:183], v[204:207], v[16:19]
	v_mfma_f32_16x16x32_bf16 v[4:7], v[172:175], v[212:215], v[4:7]
	v_mfma_f32_16x16x32_bf16 v[0:3], v[180:183], v[212:215], v[0:3]
	v_mfma_f32_16x16x32_bf16 v[52:55], v[176:179], v[192:195], v[52:55]
	v_mfma_f32_16x16x32_bf16 v[48:51], v[184:187], v[192:195], v[48:51]
	v_mfma_f32_16x16x32_bf16 v[36:39], v[176:179], v[200:203], v[36:39]
	v_mfma_f32_16x16x32_bf16 v[32:35], v[184:187], v[200:203], v[32:35]
	v_mfma_f32_16x16x32_bf16 v[20:23], v[176:179], v[208:211], v[20:23]
	v_mfma_f32_16x16x32_bf16 v[16:19], v[184:187], v[208:211], v[16:19]
	v_mfma_f32_16x16x32_bf16 v[4:7], v[176:179], v[216:219], v[4:7]
	v_mfma_f32_16x16x32_bf16 v[0:3], v[184:187], v[216:219], v[0:3]
	s_barrier
	s_setprio 0
	s_add_i32 s8, 0, 0x18000
	v_add_u32_e32 v159, s8, v151
	s_add_i32 s9, 0, 0x1c000
	ds_read_b128 v[146:149], v159
	ds_read_b128 v[160:163], v159 offset:1024
	ds_read_b128 v[164:167], v159 offset:2048
	ds_read_b128 v[168:171], v159 offset:3072
	v_add_u32_e32 v159, s9, v151
	ds_read_b128 v[172:175], v159
	ds_read_b128 v[176:179], v159 offset:1024
	ds_read_b128 v[180:183], v159 offset:2048
	ds_read_b128 v[184:187], v159 offset:3072
	s_add_u32 s60, s72, 0x60000
	s_addc_u32 s61, s73, 0
	s_mov_b32 m0, s34
	v_lshl_add_u64 v[228:229], s[60:61], 0, v[128:129]
	ds_read_b128 v[188:191], v157 offset:32768
	ds_read_b128 v[192:195], v157 offset:33792
	ds_read_b128 v[196:199], v157 offset:34816
	ds_read_b128 v[200:203], v157 offset:35840
	ds_read_b128 v[204:207], v157 offset:36864
	ds_read_b128 v[208:211], v157 offset:37888
	ds_read_b128 v[212:215], v157 offset:38912
	ds_read_b128 v[216:219], v157 offset:39936
	global_load_lds_dwordx4 v[228:229], off
	v_lshl_add_u64 v[228:229], s[60:61], 0, v[132:133]
	s_mov_b32 m0, s35
	s_nop 0
	global_load_lds_dwordx4 v[228:229], off
	s_waitcnt vmcnt(8)
	s_waitcnt lgkmcnt(0)
	s_barrier
	s_setprio 1
	s_waitcnt lgkmcnt(0)
	v_mfma_f32_16x16x32_bf16 v[124:127], v[146:149], v[188:191], v[124:127]
	v_mfma_f32_16x16x32_bf16 v[120:123], v[164:167], v[188:191], v[120:123]
	v_mfma_f32_16x16x32_bf16 v[108:111], v[146:149], v[196:199], v[108:111]
	v_mfma_f32_16x16x32_bf16 v[104:107], v[164:167], v[196:199], v[104:107]
	v_mfma_f32_16x16x32_bf16 v[92:95], v[146:149], v[204:207], v[92:95]
	v_mfma_f32_16x16x32_bf16 v[88:91], v[164:167], v[204:207], v[88:91]
	v_mfma_f32_16x16x32_bf16 v[76:79], v[146:149], v[212:215], v[76:79]
	v_mfma_f32_16x16x32_bf16 v[72:75], v[164:167], v[212:215], v[72:75]
	v_mfma_f32_16x16x32_bf16 v[124:127], v[160:163], v[192:195], v[124:127]
	v_mfma_f32_16x16x32_bf16 v[120:123], v[168:171], v[192:195], v[120:123]
	v_mfma_f32_16x16x32_bf16 v[108:111], v[160:163], v[200:203], v[108:111]
	v_mfma_f32_16x16x32_bf16 v[104:107], v[168:171], v[200:203], v[104:107]
	v_mfma_f32_16x16x32_bf16 v[92:95], v[160:163], v[208:211], v[92:95]
	v_mfma_f32_16x16x32_bf16 v[88:91], v[168:171], v[208:211], v[88:91]
	v_mfma_f32_16x16x32_bf16 v[76:79], v[160:163], v[216:219], v[76:79]
	v_mfma_f32_16x16x32_bf16 v[72:75], v[168:171], v[216:219], v[72:75]
	v_mfma_f32_16x16x32_bf16 v[116:119], v[172:175], v[188:191], v[116:119]
	v_mfma_f32_16x16x32_bf16 v[112:115], v[180:183], v[188:191], v[112:115]
	v_mfma_f32_16x16x32_bf16 v[100:103], v[172:175], v[196:199], v[100:103]
	v_mfma_f32_16x16x32_bf16 v[96:99], v[180:183], v[196:199], v[96:99]
	v_mfma_f32_16x16x32_bf16 v[84:87], v[172:175], v[204:207], v[84:87]
	v_mfma_f32_16x16x32_bf16 v[80:83], v[180:183], v[204:207], v[80:83]
	v_mfma_f32_16x16x32_bf16 v[68:71], v[172:175], v[212:215], v[68:71]
	v_mfma_f32_16x16x32_bf16 v[64:67], v[180:183], v[212:215], v[64:67]
	v_mfma_f32_16x16x32_bf16 v[116:119], v[176:179], v[192:195], v[116:119]
	v_mfma_f32_16x16x32_bf16 v[112:115], v[184:187], v[192:195], v[112:115]
	v_mfma_f32_16x16x32_bf16 v[100:103], v[176:179], v[200:203], v[100:103]
	v_mfma_f32_16x16x32_bf16 v[96:99], v[184:187], v[200:203], v[96:99]
	v_mfma_f32_16x16x32_bf16 v[84:87], v[176:179], v[208:211], v[84:87]
	v_mfma_f32_16x16x32_bf16 v[80:83], v[184:187], v[208:211], v[80:83]
	v_mfma_f32_16x16x32_bf16 v[68:71], v[176:179], v[216:219], v[68:71]
	v_mfma_f32_16x16x32_bf16 v[64:67], v[184:187], v[216:219], v[64:67]
	s_barrier
	s_setprio 0
	s_add_i32 s8, s8, s94
	v_lshl_add_u64 v[220:221], v[220:221], 0, s[22:23]
	s_mov_b32 m0, s8
	ds_read_b128 v[188:191], v157 offset:49152
	ds_read_b128 v[192:195], v157 offset:50176
	ds_read_b128 v[196:199], v157 offset:51200
	ds_read_b128 v[200:203], v157 offset:52224
	ds_read_b128 v[204:207], v157 offset:53248
	ds_read_b128 v[208:211], v157 offset:54272
	ds_read_b128 v[212:215], v157 offset:55296
	ds_read_b128 v[216:219], v157 offset:56320
	global_load_lds_dwordx4 v[220:221], off
	s_add_i32 m0, s8, 0x2000
	s_add_u32 s60, s70, 0x20080
	v_lshl_add_u64 v[220:221], v[222:223], 0, s[22:23]
	s_addc_u32 s61, s71, 0
	s_add_i32 s8, s9, s94
	global_load_lds_dwordx4 v[220:221], off
	v_lshl_add_u64 v[220:221], s[60:61], 0, v[130:131]
	s_mov_b32 m0, s8
	s_nop 0
	global_load_lds_dwordx4 v[220:221], off
	v_lshl_add_u64 v[220:221], s[60:61], 0, v[134:135]
	s_add_i32 m0, s8, 0x2000
	s_nop 0
	global_load_lds_dwordx4 v[220:221], off
	v_lshl_add_u64 v[220:221], v[224:225], 0, s[22:23]
	s_mov_b32 m0, s56
	s_nop 0
	global_load_lds_dwordx4 v[220:221], off
	v_lshl_add_u64 v[220:221], v[226:227], 0, s[22:23]
	s_mov_b32 m0, s57
	s_nop 0
	global_load_lds_dwordx4 v[220:221], off
	s_waitcnt vmcnt(8)
	s_waitcnt lgkmcnt(0)
	s_barrier
	s_setprio 1
	s_waitcnt lgkmcnt(0)
	v_mfma_f32_16x16x32_bf16 v[60:63], v[146:149], v[188:191], v[60:63]
	v_mfma_f32_16x16x32_bf16 v[56:59], v[164:167], v[188:191], v[56:59]
	v_mfma_f32_16x16x32_bf16 v[44:47], v[146:149], v[196:199], v[44:47]
	v_mfma_f32_16x16x32_bf16 v[40:43], v[164:167], v[196:199], v[40:43]
	v_mfma_f32_16x16x32_bf16 v[28:31], v[146:149], v[204:207], v[28:31]
	v_mfma_f32_16x16x32_bf16 v[24:27], v[164:167], v[204:207], v[24:27]
	v_mfma_f32_16x16x32_bf16 v[12:15], v[146:149], v[212:215], v[12:15]
	v_mfma_f32_16x16x32_bf16 v[8:11], v[164:167], v[212:215], v[8:11]
	v_mfma_f32_16x16x32_bf16 v[60:63], v[160:163], v[192:195], v[60:63]
	v_mfma_f32_16x16x32_bf16 v[56:59], v[168:171], v[192:195], v[56:59]
	v_mfma_f32_16x16x32_bf16 v[44:47], v[160:163], v[200:203], v[44:47]
	v_mfma_f32_16x16x32_bf16 v[40:43], v[168:171], v[200:203], v[40:43]
	v_mfma_f32_16x16x32_bf16 v[28:31], v[160:163], v[208:211], v[28:31]
	v_mfma_f32_16x16x32_bf16 v[24:27], v[168:171], v[208:211], v[24:27]
	v_mfma_f32_16x16x32_bf16 v[12:15], v[160:163], v[216:219], v[12:15]
	v_mfma_f32_16x16x32_bf16 v[8:11], v[168:171], v[216:219], v[8:11]
	v_mfma_f32_16x16x32_bf16 v[52:55], v[172:175], v[188:191], v[52:55]
	v_mfma_f32_16x16x32_bf16 v[48:51], v[180:183], v[188:191], v[48:51]
	v_mfma_f32_16x16x32_bf16 v[36:39], v[172:175], v[196:199], v[36:39]
	v_mfma_f32_16x16x32_bf16 v[32:35], v[180:183], v[196:199], v[32:35]
	v_mfma_f32_16x16x32_bf16 v[20:23], v[172:175], v[204:207], v[20:23]
	v_mfma_f32_16x16x32_bf16 v[16:19], v[180:183], v[204:207], v[16:19]
	v_mfma_f32_16x16x32_bf16 v[4:7], v[172:175], v[212:215], v[4:7]
	v_mfma_f32_16x16x32_bf16 v[0:3], v[180:183], v[212:215], v[0:3]
	v_mfma_f32_16x16x32_bf16 v[52:55], v[176:179], v[192:195], v[52:55]
	v_mfma_f32_16x16x32_bf16 v[48:51], v[184:187], v[192:195], v[48:51]
	v_mfma_f32_16x16x32_bf16 v[36:39], v[176:179], v[200:203], v[36:39]
	v_mfma_f32_16x16x32_bf16 v[32:35], v[184:187], v[200:203], v[32:35]
	v_mfma_f32_16x16x32_bf16 v[20:23], v[176:179], v[208:211], v[20:23]
	v_mfma_f32_16x16x32_bf16 v[16:19], v[184:187], v[208:211], v[16:19]
	v_mfma_f32_16x16x32_bf16 v[4:7], v[176:179], v[216:219], v[4:7]
	v_mfma_f32_16x16x32_bf16 v[0:3], v[184:187], v[216:219], v[0:3]
	s_barrier
	s_setprio 0
	s_add_i32 s80, s80, 2
	s_add_u32 s78, s78, 0x100
	s_addc_u32 s79, s79, 0
	s_cmp_gt_u32 s80, 5
	s_mov_b64 s[68:69], s[16:17]
	s_cbranch_scc0 .LBB0_2535
	s_and_b64 vcc, exec, s[58:59]
	s_cbranch_vccz .LBB0_2538
	s_barrier

.LBB0_2713:
	ds_read_b128 v[140:143], v149
	ds_read_b128 v[152:155], v149 offset:1024
	ds_read_b128 v[156:159], v149 offset:2048
	ds_read_b128 v[160:163], v149 offset:3072
	ds_read_b128 v[164:167], v150
	ds_read_b128 v[168:171], v150 offset:1024
	ds_read_b128 v[172:175], v150 offset:2048
	ds_read_b128 v[176:179], v150 offset:3072
	s_add_u32 s8, s62, 0xfff80080
	s_addc_u32 s9, s63, -1
	s_cmp_eq_u32 s72, 28
	s_cselect_b32 s67, s43, s9
	s_cselect_b32 s66, s57, s8
	s_cselect_b32 s65, s23, s71
	s_cselect_b32 s64, s69, s70
	v_lshl_add_u64 v[212:213], s[62:63], 0, v[132:133]
	s_add_i32 m0, s12, 0xc000
	ds_read_b128 v[180:183], v151
	ds_read_b128 v[184:187], v151 offset:1024
	ds_read_b128 v[188:191], v151 offset:2048
	ds_read_b128 v[192:195], v151 offset:3072
	ds_read_b128 v[196:199], v151 offset:4096
	ds_read_b128 v[200:203], v151 offset:5120
	ds_read_b128 v[204:207], v151 offset:6144
	ds_read_b128 v[208:211], v151 offset:7168
	global_load_lds_dwordx4 v[212:213], off
	v_lshl_add_u64 v[212:213], s[62:63], 0, v[134:135]
	s_add_i32 m0, s12, 0xe000
	s_nop 0
	global_load_lds_dwordx4 v[212:213], off
	s_waitcnt vmcnt(8)
	s_waitcnt lgkmcnt(0)
	s_barrier
	s_setprio 1
	s_waitcnt lgkmcnt(0)
	v_mfma_f32_16x16x32_bf16 v[124:127], v[140:143], v[180:183], v[124:127]
	v_mfma_f32_16x16x32_bf16 v[120:123], v[156:159], v[180:183], v[120:123]
	v_mfma_f32_16x16x32_bf16 v[108:111], v[140:143], v[188:191], v[108:111]
	v_mfma_f32_16x16x32_bf16 v[104:107], v[156:159], v[188:191], v[104:107]
	v_mfma_f32_16x16x32_bf16 v[92:95], v[140:143], v[196:199], v[92:95]
	v_mfma_f32_16x16x32_bf16 v[88:91], v[156:159], v[196:199], v[88:91]
	v_mfma_f32_16x16x32_bf16 v[76:79], v[140:143], v[204:207], v[76:79]
	v_mfma_f32_16x16x32_bf16 v[72:75], v[156:159], v[204:207], v[72:75]
	v_mfma_f32_16x16x32_bf16 v[124:127], v[152:155], v[184:187], v[124:127]
	v_mfma_f32_16x16x32_bf16 v[120:123], v[160:163], v[184:187], v[120:123]
	v_mfma_f32_16x16x32_bf16 v[108:111], v[152:155], v[192:195], v[108:111]
	v_mfma_f32_16x16x32_bf16 v[104:107], v[160:163], v[192:195], v[104:107]
	v_mfma_f32_16x16x32_bf16 v[92:95], v[152:155], v[200:203], v[92:95]
	v_mfma_f32_16x16x32_bf16 v[88:91], v[160:163], v[200:203], v[88:91]
	v_mfma_f32_16x16x32_bf16 v[76:79], v[152:155], v[208:211], v[76:79]
	v_mfma_f32_16x16x32_bf16 v[72:75], v[160:163], v[208:211], v[72:75]
	v_mfma_f32_16x16x32_bf16 v[116:119], v[164:167], v[180:183], v[116:119]
	v_mfma_f32_16x16x32_bf16 v[112:115], v[172:175], v[180:183], v[112:115]
	v_mfma_f32_16x16x32_bf16 v[100:103], v[164:167], v[188:191], v[100:103]
	v_mfma_f32_16x16x32_bf16 v[96:99], v[172:175], v[188:191], v[96:99]
	v_mfma_f32_16x16x32_bf16 v[84:87], v[164:167], v[196:199], v[84:87]
	v_mfma_f32_16x16x32_bf16 v[80:83], v[172:175], v[196:199], v[80:83]
	v_mfma_f32_16x16x32_bf16 v[68:71], v[164:167], v[204:207], v[68:71]
	v_mfma_f32_16x16x32_bf16 v[64:67], v[172:175], v[204:207], v[64:67]
	v_mfma_f32_16x16x32_bf16 v[116:119], v[168:171], v[184:187], v[116:119]
	v_mfma_f32_16x16x32_bf16 v[112:115], v[176:179], v[184:187], v[112:115]
	v_mfma_f32_16x16x32_bf16 v[100:103], v[168:171], v[192:195], v[100:103]
	v_mfma_f32_16x16x32_bf16 v[96:99], v[176:179], v[192:195], v[96:99]
	v_mfma_f32_16x16x32_bf16 v[84:87], v[168:171], v[200:203], v[84:87]
	v_mfma_f32_16x16x32_bf16 v[80:83], v[176:179], v[200:203], v[80:83]
	v_mfma_f32_16x16x32_bf16 v[68:71], v[168:171], v[208:211], v[68:71]
	v_mfma_f32_16x16x32_bf16 v[64:67], v[176:179], v[208:211], v[64:67]
	s_barrier
	s_setprio 0
	s_add_i32 s8, s46, s94
	v_lshl_add_u64 v[212:213], s[64:65], 0, v[128:129]
	s_mov_b32 m0, s8
	ds_read_b128 v[180:183], v151 offset:16384
	ds_read_b128 v[184:187], v151 offset:17408
	ds_read_b128 v[188:191], v151 offset:18432
	ds_read_b128 v[192:195], v151 offset:19456
	ds_read_b128 v[196:199], v151 offset:20480
	ds_read_b128 v[200:203], v151 offset:21504
	ds_read_b128 v[204:207], v151 offset:22528
	ds_read_b128 v[208:211], v151 offset:23552
	global_load_lds_dwordx4 v[212:213], off
	s_add_i32 m0, s8, 0x2000
	s_add_u32 s60, s64, 0x80000
	v_lshl_add_u64 v[214:215], s[64:65], 0, v[130:131]
	s_addc_u32 s61, s65, 0
	s_add_i32 s8, s47, s94
	global_load_lds_dwordx4 v[214:215], off
	v_lshl_add_u64 v[216:217], s[60:61], 0, v[128:129]
	s_mov_b32 m0, s8
	v_lshl_add_u64 v[218:219], s[66:67], 0, v[130:131]
	global_load_lds_dwordx4 v[216:217], off
	v_lshl_add_u64 v[216:217], s[60:61], 0, v[130:131]
	s_add_i32 m0, s8, 0x2000
	s_nop 0
	global_load_lds_dwordx4 v[216:217], off
	v_lshl_add_u64 v[216:217], s[66:67], 0, v[128:129]
	s_mov_b32 m0, s12
	s_nop 0
	global_load_lds_dwordx4 v[216:217], off
	s_mov_b32 m0, s13
	s_nop 0
	global_load_lds_dwordx4 v[218:219], off
	s_waitcnt vmcnt(8)
	s_waitcnt lgkmcnt(0)
	s_barrier
	s_setprio 1
	s_waitcnt lgkmcnt(0)
	v_mfma_f32_16x16x32_bf16 v[60:63], v[140:143], v[180:183], v[60:63]
	v_mfma_f32_16x16x32_bf16 v[56:59], v[156:159], v[180:183], v[56:59]
	v_mfma_f32_16x16x32_bf16 v[44:47], v[140:143], v[188:191], v[44:47]
	v_mfma_f32_16x16x32_bf16 v[40:43], v[156:159], v[188:191], v[40:43]
	v_mfma_f32_16x16x32_bf16 v[28:31], v[140:143], v[196:199], v[28:31]
	v_mfma_f32_16x16x32_bf16 v[24:27], v[156:159], v[196:199], v[24:27]
	v_mfma_f32_16x16x32_bf16 v[12:15], v[140:143], v[204:207], v[12:15]
	v_mfma_f32_16x16x32_bf16 v[8:11], v[156:159], v[204:207], v[8:11]
	v_mfma_f32_16x16x32_bf16 v[60:63], v[152:155], v[184:187], v[60:63]
	v_mfma_f32_16x16x32_bf16 v[56:59], v[160:163], v[184:187], v[56:59]
	v_mfma_f32_16x16x32_bf16 v[44:47], v[152:155], v[192:195], v[44:47]
	v_mfma_f32_16x16x32_bf16 v[40:43], v[160:163], v[192:195], v[40:43]
	v_mfma_f32_16x16x32_bf16 v[28:31], v[152:155], v[200:203], v[28:31]
	v_mfma_f32_16x16x32_bf16 v[24:27], v[160:163], v[200:203], v[24:27]
	v_mfma_f32_16x16x32_bf16 v[12:15], v[152:155], v[208:211], v[12:15]
	v_mfma_f32_16x16x32_bf16 v[8:11], v[160:163], v[208:211], v[8:11]
	v_mfma_f32_16x16x32_bf16 v[52:55], v[164:167], v[180:183], v[52:55]
	v_mfma_f32_16x16x32_bf16 v[48:51], v[172:175], v[180:183], v[48:51]
	v_mfma_f32_16x16x32_bf16 v[36:39], v[164:167], v[188:191], v[36:39]
	v_mfma_f32_16x16x32_bf16 v[32:35], v[172:175], v[188:191], v[32:35]
	v_mfma_f32_16x16x32_bf16 v[20:23], v[164:167], v[196:199], v[20:23]
	v_mfma_f32_16x16x32_bf16 v[16:19], v[172:175], v[196:199], v[16:19]
	v_mfma_f32_16x16x32_bf16 v[4:7], v[164:167], v[204:207], v[4:7]
	v_mfma_f32_16x16x32_bf16 v[0:3], v[172:175], v[204:207], v[0:3]
	v_mfma_f32_16x16x32_bf16 v[52:55], v[168:171], v[184:187], v[52:55]
	v_mfma_f32_16x16x32_bf16 v[48:51], v[176:179], v[184:187], v[48:51]
	v_mfma_f32_16x16x32_bf16 v[36:39], v[168:171], v[192:195], v[36:39]
	v_mfma_f32_16x16x32_bf16 v[32:35], v[176:179], v[192:195], v[32:35]
	v_mfma_f32_16x16x32_bf16 v[20:23], v[168:171], v[200:203], v[20:23]
	v_mfma_f32_16x16x32_bf16 v[16:19], v[176:179], v[200:203], v[16:19]
	v_mfma_f32_16x16x32_bf16 v[4:7], v[168:171], v[208:211], v[4:7]
	v_mfma_f32_16x16x32_bf16 v[0:3], v[176:179], v[208:211], v[0:3]
	s_barrier
	s_setprio 0
	s_add_i32 s8, 0, 0x18000
	s_add_i32 s9, 0, 0x1c000
	v_add_u32_e32 v160, s8, v145
	v_add_u32_e32 v176, s9, v145
	ds_read_b128 v[140:143], v160
	ds_read_b128 v[152:155], v160 offset:1024
	ds_read_b128 v[156:159], v160 offset:2048
	ds_read_b128 v[160:163], v160 offset:3072
	ds_read_b128 v[164:167], v176
	ds_read_b128 v[168:171], v176 offset:1024
	ds_read_b128 v[172:175], v176 offset:2048
	ds_read_b128 v[176:179], v176 offset:3072
	s_add_u32 s60, s66, 0x80000
	s_addc_u32 s61, s67, 0
	s_mov_b32 m0, s29
	v_lshl_add_u64 v[220:221], s[60:61], 0, v[128:129]
	ds_read_b128 v[180:183], v151 offset:32768
	ds_read_b128 v[184:187], v151 offset:33792
	ds_read_b128 v[188:191], v151 offset:34816
	ds_read_b128 v[192:195], v151 offset:35840
	ds_read_b128 v[196:199], v151 offset:36864
	ds_read_b128 v[200:203], v151 offset:37888
	ds_read_b128 v[204:207], v151 offset:38912
	ds_read_b128 v[208:211], v151 offset:39936
	global_load_lds_dwordx4 v[220:221], off
	v_lshl_add_u64 v[220:221], s[60:61], 0, v[130:131]
	s_mov_b32 m0, s30
	s_nop 0
	global_load_lds_dwordx4 v[220:221], off
	s_waitcnt vmcnt(8)
	s_waitcnt lgkmcnt(0)
	s_barrier
	s_setprio 1
	s_waitcnt lgkmcnt(0)
	v_mfma_f32_16x16x32_bf16 v[124:127], v[140:143], v[180:183], v[124:127]
	v_mfma_f32_16x16x32_bf16 v[120:123], v[156:159], v[180:183], v[120:123]
	v_mfma_f32_16x16x32_bf16 v[108:111], v[140:143], v[188:191], v[108:111]
	v_mfma_f32_16x16x32_bf16 v[104:107], v[156:159], v[188:191], v[104:107]
	v_mfma_f32_16x16x32_bf16 v[92:95], v[140:143], v[196:199], v[92:95]
	v_mfma_f32_16x16x32_bf16 v[88:91], v[156:159], v[196:199], v[88:91]
	v_mfma_f32_16x16x32_bf16 v[76:79], v[140:143], v[204:207], v[76:79]
	v_mfma_f32_16x16x32_bf16 v[72:75], v[156:159], v[204:207], v[72:75]
	v_mfma_f32_16x16x32_bf16 v[124:127], v[152:155], v[184:187], v[124:127]
	v_mfma_f32_16x16x32_bf16 v[120:123], v[160:163], v[184:187], v[120:123]
	v_mfma_f32_16x16x32_bf16 v[108:111], v[152:155], v[192:195], v[108:111]
	v_mfma_f32_16x16x32_bf16 v[104:107], v[160:163], v[192:195], v[104:107]
	v_mfma_f32_16x16x32_bf16 v[92:95], v[152:155], v[200:203], v[92:95]
	v_mfma_f32_16x16x32_bf16 v[88:91], v[160:163], v[200:203], v[88:91]
	v_mfma_f32_16x16x32_bf16 v[76:79], v[152:155], v[208:211], v[76:79]
	v_mfma_f32_16x16x32_bf16 v[72:75], v[160:163], v[208:211], v[72:75]
	v_mfma_f32_16x16x32_bf16 v[116:119], v[164:167], v[180:183], v[116:119]
	v_mfma_f32_16x16x32_bf16 v[112:115], v[172:175], v[180:183], v[112:115]
	v_mfma_f32_16x16x32_bf16 v[100:103], v[164:167], v[188:191], v[100:103]
	v_mfma_f32_16x16x32_bf16 v[96:99], v[172:175], v[188:191], v[96:99]
	v_mfma_f32_16x16x32_bf16 v[84:87], v[164:167], v[196:199], v[84:87]
	v_mfma_f32_16x16x32_bf16 v[80:83], v[172:175], v[196:199], v[80:83]
	v_mfma_f32_16x16x32_bf16 v[68:71], v[164:167], v[204:207], v[68:71]
	v_mfma_f32_16x16x32_bf16 v[64:67], v[172:175], v[204:207], v[64:67]
	v_mfma_f32_16x16x32_bf16 v[116:119], v[168:171], v[184:187], v[116:119]
	v_mfma_f32_16x16x32_bf16 v[112:115], v[176:179], v[184:187], v[112:115]
	v_mfma_f32_16x16x32_bf16 v[100:103], v[168:171], v[192:195], v[100:103]
	v_mfma_f32_16x16x32_bf16 v[96:99], v[176:179], v[192:195], v[96:99]
	v_mfma_f32_16x16x32_bf16 v[84:87], v[168:171], v[200:203], v[84:87]
	v_mfma_f32_16x16x32_bf16 v[80:83], v[176:179], v[200:203], v[80:83]
	v_mfma_f32_16x16x32_bf16 v[68:71], v[168:171], v[208:211], v[68:71]
	v_mfma_f32_16x16x32_bf16 v[64:67], v[176:179], v[208:211], v[64:67]
	s_barrier
	s_setprio 0
	s_add_i32 s8, s8, s94
	v_lshl_add_u64 v[212:213], v[212:213], 0, s[20:21]
	s_mov_b32 m0, s8
	ds_read_b128 v[180:183], v151 offset:49152
	ds_read_b128 v[184:187], v151 offset:50176
	ds_read_b128 v[188:191], v151 offset:51200
	ds_read_b128 v[192:195], v151 offset:52224
	ds_read_b128 v[196:199], v151 offset:53248
	ds_read_b128 v[200:203], v151 offset:54272
	ds_read_b128 v[204:207], v151 offset:55296
	ds_read_b128 v[208:211], v151 offset:56320
	global_load_lds_dwordx4 v[212:213], off
	s_add_i32 m0, s8, 0x2000
	s_add_u32 s60, s64, 0x80080
	v_lshl_add_u64 v[212:213], v[214:215], 0, s[20:21]
	s_addc_u32 s61, s65, 0
	s_add_i32 s8, s9, s94
	global_load_lds_dwordx4 v[212:213], off
	v_lshl_add_u64 v[212:213], s[60:61], 0, v[128:129]
	s_mov_b32 m0, s8
	s_nop 0
	global_load_lds_dwordx4 v[212:213], off
	v_lshl_add_u64 v[212:213], s[60:61], 0, v[130:131]
	s_add_i32 m0, s8, 0x2000
	s_nop 0
	global_load_lds_dwordx4 v[212:213], off
	v_lshl_add_u64 v[212:213], v[216:217], 0, s[20:21]
	s_mov_b32 m0, s34
	s_nop 0
	global_load_lds_dwordx4 v[212:213], off
	v_lshl_add_u64 v[212:213], v[218:219], 0, s[20:21]
	s_mov_b32 m0, s35
	s_nop 0
	global_load_lds_dwordx4 v[212:213], off
	s_waitcnt vmcnt(8)
	s_waitcnt lgkmcnt(0)
	s_barrier
	s_setprio 1
	s_waitcnt lgkmcnt(0)
	v_mfma_f32_16x16x32_bf16 v[60:63], v[140:143], v[180:183], v[60:63]
	v_mfma_f32_16x16x32_bf16 v[56:59], v[156:159], v[180:183], v[56:59]
	v_mfma_f32_16x16x32_bf16 v[44:47], v[140:143], v[188:191], v[44:47]
	v_mfma_f32_16x16x32_bf16 v[40:43], v[156:159], v[188:191], v[40:43]
	v_mfma_f32_16x16x32_bf16 v[28:31], v[140:143], v[196:199], v[28:31]
	v_mfma_f32_16x16x32_bf16 v[24:27], v[156:159], v[196:199], v[24:27]
	v_mfma_f32_16x16x32_bf16 v[12:15], v[140:143], v[204:207], v[12:15]
	v_mfma_f32_16x16x32_bf16 v[8:11], v[156:159], v[204:207], v[8:11]
	v_mfma_f32_16x16x32_bf16 v[60:63], v[152:155], v[184:187], v[60:63]
	v_mfma_f32_16x16x32_bf16 v[56:59], v[160:163], v[184:187], v[56:59]
	v_mfma_f32_16x16x32_bf16 v[44:47], v[152:155], v[192:195], v[44:47]
	v_mfma_f32_16x16x32_bf16 v[40:43], v[160:163], v[192:195], v[40:43]
	v_mfma_f32_16x16x32_bf16 v[28:31], v[152:155], v[200:203], v[28:31]
	v_mfma_f32_16x16x32_bf16 v[24:27], v[160:163], v[200:203], v[24:27]
	v_mfma_f32_16x16x32_bf16 v[12:15], v[152:155], v[208:211], v[12:15]
	v_mfma_f32_16x16x32_bf16 v[8:11], v[160:163], v[208:211], v[8:11]
	v_mfma_f32_16x16x32_bf16 v[52:55], v[164:167], v[180:183], v[52:55]
	v_mfma_f32_16x16x32_bf16 v[48:51], v[172:175], v[180:183], v[48:51]
	v_mfma_f32_16x16x32_bf16 v[36:39], v[164:167], v[188:191], v[36:39]
	v_mfma_f32_16x16x32_bf16 v[32:35], v[172:175], v[188:191], v[32:35]
	v_mfma_f32_16x16x32_bf16 v[20:23], v[164:167], v[196:199], v[20:23]
	v_mfma_f32_16x16x32_bf16 v[16:19], v[172:175], v[196:199], v[16:19]
	v_mfma_f32_16x16x32_bf16 v[4:7], v[164:167], v[204:207], v[4:7]
	v_mfma_f32_16x16x32_bf16 v[0:3], v[172:175], v[204:207], v[0:3]
	v_mfma_f32_16x16x32_bf16 v[52:55], v[168:171], v[184:187], v[52:55]
	v_mfma_f32_16x16x32_bf16 v[48:51], v[176:179], v[184:187], v[48:51]
	v_mfma_f32_16x16x32_bf16 v[36:39], v[168:171], v[192:195], v[36:39]
	v_mfma_f32_16x16x32_bf16 v[32:35], v[176:179], v[192:195], v[32:35]
	v_mfma_f32_16x16x32_bf16 v[20:23], v[168:171], v[200:203], v[20:23]
	v_mfma_f32_16x16x32_bf16 v[16:19], v[176:179], v[200:203], v[16:19]
	v_mfma_f32_16x16x32_bf16 v[4:7], v[168:171], v[208:211], v[4:7]
	v_mfma_f32_16x16x32_bf16 v[0:3], v[176:179], v[208:211], v[0:3]
	s_barrier
	s_setprio 0
	s_add_i32 s72, s72, 2
	s_add_u32 s62, s62, 0x100
	s_addc_u32 s63, s63, 0
	s_add_u32 s70, s70, 0x100
	s_addc_u32 s71, s71, 0
	s_cmp_gt_u32 s72, 29
	s_cbranch_scc0 .LBB0_2713
	s_and_b64 vcc, exec, s[58:59]
	s_cbranch_vccz .LBB0_2716
	s_barrier

.LBB0_2805:
	ds_read_b128 v[146:149], v155
	ds_read_b128 v[160:163], v155 offset:1024
	ds_read_b128 v[164:167], v155 offset:2048
	ds_read_b128 v[168:171], v155 offset:3072
	ds_read_b128 v[172:175], v156
	ds_read_b128 v[176:179], v156 offset:1024
	ds_read_b128 v[180:183], v156 offset:2048
	ds_read_b128 v[184:187], v156 offset:3072
	s_add_u32 s8, s48, 0xfff80080
	s_addc_u32 s9, s49, -1
	s_cmp_eq_u32 s67, 28
	s_cselect_b32 s61, s21, s9
	s_cselect_b32 s60, s43, s8
	s_cselect_b32 s57, s19, s66
	s_cselect_b32 s56, s45, s65
	v_lshl_add_u64 v[220:221], s[48:49], 0, v[138:139]
	s_add_i32 m0, s29, 0xc000
	ds_read_b128 v[188:191], v157
	ds_read_b128 v[192:195], v157 offset:1024
	ds_read_b128 v[196:199], v157 offset:2048
	ds_read_b128 v[200:203], v157 offset:3072
	ds_read_b128 v[204:207], v157 offset:4096
	ds_read_b128 v[208:211], v157 offset:5120
	ds_read_b128 v[212:215], v157 offset:6144
	ds_read_b128 v[216:219], v157 offset:7168
	global_load_lds_dwordx4 v[220:221], off
	v_lshl_add_u64 v[220:221], s[48:49], 0, v[140:141]
	s_add_i32 m0, s29, 0xe000
	s_nop 0
	global_load_lds_dwordx4 v[220:221], off
	s_waitcnt vmcnt(8)
	s_waitcnt lgkmcnt(0)
	s_barrier
	s_setprio 1
	s_waitcnt lgkmcnt(0)
	v_mfma_f32_16x16x32_bf16 v[124:127], v[146:149], v[188:191], v[124:127]
	v_mfma_f32_16x16x32_bf16 v[120:123], v[164:167], v[188:191], v[120:123]
	v_mfma_f32_16x16x32_bf16 v[108:111], v[146:149], v[196:199], v[108:111]
	v_mfma_f32_16x16x32_bf16 v[104:107], v[164:167], v[196:199], v[104:107]
	v_mfma_f32_16x16x32_bf16 v[92:95], v[146:149], v[204:207], v[92:95]
	v_mfma_f32_16x16x32_bf16 v[88:91], v[164:167], v[204:207], v[88:91]
	v_mfma_f32_16x16x32_bf16 v[76:79], v[146:149], v[212:215], v[76:79]
	v_mfma_f32_16x16x32_bf16 v[72:75], v[164:167], v[212:215], v[72:75]
	v_mfma_f32_16x16x32_bf16 v[124:127], v[160:163], v[192:195], v[124:127]
	v_mfma_f32_16x16x32_bf16 v[120:123], v[168:171], v[192:195], v[120:123]
	v_mfma_f32_16x16x32_bf16 v[108:111], v[160:163], v[200:203], v[108:111]
	v_mfma_f32_16x16x32_bf16 v[104:107], v[168:171], v[200:203], v[104:107]
	v_mfma_f32_16x16x32_bf16 v[92:95], v[160:163], v[208:211], v[92:95]
	v_mfma_f32_16x16x32_bf16 v[88:91], v[168:171], v[208:211], v[88:91]
	v_mfma_f32_16x16x32_bf16 v[76:79], v[160:163], v[216:219], v[76:79]
	v_mfma_f32_16x16x32_bf16 v[72:75], v[168:171], v[216:219], v[72:75]
	v_mfma_f32_16x16x32_bf16 v[116:119], v[172:175], v[188:191], v[116:119]
	v_mfma_f32_16x16x32_bf16 v[112:115], v[180:183], v[188:191], v[112:115]
	v_mfma_f32_16x16x32_bf16 v[100:103], v[172:175], v[196:199], v[100:103]
	v_mfma_f32_16x16x32_bf16 v[96:99], v[180:183], v[196:199], v[96:99]
	v_mfma_f32_16x16x32_bf16 v[84:87], v[172:175], v[204:207], v[84:87]
	v_mfma_f32_16x16x32_bf16 v[80:83], v[180:183], v[204:207], v[80:83]
	v_mfma_f32_16x16x32_bf16 v[68:71], v[172:175], v[212:215], v[68:71]
	v_mfma_f32_16x16x32_bf16 v[64:67], v[180:183], v[212:215], v[64:67]
	v_mfma_f32_16x16x32_bf16 v[116:119], v[176:179], v[192:195], v[116:119]
	v_mfma_f32_16x16x32_bf16 v[112:115], v[184:187], v[192:195], v[112:115]
	v_mfma_f32_16x16x32_bf16 v[100:103], v[176:179], v[200:203], v[100:103]
	v_mfma_f32_16x16x32_bf16 v[96:99], v[184:187], v[200:203], v[96:99]
	v_mfma_f32_16x16x32_bf16 v[84:87], v[176:179], v[208:211], v[84:87]
	v_mfma_f32_16x16x32_bf16 v[80:83], v[184:187], v[208:211], v[80:83]
	v_mfma_f32_16x16x32_bf16 v[68:71], v[176:179], v[216:219], v[68:71]
	v_mfma_f32_16x16x32_bf16 v[64:67], v[184:187], v[216:219], v[64:67]
	s_barrier
	s_setprio 0
	s_add_i32 s8, s63, s94
	v_lshl_add_u64 v[220:221], s[56:57], 0, v[130:131]
	s_mov_b32 m0, s8
	ds_read_b128 v[188:191], v157 offset:16384
	ds_read_b128 v[192:195], v157 offset:17408
	ds_read_b128 v[196:199], v157 offset:18432
	ds_read_b128 v[200:203], v157 offset:19456
	ds_read_b128 v[204:207], v157 offset:20480
	ds_read_b128 v[208:211], v157 offset:21504
	ds_read_b128 v[212:215], v157 offset:22528
	ds_read_b128 v[216:219], v157 offset:23552
	global_load_lds_dwordx4 v[220:221], off
	s_add_i32 m0, s8, 0x2000
	s_add_u32 s68, s56, 0x80000
	v_lshl_add_u64 v[222:223], s[56:57], 0, v[134:135]
	s_addc_u32 s69, s57, 0
	s_add_i32 s8, s64, s94
	global_load_lds_dwordx4 v[222:223], off
	v_lshl_add_u64 v[224:225], s[68:69], 0, v[130:131]
	s_mov_b32 m0, s8
	v_lshl_add_u64 v[226:227], s[60:61], 0, v[132:133]
	global_load_lds_dwordx4 v[224:225], off
	v_lshl_add_u64 v[224:225], s[68:69], 0, v[134:135]
	s_add_i32 m0, s8, 0x2000
	s_nop 0
	global_load_lds_dwordx4 v[224:225], off
	v_lshl_add_u64 v[224:225], s[60:61], 0, v[128:129]
	s_mov_b32 m0, s29
	s_nop 0
	global_load_lds_dwordx4 v[224:225], off
	s_mov_b32 m0, s30
	s_nop 0
	global_load_lds_dwordx4 v[226:227], off
	s_waitcnt vmcnt(8)
	s_waitcnt lgkmcnt(0)
	s_barrier
	s_setprio 1
	s_waitcnt lgkmcnt(0)
	v_mfma_f32_16x16x32_bf16 v[60:63], v[146:149], v[188:191], v[60:63]
	v_mfma_f32_16x16x32_bf16 v[56:59], v[164:167], v[188:191], v[56:59]
	v_mfma_f32_16x16x32_bf16 v[44:47], v[146:149], v[196:199], v[44:47]
	v_mfma_f32_16x16x32_bf16 v[40:43], v[164:167], v[196:199], v[40:43]
	v_mfma_f32_16x16x32_bf16 v[28:31], v[146:149], v[204:207], v[28:31]
	v_mfma_f32_16x16x32_bf16 v[24:27], v[164:167], v[204:207], v[24:27]
	v_mfma_f32_16x16x32_bf16 v[12:15], v[146:149], v[212:215], v[12:15]
	v_mfma_f32_16x16x32_bf16 v[8:11], v[164:167], v[212:215], v[8:11]
	v_mfma_f32_16x16x32_bf16 v[60:63], v[160:163], v[192:195], v[60:63]
	v_mfma_f32_16x16x32_bf16 v[56:59], v[168:171], v[192:195], v[56:59]
	v_mfma_f32_16x16x32_bf16 v[44:47], v[160:163], v[200:203], v[44:47]
	v_mfma_f32_16x16x32_bf16 v[40:43], v[168:171], v[200:203], v[40:43]
	v_mfma_f32_16x16x32_bf16 v[28:31], v[160:163], v[208:211], v[28:31]
	v_mfma_f32_16x16x32_bf16 v[24:27], v[168:171], v[208:211], v[24:27]
	v_mfma_f32_16x16x32_bf16 v[12:15], v[160:163], v[216:219], v[12:15]
	v_mfma_f32_16x16x32_bf16 v[8:11], v[168:171], v[216:219], v[8:11]
	v_mfma_f32_16x16x32_bf16 v[52:55], v[172:175], v[188:191], v[52:55]
	v_mfma_f32_16x16x32_bf16 v[48:51], v[180:183], v[188:191], v[48:51]
	v_mfma_f32_16x16x32_bf16 v[36:39], v[172:175], v[196:199], v[36:39]
	v_mfma_f32_16x16x32_bf16 v[32:35], v[180:183], v[196:199], v[32:35]
	v_mfma_f32_16x16x32_bf16 v[20:23], v[172:175], v[204:207], v[20:23]
	v_mfma_f32_16x16x32_bf16 v[16:19], v[180:183], v[204:207], v[16:19]
	v_mfma_f32_16x16x32_bf16 v[4:7], v[172:175], v[212:215], v[4:7]
	v_mfma_f32_16x16x32_bf16 v[0:3], v[180:183], v[212:215], v[0:3]
	v_mfma_f32_16x16x32_bf16 v[52:55], v[176:179], v[192:195], v[52:55]
	v_mfma_f32_16x16x32_bf16 v[48:51], v[184:187], v[192:195], v[48:51]
	v_mfma_f32_16x16x32_bf16 v[36:39], v[176:179], v[200:203], v[36:39]
	v_mfma_f32_16x16x32_bf16 v[32:35], v[184:187], v[200:203], v[32:35]
	v_mfma_f32_16x16x32_bf16 v[20:23], v[176:179], v[208:211], v[20:23]
	v_mfma_f32_16x16x32_bf16 v[16:19], v[184:187], v[208:211], v[16:19]
	v_mfma_f32_16x16x32_bf16 v[4:7], v[176:179], v[216:219], v[4:7]
	v_mfma_f32_16x16x32_bf16 v[0:3], v[184:187], v[216:219], v[0:3]
	s_barrier
	s_setprio 0
	s_add_i32 s8, 0, 0x18000
	v_add_u32_e32 v159, s8, v151
	s_add_i32 s9, 0, 0x1c000
	ds_read_b128 v[146:149], v159
	ds_read_b128 v[160:163], v159 offset:1024
	ds_read_b128 v[164:167], v159 offset:2048
	ds_read_b128 v[168:171], v159 offset:3072
	v_add_u32_e32 v159, s9, v151
	ds_read_b128 v[172:175], v159
	ds_read_b128 v[176:179], v159 offset:1024
	ds_read_b128 v[180:183], v159 offset:2048
	ds_read_b128 v[184:187], v159 offset:3072
	s_add_u32 s60, s60, 0x80000
	s_addc_u32 s61, s61, 0
	s_mov_b32 m0, s34
	v_lshl_add_u64 v[228:229], s[60:61], 0, v[128:129]
	ds_read_b128 v[188:191], v157 offset:32768
	ds_read_b128 v[192:195], v157 offset:33792
	ds_read_b128 v[196:199], v157 offset:34816
	ds_read_b128 v[200:203], v157 offset:35840
	ds_read_b128 v[204:207], v157 offset:36864
	ds_read_b128 v[208:211], v157 offset:37888
	ds_read_b128 v[212:215], v157 offset:38912
	ds_read_b128 v[216:219], v157 offset:39936
	global_load_lds_dwordx4 v[228:229], off
	v_lshl_add_u64 v[228:229], s[60:61], 0, v[132:133]
	s_mov_b32 m0, s35
	s_nop 0
	global_load_lds_dwordx4 v[228:229], off
	s_waitcnt vmcnt(8)
	s_waitcnt lgkmcnt(0)
	s_barrier
	s_setprio 1
	s_waitcnt lgkmcnt(0)
	v_mfma_f32_16x16x32_bf16 v[124:127], v[146:149], v[188:191], v[124:127]
	v_mfma_f32_16x16x32_bf16 v[120:123], v[164:167], v[188:191], v[120:123]
	v_mfma_f32_16x16x32_bf16 v[108:111], v[146:149], v[196:199], v[108:111]
	v_mfma_f32_16x16x32_bf16 v[104:107], v[164:167], v[196:199], v[104:107]
	v_mfma_f32_16x16x32_bf16 v[92:95], v[146:149], v[204:207], v[92:95]
	v_mfma_f32_16x16x32_bf16 v[88:91], v[164:167], v[204:207], v[88:91]
	v_mfma_f32_16x16x32_bf16 v[76:79], v[146:149], v[212:215], v[76:79]
	v_mfma_f32_16x16x32_bf16 v[72:75], v[164:167], v[212:215], v[72:75]
	v_mfma_f32_16x16x32_bf16 v[124:127], v[160:163], v[192:195], v[124:127]
	v_mfma_f32_16x16x32_bf16 v[120:123], v[168:171], v[192:195], v[120:123]
	v_mfma_f32_16x16x32_bf16 v[108:111], v[160:163], v[200:203], v[108:111]
	v_mfma_f32_16x16x32_bf16 v[104:107], v[168:171], v[200:203], v[104:107]
	v_mfma_f32_16x16x32_bf16 v[92:95], v[160:163], v[208:211], v[92:95]
	v_mfma_f32_16x16x32_bf16 v[88:91], v[168:171], v[208:211], v[88:91]
	v_mfma_f32_16x16x32_bf16 v[76:79], v[160:163], v[216:219], v[76:79]
	v_mfma_f32_16x16x32_bf16 v[72:75], v[168:171], v[216:219], v[72:75]
	v_mfma_f32_16x16x32_bf16 v[116:119], v[172:175], v[188:191], v[116:119]
	v_mfma_f32_16x16x32_bf16 v[112:115], v[180:183], v[188:191], v[112:115]
	v_mfma_f32_16x16x32_bf16 v[100:103], v[172:175], v[196:199], v[100:103]
	v_mfma_f32_16x16x32_bf16 v[96:99], v[180:183], v[196:199], v[96:99]
	v_mfma_f32_16x16x32_bf16 v[84:87], v[172:175], v[204:207], v[84:87]
	v_mfma_f32_16x16x32_bf16 v[80:83], v[180:183], v[204:207], v[80:83]
	v_mfma_f32_16x16x32_bf16 v[68:71], v[172:175], v[212:215], v[68:71]
	v_mfma_f32_16x16x32_bf16 v[64:67], v[180:183], v[212:215], v[64:67]
	v_mfma_f32_16x16x32_bf16 v[116:119], v[176:179], v[192:195], v[116:119]
	v_mfma_f32_16x16x32_bf16 v[112:115], v[184:187], v[192:195], v[112:115]
	v_mfma_f32_16x16x32_bf16 v[100:103], v[176:179], v[200:203], v[100:103]
	v_mfma_f32_16x16x32_bf16 v[96:99], v[184:187], v[200:203], v[96:99]
	v_mfma_f32_16x16x32_bf16 v[84:87], v[176:179], v[208:211], v[84:87]
	v_mfma_f32_16x16x32_bf16 v[80:83], v[184:187], v[208:211], v[80:83]
	v_mfma_f32_16x16x32_bf16 v[68:71], v[176:179], v[216:219], v[68:71]
	v_mfma_f32_16x16x32_bf16 v[64:67], v[184:187], v[216:219], v[64:67]
	s_barrier
	s_setprio 0
	s_add_i32 s8, s8, s94
	v_lshl_add_u64 v[220:221], v[220:221], 0, s[16:17]
	s_mov_b32 m0, s8
	ds_read_b128 v[188:191], v157 offset:49152
	ds_read_b128 v[192:195], v157 offset:50176
	ds_read_b128 v[196:199], v157 offset:51200
	ds_read_b128 v[200:203], v157 offset:52224
	ds_read_b128 v[204:207], v157 offset:53248
	ds_read_b128 v[208:211], v157 offset:54272
	ds_read_b128 v[212:215], v157 offset:55296
	ds_read_b128 v[216:219], v157 offset:56320
	global_load_lds_dwordx4 v[220:221], off
	s_add_i32 m0, s8, 0x2000
	s_add_u32 s56, s56, 0x80080
	v_lshl_add_u64 v[220:221], v[222:223], 0, s[16:17]
	s_addc_u32 s57, s57, 0
	s_add_i32 s8, s9, s94
	global_load_lds_dwordx4 v[220:221], off
	v_lshl_add_u64 v[220:221], s[56:57], 0, v[130:131]
	s_mov_b32 m0, s8
	s_nop 0
	global_load_lds_dwordx4 v[220:221], off
	v_lshl_add_u64 v[220:221], s[56:57], 0, v[134:135]
	s_add_i32 m0, s8, 0x2000
	s_nop 0
	global_load_lds_dwordx4 v[220:221], off
	v_lshl_add_u64 v[220:221], v[224:225], 0, s[16:17]
	s_mov_b32 m0, s47
	s_nop 0
	global_load_lds_dwordx4 v[220:221], off
	v_lshl_add_u64 v[220:221], v[226:227], 0, s[16:17]
	s_mov_b32 m0, s62
	s_nop 0
	global_load_lds_dwordx4 v[220:221], off
	s_waitcnt vmcnt(8)
	s_waitcnt lgkmcnt(0)
	s_barrier
	s_setprio 1
	s_waitcnt lgkmcnt(0)
	v_mfma_f32_16x16x32_bf16 v[60:63], v[146:149], v[188:191], v[60:63]
	v_mfma_f32_16x16x32_bf16 v[56:59], v[164:167], v[188:191], v[56:59]
	v_mfma_f32_16x16x32_bf16 v[44:47], v[146:149], v[196:199], v[44:47]
	v_mfma_f32_16x16x32_bf16 v[40:43], v[164:167], v[196:199], v[40:43]
	v_mfma_f32_16x16x32_bf16 v[28:31], v[146:149], v[204:207], v[28:31]
	v_mfma_f32_16x16x32_bf16 v[24:27], v[164:167], v[204:207], v[24:27]
	v_mfma_f32_16x16x32_bf16 v[12:15], v[146:149], v[212:215], v[12:15]
	v_mfma_f32_16x16x32_bf16 v[8:11], v[164:167], v[212:215], v[8:11]
	v_mfma_f32_16x16x32_bf16 v[60:63], v[160:163], v[192:195], v[60:63]
	v_mfma_f32_16x16x32_bf16 v[56:59], v[168:171], v[192:195], v[56:59]
	v_mfma_f32_16x16x32_bf16 v[44:47], v[160:163], v[200:203], v[44:47]
	v_mfma_f32_16x16x32_bf16 v[40:43], v[168:171], v[200:203], v[40:43]
	v_mfma_f32_16x16x32_bf16 v[28:31], v[160:163], v[208:211], v[28:31]
	v_mfma_f32_16x16x32_bf16 v[24:27], v[168:171], v[208:211], v[24:27]
	v_mfma_f32_16x16x32_bf16 v[12:15], v[160:163], v[216:219], v[12:15]
	v_mfma_f32_16x16x32_bf16 v[8:11], v[168:171], v[216:219], v[8:11]
	v_mfma_f32_16x16x32_bf16 v[52:55], v[172:175], v[188:191], v[52:55]
	v_mfma_f32_16x16x32_bf16 v[48:51], v[180:183], v[188:191], v[48:51]
	v_mfma_f32_16x16x32_bf16 v[36:39], v[172:175], v[196:199], v[36:39]
	v_mfma_f32_16x16x32_bf16 v[32:35], v[180:183], v[196:199], v[32:35]
	v_mfma_f32_16x16x32_bf16 v[20:23], v[172:175], v[204:207], v[20:23]
	v_mfma_f32_16x16x32_bf16 v[16:19], v[180:183], v[204:207], v[16:19]
	v_mfma_f32_16x16x32_bf16 v[4:7], v[172:175], v[212:215], v[4:7]
	v_mfma_f32_16x16x32_bf16 v[0:3], v[180:183], v[212:215], v[0:3]
	v_mfma_f32_16x16x32_bf16 v[52:55], v[176:179], v[192:195], v[52:55]
	v_mfma_f32_16x16x32_bf16 v[48:51], v[184:187], v[192:195], v[48:51]
	v_mfma_f32_16x16x32_bf16 v[36:39], v[176:179], v[200:203], v[36:39]
	v_mfma_f32_16x16x32_bf16 v[32:35], v[184:187], v[200:203], v[32:35]
	v_mfma_f32_16x16x32_bf16 v[20:23], v[176:179], v[208:211], v[20:23]
	v_mfma_f32_16x16x32_bf16 v[16:19], v[184:187], v[208:211], v[16:19]
	v_mfma_f32_16x16x32_bf16 v[4:7], v[176:179], v[216:219], v[4:7]
	v_mfma_f32_16x16x32_bf16 v[0:3], v[184:187], v[216:219], v[0:3]
	s_barrier
	s_setprio 0
	s_add_i32 s67, s67, 2
	s_add_u32 s48, s48, 0x100
	s_addc_u32 s49, s49, 0
	s_add_u32 s65, s65, 0x100
	s_addc_u32 s66, s66, 0
	s_cmp_gt_u32 s67, 29
	s_cbranch_scc0 .LBB0_2805
	s_and_b64 vcc, exec, s[58:59]
	s_cbranch_vccz .LBB0_2808
	s_barrier

.LBB0_2917:
	ds_read_b128 v[140:143], v149
	ds_read_b128 v[152:155], v149 offset:1024
	ds_read_b128 v[156:159], v149 offset:2048
	ds_read_b128 v[160:163], v149 offset:3072
	ds_read_b128 v[164:167], v150
	ds_read_b128 v[168:171], v150 offset:1024
	ds_read_b128 v[172:175], v150 offset:2048
	ds_read_b128 v[176:179], v150 offset:3072
	s_add_u32 s42, s40, 0xffe00080
	s_addc_u32 s43, s41, -1
	s_cmpk_eq_i32 s64, 0x7c
	s_cselect_b32 s45, s21, s43
	s_cselect_b32 s44, s39, s42
	s_cselect_b32 s43, s19, s63
	s_cselect_b32 s42, s61, s62
	v_lshl_add_u64 v[212:213], s[40:41], 0, v[132:133]
	s_add_i32 m0, s29, 0xc000
	ds_read_b128 v[180:183], v151
	ds_read_b128 v[184:187], v151 offset:1024
	ds_read_b128 v[188:191], v151 offset:2048
	ds_read_b128 v[192:195], v151 offset:3072
	ds_read_b128 v[196:199], v151 offset:4096
	ds_read_b128 v[200:203], v151 offset:5120
	ds_read_b128 v[204:207], v151 offset:6144
	ds_read_b128 v[208:211], v151 offset:7168
	global_load_lds_dwordx4 v[212:213], off
	v_lshl_add_u64 v[212:213], s[40:41], 0, v[134:135]
	s_add_i32 m0, s29, 0xe000
	s_nop 0
	global_load_lds_dwordx4 v[212:213], off
	s_waitcnt vmcnt(8)
	s_waitcnt lgkmcnt(0)
	s_barrier
	s_setprio 1
	s_waitcnt lgkmcnt(0)
	v_mfma_f32_16x16x32_bf16 v[124:127], v[140:143], v[180:183], v[124:127]
	v_mfma_f32_16x16x32_bf16 v[120:123], v[156:159], v[180:183], v[120:123]
	v_mfma_f32_16x16x32_bf16 v[108:111], v[140:143], v[188:191], v[108:111]
	v_mfma_f32_16x16x32_bf16 v[104:107], v[156:159], v[188:191], v[104:107]
	v_mfma_f32_16x16x32_bf16 v[92:95], v[140:143], v[196:199], v[92:95]
	v_mfma_f32_16x16x32_bf16 v[88:91], v[156:159], v[196:199], v[88:91]
	v_mfma_f32_16x16x32_bf16 v[76:79], v[140:143], v[204:207], v[76:79]
	v_mfma_f32_16x16x32_bf16 v[72:75], v[156:159], v[204:207], v[72:75]
	v_mfma_f32_16x16x32_bf16 v[124:127], v[152:155], v[184:187], v[124:127]
	v_mfma_f32_16x16x32_bf16 v[120:123], v[160:163], v[184:187], v[120:123]
	v_mfma_f32_16x16x32_bf16 v[108:111], v[152:155], v[192:195], v[108:111]
	v_mfma_f32_16x16x32_bf16 v[104:107], v[160:163], v[192:195], v[104:107]
	v_mfma_f32_16x16x32_bf16 v[92:95], v[152:155], v[200:203], v[92:95]
	v_mfma_f32_16x16x32_bf16 v[88:91], v[160:163], v[200:203], v[88:91]
	v_mfma_f32_16x16x32_bf16 v[76:79], v[152:155], v[208:211], v[76:79]
	v_mfma_f32_16x16x32_bf16 v[72:75], v[160:163], v[208:211], v[72:75]
	v_mfma_f32_16x16x32_bf16 v[116:119], v[164:167], v[180:183], v[116:119]
	v_mfma_f32_16x16x32_bf16 v[112:115], v[172:175], v[180:183], v[112:115]
	v_mfma_f32_16x16x32_bf16 v[100:103], v[164:167], v[188:191], v[100:103]
	v_mfma_f32_16x16x32_bf16 v[96:99], v[172:175], v[188:191], v[96:99]
	v_mfma_f32_16x16x32_bf16 v[84:87], v[164:167], v[196:199], v[84:87]
	v_mfma_f32_16x16x32_bf16 v[80:83], v[172:175], v[196:199], v[80:83]
	v_mfma_f32_16x16x32_bf16 v[68:71], v[164:167], v[204:207], v[68:71]
	v_mfma_f32_16x16x32_bf16 v[64:67], v[172:175], v[204:207], v[64:67]
	v_mfma_f32_16x16x32_bf16 v[116:119], v[168:171], v[184:187], v[116:119]
	v_mfma_f32_16x16x32_bf16 v[112:115], v[176:179], v[184:187], v[112:115]
	v_mfma_f32_16x16x32_bf16 v[100:103], v[168:171], v[192:195], v[100:103]
	v_mfma_f32_16x16x32_bf16 v[96:99], v[176:179], v[192:195], v[96:99]
	v_mfma_f32_16x16x32_bf16 v[84:87], v[168:171], v[200:203], v[84:87]
	v_mfma_f32_16x16x32_bf16 v[80:83], v[176:179], v[200:203], v[80:83]
	v_mfma_f32_16x16x32_bf16 v[68:71], v[168:171], v[208:211], v[68:71]
	v_mfma_f32_16x16x32_bf16 v[64:67], v[176:179], v[208:211], v[64:67]
	s_barrier
	s_setprio 0
	s_add_i32 s65, s56, s94
	v_lshl_add_u64 v[212:213], s[42:43], 0, v[128:129]
	s_mov_b32 m0, s65
	ds_read_b128 v[180:183], v151 offset:16384
	ds_read_b128 v[184:187], v151 offset:17408
	ds_read_b128 v[188:191], v151 offset:18432
	ds_read_b128 v[192:195], v151 offset:19456
	ds_read_b128 v[196:199], v151 offset:20480
	ds_read_b128 v[200:203], v151 offset:21504
	ds_read_b128 v[204:207], v151 offset:22528
	ds_read_b128 v[208:211], v151 offset:23552
	global_load_lds_dwordx4 v[212:213], off
	s_add_i32 m0, s65, 0x2000
	s_add_u32 s66, s42, 0x200000
	v_lshl_add_u64 v[214:215], s[42:43], 0, v[130:131]
	s_addc_u32 s67, s43, 0
	s_add_i32 s65, s57, s94
	global_load_lds_dwordx4 v[214:215], off
	v_lshl_add_u64 v[216:217], s[66:67], 0, v[128:129]
	s_mov_b32 m0, s65
	v_lshl_add_u64 v[218:219], s[44:45], 0, v[130:131]
	global_load_lds_dwordx4 v[216:217], off
	v_lshl_add_u64 v[216:217], s[66:67], 0, v[130:131]
	s_add_i32 m0, s65, 0x2000
	s_nop 0
	global_load_lds_dwordx4 v[216:217], off
	v_lshl_add_u64 v[216:217], s[44:45], 0, v[128:129]
	s_mov_b32 m0, s29
	s_nop 0
	global_load_lds_dwordx4 v[216:217], off
	s_mov_b32 m0, s30
	s_nop 0
	global_load_lds_dwordx4 v[218:219], off
	s_waitcnt vmcnt(8)
	s_waitcnt lgkmcnt(0)
	s_barrier
	s_setprio 1
	s_waitcnt lgkmcnt(0)
	v_mfma_f32_16x16x32_bf16 v[60:63], v[140:143], v[180:183], v[60:63]
	v_mfma_f32_16x16x32_bf16 v[56:59], v[156:159], v[180:183], v[56:59]
	v_mfma_f32_16x16x32_bf16 v[44:47], v[140:143], v[188:191], v[44:47]
	v_mfma_f32_16x16x32_bf16 v[40:43], v[156:159], v[188:191], v[40:43]
	v_mfma_f32_16x16x32_bf16 v[28:31], v[140:143], v[196:199], v[28:31]
	v_mfma_f32_16x16x32_bf16 v[24:27], v[156:159], v[196:199], v[24:27]
	v_mfma_f32_16x16x32_bf16 v[12:15], v[140:143], v[204:207], v[12:15]
	v_mfma_f32_16x16x32_bf16 v[8:11], v[156:159], v[204:207], v[8:11]
	v_mfma_f32_16x16x32_bf16 v[60:63], v[152:155], v[184:187], v[60:63]
	v_mfma_f32_16x16x32_bf16 v[56:59], v[160:163], v[184:187], v[56:59]
	v_mfma_f32_16x16x32_bf16 v[44:47], v[152:155], v[192:195], v[44:47]
	v_mfma_f32_16x16x32_bf16 v[40:43], v[160:163], v[192:195], v[40:43]
	v_mfma_f32_16x16x32_bf16 v[28:31], v[152:155], v[200:203], v[28:31]
	v_mfma_f32_16x16x32_bf16 v[24:27], v[160:163], v[200:203], v[24:27]
	v_mfma_f32_16x16x32_bf16 v[12:15], v[152:155], v[208:211], v[12:15]
	v_mfma_f32_16x16x32_bf16 v[8:11], v[160:163], v[208:211], v[8:11]
	v_mfma_f32_16x16x32_bf16 v[52:55], v[164:167], v[180:183], v[52:55]
	v_mfma_f32_16x16x32_bf16 v[48:51], v[172:175], v[180:183], v[48:51]
	v_mfma_f32_16x16x32_bf16 v[36:39], v[164:167], v[188:191], v[36:39]
	v_mfma_f32_16x16x32_bf16 v[32:35], v[172:175], v[188:191], v[32:35]
	v_mfma_f32_16x16x32_bf16 v[20:23], v[164:167], v[196:199], v[20:23]
	v_mfma_f32_16x16x32_bf16 v[16:19], v[172:175], v[196:199], v[16:19]
	v_mfma_f32_16x16x32_bf16 v[4:7], v[164:167], v[204:207], v[4:7]
	v_mfma_f32_16x16x32_bf16 v[0:3], v[172:175], v[204:207], v[0:3]
	v_mfma_f32_16x16x32_bf16 v[52:55], v[168:171], v[184:187], v[52:55]
	v_mfma_f32_16x16x32_bf16 v[48:51], v[176:179], v[184:187], v[48:51]
	v_mfma_f32_16x16x32_bf16 v[36:39], v[168:171], v[192:195], v[36:39]
	v_mfma_f32_16x16x32_bf16 v[32:35], v[176:179], v[192:195], v[32:35]
	v_mfma_f32_16x16x32_bf16 v[20:23], v[168:171], v[200:203], v[20:23]
	v_mfma_f32_16x16x32_bf16 v[16:19], v[176:179], v[200:203], v[16:19]
	v_mfma_f32_16x16x32_bf16 v[4:7], v[168:171], v[208:211], v[4:7]
	v_mfma_f32_16x16x32_bf16 v[0:3], v[176:179], v[208:211], v[0:3]
	s_barrier
	s_setprio 0
	s_add_i32 s65, 0, 0x18000
	s_add_i32 s66, 0, 0x1c000
	v_add_u32_e32 v160, s65, v145
	v_add_u32_e32 v176, s66, v145
	ds_read_b128 v[140:143], v160
	ds_read_b128 v[152:155], v160 offset:1024
	ds_read_b128 v[156:159], v160 offset:2048
	ds_read_b128 v[160:163], v160 offset:3072
	ds_read_b128 v[164:167], v176
	ds_read_b128 v[168:171], v176 offset:1024
	ds_read_b128 v[172:175], v176 offset:2048
	ds_read_b128 v[176:179], v176 offset:3072
	s_add_u32 s44, s44, 0x200000
	s_addc_u32 s45, s45, 0
	s_mov_b32 m0, s46
	v_lshl_add_u64 v[220:221], s[44:45], 0, v[128:129]
	ds_read_b128 v[180:183], v151 offset:32768
	ds_read_b128 v[184:187], v151 offset:33792
	ds_read_b128 v[188:191], v151 offset:34816
	ds_read_b128 v[192:195], v151 offset:35840
	ds_read_b128 v[196:199], v151 offset:36864
	ds_read_b128 v[200:203], v151 offset:37888
	ds_read_b128 v[204:207], v151 offset:38912
	ds_read_b128 v[208:211], v151 offset:39936
	global_load_lds_dwordx4 v[220:221], off
	v_lshl_add_u64 v[220:221], s[44:45], 0, v[130:131]
	s_mov_b32 m0, s47
	s_nop 0
	global_load_lds_dwordx4 v[220:221], off
	s_waitcnt vmcnt(8)
	s_waitcnt lgkmcnt(0)
	s_barrier
	s_setprio 1
	s_waitcnt lgkmcnt(0)
	v_mfma_f32_16x16x32_bf16 v[124:127], v[140:143], v[180:183], v[124:127]
	v_mfma_f32_16x16x32_bf16 v[120:123], v[156:159], v[180:183], v[120:123]
	v_mfma_f32_16x16x32_bf16 v[108:111], v[140:143], v[188:191], v[108:111]
	v_mfma_f32_16x16x32_bf16 v[104:107], v[156:159], v[188:191], v[104:107]
	v_mfma_f32_16x16x32_bf16 v[92:95], v[140:143], v[196:199], v[92:95]
	v_mfma_f32_16x16x32_bf16 v[88:91], v[156:159], v[196:199], v[88:91]
	v_mfma_f32_16x16x32_bf16 v[76:79], v[140:143], v[204:207], v[76:79]
	v_mfma_f32_16x16x32_bf16 v[72:75], v[156:159], v[204:207], v[72:75]
	v_mfma_f32_16x16x32_bf16 v[124:127], v[152:155], v[184:187], v[124:127]
	v_mfma_f32_16x16x32_bf16 v[120:123], v[160:163], v[184:187], v[120:123]
	v_mfma_f32_16x16x32_bf16 v[108:111], v[152:155], v[192:195], v[108:111]
	v_mfma_f32_16x16x32_bf16 v[104:107], v[160:163], v[192:195], v[104:107]
	v_mfma_f32_16x16x32_bf16 v[92:95], v[152:155], v[200:203], v[92:95]
	v_mfma_f32_16x16x32_bf16 v[88:91], v[160:163], v[200:203], v[88:91]
	v_mfma_f32_16x16x32_bf16 v[76:79], v[152:155], v[208:211], v[76:79]
	v_mfma_f32_16x16x32_bf16 v[72:75], v[160:163], v[208:211], v[72:75]
	v_mfma_f32_16x16x32_bf16 v[116:119], v[164:167], v[180:183], v[116:119]
	v_mfma_f32_16x16x32_bf16 v[112:115], v[172:175], v[180:183], v[112:115]
	v_mfma_f32_16x16x32_bf16 v[100:103], v[164:167], v[188:191], v[100:103]
	v_mfma_f32_16x16x32_bf16 v[96:99], v[172:175], v[188:191], v[96:99]
	v_mfma_f32_16x16x32_bf16 v[84:87], v[164:167], v[196:199], v[84:87]
	v_mfma_f32_16x16x32_bf16 v[80:83], v[172:175], v[196:199], v[80:83]
	v_mfma_f32_16x16x32_bf16 v[68:71], v[164:167], v[204:207], v[68:71]
	v_mfma_f32_16x16x32_bf16 v[64:67], v[172:175], v[204:207], v[64:67]
	v_mfma_f32_16x16x32_bf16 v[116:119], v[168:171], v[184:187], v[116:119]
	v_mfma_f32_16x16x32_bf16 v[112:115], v[176:179], v[184:187], v[112:115]
	v_mfma_f32_16x16x32_bf16 v[100:103], v[168:171], v[192:195], v[100:103]
	v_mfma_f32_16x16x32_bf16 v[96:99], v[176:179], v[192:195], v[96:99]
	v_mfma_f32_16x16x32_bf16 v[84:87], v[168:171], v[200:203], v[84:87]
	v_mfma_f32_16x16x32_bf16 v[80:83], v[176:179], v[200:203], v[80:83]
	v_mfma_f32_16x16x32_bf16 v[68:71], v[168:171], v[208:211], v[68:71]
	v_mfma_f32_16x16x32_bf16 v[64:67], v[176:179], v[208:211], v[64:67]
	s_barrier
	s_setprio 0
	s_add_i32 s44, s65, s94
	v_lshl_add_u64 v[212:213], v[212:213], 0, s[16:17]
	s_mov_b32 m0, s44
	ds_read_b128 v[180:183], v151 offset:49152
	ds_read_b128 v[184:187], v151 offset:50176
	ds_read_b128 v[188:191], v151 offset:51200
	ds_read_b128 v[192:195], v151 offset:52224
	ds_read_b128 v[196:199], v151 offset:53248
	ds_read_b128 v[200:203], v151 offset:54272
	ds_read_b128 v[204:207], v151 offset:55296
	ds_read_b128 v[208:211], v151 offset:56320
	global_load_lds_dwordx4 v[212:213], off
	s_add_i32 m0, s44, 0x2000
	s_add_u32 s42, s42, 0x200080
	v_lshl_add_u64 v[212:213], v[214:215], 0, s[16:17]
	s_addc_u32 s43, s43, 0
	s_add_i32 s44, s66, s94
	global_load_lds_dwordx4 v[212:213], off
	v_lshl_add_u64 v[212:213], s[42:43], 0, v[128:129]
	s_mov_b32 m0, s44
	s_nop 0
	global_load_lds_dwordx4 v[212:213], off
	v_lshl_add_u64 v[212:213], s[42:43], 0, v[130:131]
	s_add_i32 m0, s44, 0x2000
	s_nop 0
	global_load_lds_dwordx4 v[212:213], off
	v_lshl_add_u64 v[212:213], v[216:217], 0, s[16:17]
	s_mov_b32 m0, s48
	s_nop 0
	global_load_lds_dwordx4 v[212:213], off
	v_lshl_add_u64 v[212:213], v[218:219], 0, s[16:17]
	s_mov_b32 m0, s49
	s_nop 0
	global_load_lds_dwordx4 v[212:213], off
	s_waitcnt vmcnt(8)
	s_waitcnt lgkmcnt(0)
	s_barrier
	s_setprio 1
	s_waitcnt lgkmcnt(0)
	v_mfma_f32_16x16x32_bf16 v[60:63], v[140:143], v[180:183], v[60:63]
	v_mfma_f32_16x16x32_bf16 v[56:59], v[156:159], v[180:183], v[56:59]
	v_mfma_f32_16x16x32_bf16 v[44:47], v[140:143], v[188:191], v[44:47]
	v_mfma_f32_16x16x32_bf16 v[40:43], v[156:159], v[188:191], v[40:43]
	v_mfma_f32_16x16x32_bf16 v[28:31], v[140:143], v[196:199], v[28:31]
	v_mfma_f32_16x16x32_bf16 v[24:27], v[156:159], v[196:199], v[24:27]
	v_mfma_f32_16x16x32_bf16 v[12:15], v[140:143], v[204:207], v[12:15]
	v_mfma_f32_16x16x32_bf16 v[8:11], v[156:159], v[204:207], v[8:11]
	v_mfma_f32_16x16x32_bf16 v[60:63], v[152:155], v[184:187], v[60:63]
	v_mfma_f32_16x16x32_bf16 v[56:59], v[160:163], v[184:187], v[56:59]
	v_mfma_f32_16x16x32_bf16 v[44:47], v[152:155], v[192:195], v[44:47]
	v_mfma_f32_16x16x32_bf16 v[40:43], v[160:163], v[192:195], v[40:43]
	v_mfma_f32_16x16x32_bf16 v[28:31], v[152:155], v[200:203], v[28:31]
	v_mfma_f32_16x16x32_bf16 v[24:27], v[160:163], v[200:203], v[24:27]
	v_mfma_f32_16x16x32_bf16 v[12:15], v[152:155], v[208:211], v[12:15]
	v_mfma_f32_16x16x32_bf16 v[8:11], v[160:163], v[208:211], v[8:11]
	v_mfma_f32_16x16x32_bf16 v[52:55], v[164:167], v[180:183], v[52:55]
	v_mfma_f32_16x16x32_bf16 v[48:51], v[172:175], v[180:183], v[48:51]
	v_mfma_f32_16x16x32_bf16 v[36:39], v[164:167], v[188:191], v[36:39]
	v_mfma_f32_16x16x32_bf16 v[32:35], v[172:175], v[188:191], v[32:35]
	v_mfma_f32_16x16x32_bf16 v[20:23], v[164:167], v[196:199], v[20:23]
	v_mfma_f32_16x16x32_bf16 v[16:19], v[172:175], v[196:199], v[16:19]
	v_mfma_f32_16x16x32_bf16 v[4:7], v[164:167], v[204:207], v[4:7]
	v_mfma_f32_16x16x32_bf16 v[0:3], v[172:175], v[204:207], v[0:3]
	v_mfma_f32_16x16x32_bf16 v[52:55], v[168:171], v[184:187], v[52:55]
	v_mfma_f32_16x16x32_bf16 v[48:51], v[176:179], v[184:187], v[48:51]
	v_mfma_f32_16x16x32_bf16 v[36:39], v[168:171], v[192:195], v[36:39]
	v_mfma_f32_16x16x32_bf16 v[32:35], v[176:179], v[192:195], v[32:35]
	v_mfma_f32_16x16x32_bf16 v[20:23], v[168:171], v[200:203], v[20:23]
	v_mfma_f32_16x16x32_bf16 v[16:19], v[176:179], v[200:203], v[16:19]
	v_mfma_f32_16x16x32_bf16 v[4:7], v[168:171], v[208:211], v[4:7]
	v_mfma_f32_16x16x32_bf16 v[0:3], v[176:179], v[208:211], v[0:3]
	s_barrier
	s_setprio 0
	s_add_i32 s64, s64, 2
	s_add_u32 s40, s40, 0x100
	s_addc_u32 s41, s41, 0
	s_add_u32 s62, s62, 0x100
	s_addc_u32 s63, s63, 0
	s_cmpk_gt_u32 s64, 0x7d
	s_cbranch_scc0 .LBB0_2917
	s_and_b64 vcc, exec, s[58:59]
	s_cbranch_vccz .LBB0_2920
	s_barrier
